# E_HG GEMM epilogue rewritten: one part dispatch per tile, straight-line per-part math (same per-element ops), permlane16_swap -> dwordx4 stores
# speedup vs baseline: 1.0221x; 1.0046x over previous
.LBB0_654:
	s_and_b64 vcc, exec, s[2:3]
	s_cbranch_vccz .LBB0_1040
	v_lshlrev_b32_e32 v0, 2, v223
	s_and_b32 s2, s6, 0x300
	v_or3_b32 v148, v224, s2, v0
	v_add_u32_e32 v146, s45, v225
	v_subrev_u32_e32 v146, s39, v146
	v_ashrrev_i32_e32 v147, 31, v146
	v_lshlrev_b64 v[150:151], 11, v[146:147]
	v_lshlrev_b32_e32 v152, 1, v148
	v_and_b32_e32 v153, 1, v223
	v_mul_u32_u24_e32 v153, 24, v153
	v_add_u32_e32 v152, v152, v153
	v_mov_b32_e32 v153, 0
	v_lshl_add_u64 v[150:151], v[150:151], 0, v[152:153]
	s_ashr_i32 s34, s47, 2
	s_mov_b32 s4, 0x8000
	s_mov_b32 s5, 0
	s_cmp_eq_u32 s34, 0
	s_cbranch_scc1 .Lhg_part0
	s_cmp_eq_u32 s34, 3
	s_cbranch_scc1 .Lhg_part3
	s_cmp_gt_u32 s34, 3
	s_cbranch_scc1 .Lhg_part4
	v_lshlrev_b32_e32 v130, 2, v148
	v_readlane_b32 s60, v255, 3
	v_readlane_b32 s61, v255, 4
	v_readlane_b32 s48, v252, 28
	v_readlane_b32 s49, v252, 29
	s_add_i32 s2, s34, -1
	s_mul_hi_i32 s3, s2, 0x2200000
	s_mul_i32 s2, s2, 0x2200000
	global_load_dwordx4 v[142:145], v130, s[60:61]
	global_load_dwordx4 v[138:141], v130, s[60:61] offset:64
	global_load_dwordx4 v[134:137], v130, s[60:61] offset:128
	global_load_dwordx4 v[130:133], v130, s[60:61] offset:192
	s_add_u32 s48, s48, s2
	s_addc_u32 s49, s49, s3
	s_mov_b32 s14, 0x800000
	s_mov_b32 s24, 0x3f317217
	s_mov_b32 s15, 0x7f800000
	s_waitcnt vmcnt(0)
	v_sub_f32_e32 v156, 1.0, v142
	v_sub_f32_e32 v157, 1.0, v143
	v_sub_f32_e32 v158, 1.0, v144
	v_sub_f32_e32 v159, 1.0, v145
	v_sub_f32_e32 v164, 1.0, v138
	v_sub_f32_e32 v165, 1.0, v139
	v_sub_f32_e32 v166, 1.0, v140
	v_sub_f32_e32 v167, 1.0, v141
	v_sub_f32_e32 v168, 1.0, v134
	v_sub_f32_e32 v169, 1.0, v135
	v_sub_f32_e32 v170, 1.0, v136
	v_sub_f32_e32 v171, 1.0, v137
	v_sub_f32_e32 v172, 1.0, v130
	v_sub_f32_e32 v173, 1.0, v131
	v_sub_f32_e32 v174, 1.0, v132
	v_sub_f32_e32 v175, 1.0, v133
	v_mov_b32_e32 v184, v130
	v_mov_b32_e32 v185, v131
	v_mov_b32_e32 v186, v132
	v_mov_b32_e32 v187, v133
	v_lshl_add_u64 v[132:133], s[48:49], 0, v[150:151]
	v_mul_f32_e32 v176, 0xbfb8aa3b, v126
	v_mul_f32_e32 v177, 0xbfb8aa3b, v127
	v_mul_f32_e32 v178, 0xbfb8aa3b, v128
	v_mul_f32_e32 v179, 0xbfb8aa3b, v129
	v_exp_f32_e32 v176, v176
	v_exp_f32_e32 v177, v177
	v_exp_f32_e32 v178, v178
	v_exp_f32_e32 v179, v179
	v_add_f32_e32 v176, 1.0, v176
	v_add_f32_e32 v177, 1.0, v177
	v_add_f32_e32 v178, 1.0, v178
	v_add_f32_e32 v179, 1.0, v179
	v_rcp_f32_e32 v176, v176
	v_rcp_f32_e32 v177, v177
	v_rcp_f32_e32 v178, v178
	v_rcp_f32_e32 v179, v179
	v_fma_f32 v126, v176, v156, v142
	v_fma_f32 v127, v177, v157, v143
	v_fma_f32 v128, v178, v158, v144
	v_fma_f32 v129, v179, v159, v145
	v_cmp_gt_f32_e64 s[50:51], s14, v126
	v_cmp_gt_f32_e64 s[52:53], s14, v127
	v_cmp_gt_f32_e64 s[54:55], s14, v128
	v_cmp_gt_f32_e64 s[56:57], s14, v129
	v_cndmask_b32_e64 v180, 0, 32, s[50:51]
	v_cndmask_b32_e64 v181, 0, 32, s[52:53]
	v_cndmask_b32_e64 v182, 0, 32, s[54:55]
	v_cndmask_b32_e64 v183, 0, 32, s[56:57]
	v_ldexp_f32 v126, v126, v180
	v_ldexp_f32 v127, v127, v181
	v_ldexp_f32 v128, v128, v182
	v_ldexp_f32 v129, v129, v183
	v_log_f32_e32 v126, v126
	v_log_f32_e32 v127, v127
	v_log_f32_e32 v128, v128
	v_log_f32_e32 v129, v129
	v_cndmask_b32_e64 v180, 0, v213, s[50:51]
	v_cndmask_b32_e64 v181, 0, v213, s[52:53]
	v_cndmask_b32_e64 v182, 0, v213, s[54:55]
	v_cndmask_b32_e64 v183, 0, v213, s[56:57]
	v_mul_f32_e32 v176, 0x3f317217, v126
	v_mul_f32_e32 v177, 0x3f317217, v127
	v_mul_f32_e32 v178, 0x3f317217, v128
	v_mul_f32_e32 v179, 0x3f317217, v129
	v_fma_f32 v176, v126, s24, -v176
	v_fma_f32 v177, v127, s24, -v177
	v_fma_f32 v178, v128, s24, -v178
	v_fma_f32 v179, v129, s24, -v179
	v_fmac_f32_e32 v176, 0x3377d1cf, v126
	v_fmac_f32_e32 v177, 0x3377d1cf, v127
	v_fmac_f32_e32 v178, 0x3377d1cf, v128
	v_fmac_f32_e32 v179, 0x3377d1cf, v129
	v_fmac_f32_e32 v176, 0x3f317217, v126
	v_fmac_f32_e32 v177, 0x3f317217, v127
	v_fmac_f32_e32 v178, 0x3f317217, v128
	v_fmac_f32_e32 v179, 0x3f317217, v129
	v_cmp_lt_f32_e64 s[58:59], |v126|, s15
	v_cmp_lt_f32_e64 s[60:61], |v127|, s15
	v_cmp_lt_f32_e64 s[62:63], |v128|, s15
	v_cmp_lt_f32_e64 s[40:41], |v129|, s15
	v_cndmask_b32_e64 v126, v126, v176, s[58:59]
	v_cndmask_b32_e64 v127, v127, v177, s[60:61]
	v_cndmask_b32_e64 v128, v128, v178, s[62:63]
	v_cndmask_b32_e64 v129, v129, v179, s[40:41]
	v_sub_f32_e32 v126, v126, v180
	v_sub_f32_e32 v127, v127, v181
	v_sub_f32_e32 v128, v128, v182
	v_sub_f32_e32 v129, v129, v183
	v_mul_f32_e32 v176, 0xbfb8aa3b, v122
	v_mul_f32_e32 v177, 0xbfb8aa3b, v123
	v_mul_f32_e32 v178, 0xbfb8aa3b, v124
	v_mul_f32_e32 v179, 0xbfb8aa3b, v125
	v_exp_f32_e32 v176, v176
	v_exp_f32_e32 v177, v177
	v_exp_f32_e32 v178, v178
	v_exp_f32_e32 v179, v179
	v_add_f32_e32 v176, 1.0, v176
	v_add_f32_e32 v177, 1.0, v177
	v_add_f32_e32 v178, 1.0, v178
	v_add_f32_e32 v179, 1.0, v179
	v_rcp_f32_e32 v176, v176
	v_rcp_f32_e32 v177, v177
	v_rcp_f32_e32 v178, v178
	v_rcp_f32_e32 v179, v179
	v_fma_f32 v122, v176, v164, v138
	v_fma_f32 v123, v177, v165, v139
	v_fma_f32 v124, v178, v166, v140
	v_fma_f32 v125, v179, v167, v141
	v_cmp_gt_f32_e64 s[50:51], s14, v122
	v_cmp_gt_f32_e64 s[52:53], s14, v123
	v_cmp_gt_f32_e64 s[54:55], s14, v124
	v_cmp_gt_f32_e64 s[56:57], s14, v125
	v_cndmask_b32_e64 v180, 0, 32, s[50:51]
	v_cndmask_b32_e64 v181, 0, 32, s[52:53]
	v_cndmask_b32_e64 v182, 0, 32, s[54:55]
	v_cndmask_b32_e64 v183, 0, 32, s[56:57]
	v_ldexp_f32 v122, v122, v180
	v_ldexp_f32 v123, v123, v181
	v_ldexp_f32 v124, v124, v182
	v_ldexp_f32 v125, v125, v183
	v_log_f32_e32 v122, v122
	v_log_f32_e32 v123, v123
	v_log_f32_e32 v124, v124
	v_log_f32_e32 v125, v125
	v_cndmask_b32_e64 v180, 0, v213, s[50:51]
	v_cndmask_b32_e64 v181, 0, v213, s[52:53]
	v_cndmask_b32_e64 v182, 0, v213, s[54:55]
	v_cndmask_b32_e64 v183, 0, v213, s[56:57]
	v_mul_f32_e32 v176, 0x3f317217, v122
	v_mul_f32_e32 v177, 0x3f317217, v123
	v_mul_f32_e32 v178, 0x3f317217, v124
	v_mul_f32_e32 v179, 0x3f317217, v125
	v_fma_f32 v176, v122, s24, -v176
	v_fma_f32 v177, v123, s24, -v177
	v_fma_f32 v178, v124, s24, -v178
	v_fma_f32 v179, v125, s24, -v179
	v_fmac_f32_e32 v176, 0x3377d1cf, v122
	v_fmac_f32_e32 v177, 0x3377d1cf, v123
	v_fmac_f32_e32 v178, 0x3377d1cf, v124
	v_fmac_f32_e32 v179, 0x3377d1cf, v125
	v_fmac_f32_e32 v176, 0x3f317217, v122
	v_fmac_f32_e32 v177, 0x3f317217, v123
	v_fmac_f32_e32 v178, 0x3f317217, v124
	v_fmac_f32_e32 v179, 0x3f317217, v125
	v_cmp_lt_f32_e64 s[58:59], |v122|, s15
	v_cmp_lt_f32_e64 s[60:61], |v123|, s15
	v_cmp_lt_f32_e64 s[62:63], |v124|, s15
	v_cmp_lt_f32_e64 s[40:41], |v125|, s15
	v_cndmask_b32_e64 v122, v122, v176, s[58:59]
	v_cndmask_b32_e64 v123, v123, v177, s[60:61]
	v_cndmask_b32_e64 v124, v124, v178, s[62:63]
	v_cndmask_b32_e64 v125, v125, v179, s[40:41]
	v_sub_f32_e32 v122, v122, v180
	v_sub_f32_e32 v123, v123, v181
	v_sub_f32_e32 v124, v124, v182
	v_sub_f32_e32 v125, v125, v183
	v_cvt_pk_f16_f32 v126, v126, v127
	v_cvt_pk_f16_f32 v127, v128, v129
	v_cvt_pk_f16_f32 v128, v122, v123
	v_cvt_pk_f16_f32 v129, v124, v125
	s_nop 1
	v_permlane16_swap_b32_e32 v126, v128
	v_permlane16_swap_b32_e32 v127, v129
	global_store_dwordx4 v[132:133], v[126:129], off
	v_mul_f32_e32 v176, 0xbfb8aa3b, v118
	v_mul_f32_e32 v177, 0xbfb8aa3b, v119
	v_mul_f32_e32 v178, 0xbfb8aa3b, v120
	v_mul_f32_e32 v179, 0xbfb8aa3b, v121
	v_exp_f32_e32 v176, v176
	v_exp_f32_e32 v177, v177
	v_exp_f32_e32 v178, v178
	v_exp_f32_e32 v179, v179
	v_add_f32_e32 v176, 1.0, v176
	v_add_f32_e32 v177, 1.0, v177
	v_add_f32_e32 v178, 1.0, v178
	v_add_f32_e32 v179, 1.0, v179
	v_rcp_f32_e32 v176, v176
	v_rcp_f32_e32 v177, v177
	v_rcp_f32_e32 v178, v178
	v_rcp_f32_e32 v179, v179
	v_fma_f32 v118, v176, v168, v134
	v_fma_f32 v119, v177, v169, v135
	v_fma_f32 v120, v178, v170, v136
	v_fma_f32 v121, v179, v171, v137
	v_cmp_gt_f32_e64 s[50:51], s14, v118
	v_cmp_gt_f32_e64 s[52:53], s14, v119
	v_cmp_gt_f32_e64 s[54:55], s14, v120
	v_cmp_gt_f32_e64 s[56:57], s14, v121
	v_cndmask_b32_e64 v180, 0, 32, s[50:51]
	v_cndmask_b32_e64 v181, 0, 32, s[52:53]
	v_cndmask_b32_e64 v182, 0, 32, s[54:55]
	v_cndmask_b32_e64 v183, 0, 32, s[56:57]
	v_ldexp_f32 v118, v118, v180
	v_ldexp_f32 v119, v119, v181
	v_ldexp_f32 v120, v120, v182
	v_ldexp_f32 v121, v121, v183
	v_log_f32_e32 v118, v118
	v_log_f32_e32 v119, v119
	v_log_f32_e32 v120, v120
	v_log_f32_e32 v121, v121
	v_cndmask_b32_e64 v180, 0, v213, s[50:51]
	v_cndmask_b32_e64 v181, 0, v213, s[52:53]
	v_cndmask_b32_e64 v182, 0, v213, s[54:55]
	v_cndmask_b32_e64 v183, 0, v213, s[56:57]
	v_mul_f32_e32 v176, 0x3f317217, v118
	v_mul_f32_e32 v177, 0x3f317217, v119
	v_mul_f32_e32 v178, 0x3f317217, v120
	v_mul_f32_e32 v179, 0x3f317217, v121
	v_fma_f32 v176, v118, s24, -v176
	v_fma_f32 v177, v119, s24, -v177
	v_fma_f32 v178, v120, s24, -v178
	v_fma_f32 v179, v121, s24, -v179
	v_fmac_f32_e32 v176, 0x3377d1cf, v118
	v_fmac_f32_e32 v177, 0x3377d1cf, v119
	v_fmac_f32_e32 v178, 0x3377d1cf, v120
	v_fmac_f32_e32 v179, 0x3377d1cf, v121
	v_fmac_f32_e32 v176, 0x3f317217, v118
	v_fmac_f32_e32 v177, 0x3f317217, v119
	v_fmac_f32_e32 v178, 0x3f317217, v120
	v_fmac_f32_e32 v179, 0x3f317217, v121
	v_cmp_lt_f32_e64 s[58:59], |v118|, s15
	v_cmp_lt_f32_e64 s[60:61], |v119|, s15
	v_cmp_lt_f32_e64 s[62:63], |v120|, s15
	v_cmp_lt_f32_e64 s[40:41], |v121|, s15
	v_cndmask_b32_e64 v118, v118, v176, s[58:59]
	v_cndmask_b32_e64 v119, v119, v177, s[60:61]
	v_cndmask_b32_e64 v120, v120, v178, s[62:63]
	v_cndmask_b32_e64 v121, v121, v179, s[40:41]
	v_sub_f32_e32 v118, v118, v180
	v_sub_f32_e32 v119, v119, v181
	v_sub_f32_e32 v120, v120, v182
	v_sub_f32_e32 v121, v121, v183
	v_mul_f32_e32 v176, 0xbfb8aa3b, v114
	v_mul_f32_e32 v177, 0xbfb8aa3b, v115
	v_mul_f32_e32 v178, 0xbfb8aa3b, v116
	v_mul_f32_e32 v179, 0xbfb8aa3b, v117
	v_exp_f32_e32 v176, v176
	v_exp_f32_e32 v177, v177
	v_exp_f32_e32 v178, v178
	v_exp_f32_e32 v179, v179
	v_add_f32_e32 v176, 1.0, v176
	v_add_f32_e32 v177, 1.0, v177
	v_add_f32_e32 v178, 1.0, v178
	v_add_f32_e32 v179, 1.0, v179
	v_rcp_f32_e32 v176, v176
	v_rcp_f32_e32 v177, v177
	v_rcp_f32_e32 v178, v178
	v_rcp_f32_e32 v179, v179
	v_fma_f32 v114, v176, v172, v184
	v_fma_f32 v115, v177, v173, v185
	v_fma_f32 v116, v178, v174, v186
	v_fma_f32 v117, v179, v175, v187
	v_cmp_gt_f32_e64 s[50:51], s14, v114
	v_cmp_gt_f32_e64 s[52:53], s14, v115
	v_cmp_gt_f32_e64 s[54:55], s14, v116
	v_cmp_gt_f32_e64 s[56:57], s14, v117
	v_cndmask_b32_e64 v180, 0, 32, s[50:51]
	v_cndmask_b32_e64 v181, 0, 32, s[52:53]
	v_cndmask_b32_e64 v182, 0, 32, s[54:55]
	v_cndmask_b32_e64 v183, 0, 32, s[56:57]
	v_ldexp_f32 v114, v114, v180
	v_ldexp_f32 v115, v115, v181
	v_ldexp_f32 v116, v116, v182
	v_ldexp_f32 v117, v117, v183
	v_log_f32_e32 v114, v114
	v_log_f32_e32 v115, v115
	v_log_f32_e32 v116, v116
	v_log_f32_e32 v117, v117
	v_cndmask_b32_e64 v180, 0, v213, s[50:51]
	v_cndmask_b32_e64 v181, 0, v213, s[52:53]
	v_cndmask_b32_e64 v182, 0, v213, s[54:55]
	v_cndmask_b32_e64 v183, 0, v213, s[56:57]
	v_mul_f32_e32 v176, 0x3f317217, v114
	v_mul_f32_e32 v177, 0x3f317217, v115
	v_mul_f32_e32 v178, 0x3f317217, v116
	v_mul_f32_e32 v179, 0x3f317217, v117
	v_fma_f32 v176, v114, s24, -v176
	v_fma_f32 v177, v115, s24, -v177
	v_fma_f32 v178, v116, s24, -v178
	v_fma_f32 v179, v117, s24, -v179
	v_fmac_f32_e32 v176, 0x3377d1cf, v114
	v_fmac_f32_e32 v177, 0x3377d1cf, v115
	v_fmac_f32_e32 v178, 0x3377d1cf, v116
	v_fmac_f32_e32 v179, 0x3377d1cf, v117
	v_fmac_f32_e32 v176, 0x3f317217, v114
	v_fmac_f32_e32 v177, 0x3f317217, v115
	v_fmac_f32_e32 v178, 0x3f317217, v116
	v_fmac_f32_e32 v179, 0x3f317217, v117
	v_cmp_lt_f32_e64 s[58:59], |v114|, s15
	v_cmp_lt_f32_e64 s[60:61], |v115|, s15
	v_cmp_lt_f32_e64 s[62:63], |v116|, s15
	v_cmp_lt_f32_e64 s[40:41], |v117|, s15
	v_cndmask_b32_e64 v114, v114, v176, s[58:59]
	v_cndmask_b32_e64 v115, v115, v177, s[60:61]
	v_cndmask_b32_e64 v116, v116, v178, s[62:63]
	v_cndmask_b32_e64 v117, v117, v179, s[40:41]
	v_sub_f32_e32 v114, v114, v180
	v_sub_f32_e32 v115, v115, v181
	v_sub_f32_e32 v116, v116, v182
	v_sub_f32_e32 v117, v117, v183
	v_cvt_pk_f16_f32 v118, v118, v119
	v_cvt_pk_f16_f32 v119, v120, v121
	v_cvt_pk_f16_f32 v120, v114, v115
	v_cvt_pk_f16_f32 v121, v116, v117
	s_nop 1
	v_permlane16_swap_b32_e32 v118, v120
	v_permlane16_swap_b32_e32 v119, v121
	global_store_dwordx4 v[132:133], v[118:121], off offset:64
	v_lshl_add_u64 v[132:133], v[132:133], 0, s[4:5]
	v_mul_f32_e32 v176, 0xbfb8aa3b, v110
	v_mul_f32_e32 v177, 0xbfb8aa3b, v111
	v_mul_f32_e32 v178, 0xbfb8aa3b, v112
	v_mul_f32_e32 v179, 0xbfb8aa3b, v113
	v_exp_f32_e32 v176, v176
	v_exp_f32_e32 v177, v177
	v_exp_f32_e32 v178, v178
	v_exp_f32_e32 v179, v179
	v_add_f32_e32 v176, 1.0, v176
	v_add_f32_e32 v177, 1.0, v177
	v_add_f32_e32 v178, 1.0, v178
	v_add_f32_e32 v179, 1.0, v179
	v_rcp_f32_e32 v176, v176
	v_rcp_f32_e32 v177, v177
	v_rcp_f32_e32 v178, v178
	v_rcp_f32_e32 v179, v179
	v_fma_f32 v110, v176, v156, v142
	v_fma_f32 v111, v177, v157, v143
	v_fma_f32 v112, v178, v158, v144
	v_fma_f32 v113, v179, v159, v145
	v_cmp_gt_f32_e64 s[50:51], s14, v110
	v_cmp_gt_f32_e64 s[52:53], s14, v111
	v_cmp_gt_f32_e64 s[54:55], s14, v112
	v_cmp_gt_f32_e64 s[56:57], s14, v113
	v_cndmask_b32_e64 v180, 0, 32, s[50:51]
	v_cndmask_b32_e64 v181, 0, 32, s[52:53]
	v_cndmask_b32_e64 v182, 0, 32, s[54:55]
	v_cndmask_b32_e64 v183, 0, 32, s[56:57]
	v_ldexp_f32 v110, v110, v180
	v_ldexp_f32 v111, v111, v181
	v_ldexp_f32 v112, v112, v182
	v_ldexp_f32 v113, v113, v183
	v_log_f32_e32 v110, v110
	v_log_f32_e32 v111, v111
	v_log_f32_e32 v112, v112
	v_log_f32_e32 v113, v113
	v_cndmask_b32_e64 v180, 0, v213, s[50:51]
	v_cndmask_b32_e64 v181, 0, v213, s[52:53]
	v_cndmask_b32_e64 v182, 0, v213, s[54:55]
	v_cndmask_b32_e64 v183, 0, v213, s[56:57]
	v_mul_f32_e32 v176, 0x3f317217, v110
	v_mul_f32_e32 v177, 0x3f317217, v111
	v_mul_f32_e32 v178, 0x3f317217, v112
	v_mul_f32_e32 v179, 0x3f317217, v113
	v_fma_f32 v176, v110, s24, -v176
	v_fma_f32 v177, v111, s24, -v177
	v_fma_f32 v178, v112, s24, -v178
	v_fma_f32 v179, v113, s24, -v179
	v_fmac_f32_e32 v176, 0x3377d1cf, v110
	v_fmac_f32_e32 v177, 0x3377d1cf, v111
	v_fmac_f32_e32 v178, 0x3377d1cf, v112
	v_fmac_f32_e32 v179, 0x3377d1cf, v113
	v_fmac_f32_e32 v176, 0x3f317217, v110
	v_fmac_f32_e32 v177, 0x3f317217, v111
	v_fmac_f32_e32 v178, 0x3f317217, v112
	v_fmac_f32_e32 v179, 0x3f317217, v113
	v_cmp_lt_f32_e64 s[58:59], |v110|, s15
	v_cmp_lt_f32_e64 s[60:61], |v111|, s15
	v_cmp_lt_f32_e64 s[62:63], |v112|, s15
	v_cmp_lt_f32_e64 s[40:41], |v113|, s15
	v_cndmask_b32_e64 v110, v110, v176, s[58:59]
	v_cndmask_b32_e64 v111, v111, v177, s[60:61]
	v_cndmask_b32_e64 v112, v112, v178, s[62:63]
	v_cndmask_b32_e64 v113, v113, v179, s[40:41]
	v_sub_f32_e32 v110, v110, v180
	v_sub_f32_e32 v111, v111, v181
	v_sub_f32_e32 v112, v112, v182
	v_sub_f32_e32 v113, v113, v183
	v_mul_f32_e32 v176, 0xbfb8aa3b, v106
	v_mul_f32_e32 v177, 0xbfb8aa3b, v107
	v_mul_f32_e32 v178, 0xbfb8aa3b, v108
	v_mul_f32_e32 v179, 0xbfb8aa3b, v109
	v_exp_f32_e32 v176, v176
	v_exp_f32_e32 v177, v177
	v_exp_f32_e32 v178, v178
	v_exp_f32_e32 v179, v179
	v_add_f32_e32 v176, 1.0, v176
	v_add_f32_e32 v177, 1.0, v177
	v_add_f32_e32 v178, 1.0, v178
	v_add_f32_e32 v179, 1.0, v179
	v_rcp_f32_e32 v176, v176
	v_rcp_f32_e32 v177, v177
	v_rcp_f32_e32 v178, v178
	v_rcp_f32_e32 v179, v179
	v_fma_f32 v106, v176, v164, v138
	v_fma_f32 v107, v177, v165, v139
	v_fma_f32 v108, v178, v166, v140
	v_fma_f32 v109, v179, v167, v141
	v_cmp_gt_f32_e64 s[50:51], s14, v106
	v_cmp_gt_f32_e64 s[52:53], s14, v107
	v_cmp_gt_f32_e64 s[54:55], s14, v108
	v_cmp_gt_f32_e64 s[56:57], s14, v109
	v_cndmask_b32_e64 v180, 0, 32, s[50:51]
	v_cndmask_b32_e64 v181, 0, 32, s[52:53]
	v_cndmask_b32_e64 v182, 0, 32, s[54:55]
	v_cndmask_b32_e64 v183, 0, 32, s[56:57]
	v_ldexp_f32 v106, v106, v180
	v_ldexp_f32 v107, v107, v181
	v_ldexp_f32 v108, v108, v182
	v_ldexp_f32 v109, v109, v183
	v_log_f32_e32 v106, v106
	v_log_f32_e32 v107, v107
	v_log_f32_e32 v108, v108
	v_log_f32_e32 v109, v109
	v_cndmask_b32_e64 v180, 0, v213, s[50:51]
	v_cndmask_b32_e64 v181, 0, v213, s[52:53]
	v_cndmask_b32_e64 v182, 0, v213, s[54:55]
	v_cndmask_b32_e64 v183, 0, v213, s[56:57]
	v_mul_f32_e32 v176, 0x3f317217, v106
	v_mul_f32_e32 v177, 0x3f317217, v107
	v_mul_f32_e32 v178, 0x3f317217, v108
	v_mul_f32_e32 v179, 0x3f317217, v109
	v_fma_f32 v176, v106, s24, -v176
	v_fma_f32 v177, v107, s24, -v177
	v_fma_f32 v178, v108, s24, -v178
	v_fma_f32 v179, v109, s24, -v179
	v_fmac_f32_e32 v176, 0x3377d1cf, v106
	v_fmac_f32_e32 v177, 0x3377d1cf, v107
	v_fmac_f32_e32 v178, 0x3377d1cf, v108
	v_fmac_f32_e32 v179, 0x3377d1cf, v109
	v_fmac_f32_e32 v176, 0x3f317217, v106
	v_fmac_f32_e32 v177, 0x3f317217, v107
	v_fmac_f32_e32 v178, 0x3f317217, v108
	v_fmac_f32_e32 v179, 0x3f317217, v109
	v_cmp_lt_f32_e64 s[58:59], |v106|, s15
	v_cmp_lt_f32_e64 s[60:61], |v107|, s15
	v_cmp_lt_f32_e64 s[62:63], |v108|, s15
	v_cmp_lt_f32_e64 s[40:41], |v109|, s15
	v_cndmask_b32_e64 v106, v106, v176, s[58:59]
	v_cndmask_b32_e64 v107, v107, v177, s[60:61]
	v_cndmask_b32_e64 v108, v108, v178, s[62:63]
	v_cndmask_b32_e64 v109, v109, v179, s[40:41]
	v_sub_f32_e32 v106, v106, v180
	v_sub_f32_e32 v107, v107, v181
	v_sub_f32_e32 v108, v108, v182
	v_sub_f32_e32 v109, v109, v183
	v_cvt_pk_f16_f32 v110, v110, v111
	v_cvt_pk_f16_f32 v111, v112, v113
	v_cvt_pk_f16_f32 v112, v106, v107
	v_cvt_pk_f16_f32 v113, v108, v109
	s_nop 1
	v_permlane16_swap_b32_e32 v110, v112
	v_permlane16_swap_b32_e32 v111, v113
	global_store_dwordx4 v[132:133], v[110:113], off
	v_mul_f32_e32 v176, 0xbfb8aa3b, v102
	v_mul_f32_e32 v177, 0xbfb8aa3b, v103
	v_mul_f32_e32 v178, 0xbfb8aa3b, v104
	v_mul_f32_e32 v179, 0xbfb8aa3b, v105
	v_exp_f32_e32 v176, v176
	v_exp_f32_e32 v177, v177
	v_exp_f32_e32 v178, v178
	v_exp_f32_e32 v179, v179
	v_add_f32_e32 v176, 1.0, v176
	v_add_f32_e32 v177, 1.0, v177
	v_add_f32_e32 v178, 1.0, v178
	v_add_f32_e32 v179, 1.0, v179
	v_rcp_f32_e32 v176, v176
	v_rcp_f32_e32 v177, v177
	v_rcp_f32_e32 v178, v178
	v_rcp_f32_e32 v179, v179
	v_fma_f32 v102, v176, v168, v134
	v_fma_f32 v103, v177, v169, v135
	v_fma_f32 v104, v178, v170, v136
	v_fma_f32 v105, v179, v171, v137
	v_cmp_gt_f32_e64 s[50:51], s14, v102
	v_cmp_gt_f32_e64 s[52:53], s14, v103
	v_cmp_gt_f32_e64 s[54:55], s14, v104
	v_cmp_gt_f32_e64 s[56:57], s14, v105
	v_cndmask_b32_e64 v180, 0, 32, s[50:51]
	v_cndmask_b32_e64 v181, 0, 32, s[52:53]
	v_cndmask_b32_e64 v182, 0, 32, s[54:55]
	v_cndmask_b32_e64 v183, 0, 32, s[56:57]
	v_ldexp_f32 v102, v102, v180
	v_ldexp_f32 v103, v103, v181
	v_ldexp_f32 v104, v104, v182
	v_ldexp_f32 v105, v105, v183
	v_log_f32_e32 v102, v102
	v_log_f32_e32 v103, v103
	v_log_f32_e32 v104, v104
	v_log_f32_e32 v105, v105
	v_cndmask_b32_e64 v180, 0, v213, s[50:51]
	v_cndmask_b32_e64 v181, 0, v213, s[52:53]
	v_cndmask_b32_e64 v182, 0, v213, s[54:55]
	v_cndmask_b32_e64 v183, 0, v213, s[56:57]
	v_mul_f32_e32 v176, 0x3f317217, v102
	v_mul_f32_e32 v177, 0x3f317217, v103
	v_mul_f32_e32 v178, 0x3f317217, v104
	v_mul_f32_e32 v179, 0x3f317217, v105
	v_fma_f32 v176, v102, s24, -v176
	v_fma_f32 v177, v103, s24, -v177
	v_fma_f32 v178, v104, s24, -v178
	v_fma_f32 v179, v105, s24, -v179
	v_fmac_f32_e32 v176, 0x3377d1cf, v102
	v_fmac_f32_e32 v177, 0x3377d1cf, v103
	v_fmac_f32_e32 v178, 0x3377d1cf, v104
	v_fmac_f32_e32 v179, 0x3377d1cf, v105
	v_fmac_f32_e32 v176, 0x3f317217, v102
	v_fmac_f32_e32 v177, 0x3f317217, v103
	v_fmac_f32_e32 v178, 0x3f317217, v104
	v_fmac_f32_e32 v179, 0x3f317217, v105
	v_cmp_lt_f32_e64 s[58:59], |v102|, s15
	v_cmp_lt_f32_e64 s[60:61], |v103|, s15
	v_cmp_lt_f32_e64 s[62:63], |v104|, s15
	v_cmp_lt_f32_e64 s[40:41], |v105|, s15
	v_cndmask_b32_e64 v102, v102, v176, s[58:59]
	v_cndmask_b32_e64 v103, v103, v177, s[60:61]
	v_cndmask_b32_e64 v104, v104, v178, s[62:63]
	v_cndmask_b32_e64 v105, v105, v179, s[40:41]
	v_sub_f32_e32 v102, v102, v180
	v_sub_f32_e32 v103, v103, v181
	v_sub_f32_e32 v104, v104, v182
	v_sub_f32_e32 v105, v105, v183
	v_mul_f32_e32 v176, 0xbfb8aa3b, v98
	v_mul_f32_e32 v177, 0xbfb8aa3b, v99
	v_mul_f32_e32 v178, 0xbfb8aa3b, v100
	v_mul_f32_e32 v179, 0xbfb8aa3b, v101
	v_exp_f32_e32 v176, v176
	v_exp_f32_e32 v177, v177
	v_exp_f32_e32 v178, v178
	v_exp_f32_e32 v179, v179
	v_add_f32_e32 v176, 1.0, v176
	v_add_f32_e32 v177, 1.0, v177
	v_add_f32_e32 v178, 1.0, v178
	v_add_f32_e32 v179, 1.0, v179
	v_rcp_f32_e32 v176, v176
	v_rcp_f32_e32 v177, v177
	v_rcp_f32_e32 v178, v178
	v_rcp_f32_e32 v179, v179
	v_fma_f32 v98, v176, v172, v184
	v_fma_f32 v99, v177, v173, v185
	v_fma_f32 v100, v178, v174, v186
	v_fma_f32 v101, v179, v175, v187
	v_cmp_gt_f32_e64 s[50:51], s14, v98
	v_cmp_gt_f32_e64 s[52:53], s14, v99
	v_cmp_gt_f32_e64 s[54:55], s14, v100
	v_cmp_gt_f32_e64 s[56:57], s14, v101
	v_cndmask_b32_e64 v180, 0, 32, s[50:51]
	v_cndmask_b32_e64 v181, 0, 32, s[52:53]
	v_cndmask_b32_e64 v182, 0, 32, s[54:55]
	v_cndmask_b32_e64 v183, 0, 32, s[56:57]
	v_ldexp_f32 v98, v98, v180
	v_ldexp_f32 v99, v99, v181
	v_ldexp_f32 v100, v100, v182
	v_ldexp_f32 v101, v101, v183
	v_log_f32_e32 v98, v98
	v_log_f32_e32 v99, v99
	v_log_f32_e32 v100, v100
	v_log_f32_e32 v101, v101
	v_cndmask_b32_e64 v180, 0, v213, s[50:51]
	v_cndmask_b32_e64 v181, 0, v213, s[52:53]
	v_cndmask_b32_e64 v182, 0, v213, s[54:55]
	v_cndmask_b32_e64 v183, 0, v213, s[56:57]
	v_mul_f32_e32 v176, 0x3f317217, v98
	v_mul_f32_e32 v177, 0x3f317217, v99
	v_mul_f32_e32 v178, 0x3f317217, v100
	v_mul_f32_e32 v179, 0x3f317217, v101
	v_fma_f32 v176, v98, s24, -v176
	v_fma_f32 v177, v99, s24, -v177
	v_fma_f32 v178, v100, s24, -v178
	v_fma_f32 v179, v101, s24, -v179
	v_fmac_f32_e32 v176, 0x3377d1cf, v98
	v_fmac_f32_e32 v177, 0x3377d1cf, v99
	v_fmac_f32_e32 v178, 0x3377d1cf, v100
	v_fmac_f32_e32 v179, 0x3377d1cf, v101
	v_fmac_f32_e32 v176, 0x3f317217, v98
	v_fmac_f32_e32 v177, 0x3f317217, v99
	v_fmac_f32_e32 v178, 0x3f317217, v100
	v_fmac_f32_e32 v179, 0x3f317217, v101
	v_cmp_lt_f32_e64 s[58:59], |v98|, s15
	v_cmp_lt_f32_e64 s[60:61], |v99|, s15
	v_cmp_lt_f32_e64 s[62:63], |v100|, s15
	v_cmp_lt_f32_e64 s[40:41], |v101|, s15
	v_cndmask_b32_e64 v98, v98, v176, s[58:59]
	v_cndmask_b32_e64 v99, v99, v177, s[60:61]
	v_cndmask_b32_e64 v100, v100, v178, s[62:63]
	v_cndmask_b32_e64 v101, v101, v179, s[40:41]
	v_sub_f32_e32 v98, v98, v180
	v_sub_f32_e32 v99, v99, v181
	v_sub_f32_e32 v100, v100, v182
	v_sub_f32_e32 v101, v101, v183
	v_cvt_pk_f16_f32 v102, v102, v103
	v_cvt_pk_f16_f32 v103, v104, v105
	v_cvt_pk_f16_f32 v104, v98, v99
	v_cvt_pk_f16_f32 v105, v100, v101
	s_nop 1
	v_permlane16_swap_b32_e32 v102, v104
	v_permlane16_swap_b32_e32 v103, v105
	global_store_dwordx4 v[132:133], v[102:105], off offset:64
	v_lshl_add_u64 v[132:133], v[132:133], 0, s[4:5]
	v_mul_f32_e32 v176, 0xbfb8aa3b, v94
	v_mul_f32_e32 v177, 0xbfb8aa3b, v95
	v_mul_f32_e32 v178, 0xbfb8aa3b, v96
	v_mul_f32_e32 v179, 0xbfb8aa3b, v97
	v_exp_f32_e32 v176, v176
	v_exp_f32_e32 v177, v177
	v_exp_f32_e32 v178, v178
	v_exp_f32_e32 v179, v179
	v_add_f32_e32 v176, 1.0, v176
	v_add_f32_e32 v177, 1.0, v177
	v_add_f32_e32 v178, 1.0, v178
	v_add_f32_e32 v179, 1.0, v179
	v_rcp_f32_e32 v176, v176
	v_rcp_f32_e32 v177, v177
	v_rcp_f32_e32 v178, v178
	v_rcp_f32_e32 v179, v179
	v_fma_f32 v94, v176, v156, v142
	v_fma_f32 v95, v177, v157, v143
	v_fma_f32 v96, v178, v158, v144
	v_fma_f32 v97, v179, v159, v145
	v_cmp_gt_f32_e64 s[50:51], s14, v94
	v_cmp_gt_f32_e64 s[52:53], s14, v95
	v_cmp_gt_f32_e64 s[54:55], s14, v96
	v_cmp_gt_f32_e64 s[56:57], s14, v97
	v_cndmask_b32_e64 v180, 0, 32, s[50:51]
	v_cndmask_b32_e64 v181, 0, 32, s[52:53]
	v_cndmask_b32_e64 v182, 0, 32, s[54:55]
	v_cndmask_b32_e64 v183, 0, 32, s[56:57]
	v_ldexp_f32 v94, v94, v180
	v_ldexp_f32 v95, v95, v181
	v_ldexp_f32 v96, v96, v182
	v_ldexp_f32 v97, v97, v183
	v_log_f32_e32 v94, v94
	v_log_f32_e32 v95, v95
	v_log_f32_e32 v96, v96
	v_log_f32_e32 v97, v97
	v_cndmask_b32_e64 v180, 0, v213, s[50:51]
	v_cndmask_b32_e64 v181, 0, v213, s[52:53]
	v_cndmask_b32_e64 v182, 0, v213, s[54:55]
	v_cndmask_b32_e64 v183, 0, v213, s[56:57]
	v_mul_f32_e32 v176, 0x3f317217, v94
	v_mul_f32_e32 v177, 0x3f317217, v95
	v_mul_f32_e32 v178, 0x3f317217, v96
	v_mul_f32_e32 v179, 0x3f317217, v97
	v_fma_f32 v176, v94, s24, -v176
	v_fma_f32 v177, v95, s24, -v177
	v_fma_f32 v178, v96, s24, -v178
	v_fma_f32 v179, v97, s24, -v179
	v_fmac_f32_e32 v176, 0x3377d1cf, v94
	v_fmac_f32_e32 v177, 0x3377d1cf, v95
	v_fmac_f32_e32 v178, 0x3377d1cf, v96
	v_fmac_f32_e32 v179, 0x3377d1cf, v97
	v_fmac_f32_e32 v176, 0x3f317217, v94
	v_fmac_f32_e32 v177, 0x3f317217, v95
	v_fmac_f32_e32 v178, 0x3f317217, v96
	v_fmac_f32_e32 v179, 0x3f317217, v97
	v_cmp_lt_f32_e64 s[58:59], |v94|, s15
	v_cmp_lt_f32_e64 s[60:61], |v95|, s15
	v_cmp_lt_f32_e64 s[62:63], |v96|, s15
	v_cmp_lt_f32_e64 s[40:41], |v97|, s15
	v_cndmask_b32_e64 v94, v94, v176, s[58:59]
	v_cndmask_b32_e64 v95, v95, v177, s[60:61]
	v_cndmask_b32_e64 v96, v96, v178, s[62:63]
	v_cndmask_b32_e64 v97, v97, v179, s[40:41]
	v_sub_f32_e32 v94, v94, v180
	v_sub_f32_e32 v95, v95, v181
	v_sub_f32_e32 v96, v96, v182
	v_sub_f32_e32 v97, v97, v183
	v_mul_f32_e32 v176, 0xbfb8aa3b, v90
	v_mul_f32_e32 v177, 0xbfb8aa3b, v91
	v_mul_f32_e32 v178, 0xbfb8aa3b, v92
	v_mul_f32_e32 v179, 0xbfb8aa3b, v93
	v_exp_f32_e32 v176, v176
	v_exp_f32_e32 v177, v177
	v_exp_f32_e32 v178, v178
	v_exp_f32_e32 v179, v179
	v_add_f32_e32 v176, 1.0, v176
	v_add_f32_e32 v177, 1.0, v177
	v_add_f32_e32 v178, 1.0, v178
	v_add_f32_e32 v179, 1.0, v179
	v_rcp_f32_e32 v176, v176
	v_rcp_f32_e32 v177, v177
	v_rcp_f32_e32 v178, v178
	v_rcp_f32_e32 v179, v179
	v_fma_f32 v90, v176, v164, v138
	v_fma_f32 v91, v177, v165, v139
	v_fma_f32 v92, v178, v166, v140
	v_fma_f32 v93, v179, v167, v141
	v_cmp_gt_f32_e64 s[50:51], s14, v90
	v_cmp_gt_f32_e64 s[52:53], s14, v91
	v_cmp_gt_f32_e64 s[54:55], s14, v92
	v_cmp_gt_f32_e64 s[56:57], s14, v93
	v_cndmask_b32_e64 v180, 0, 32, s[50:51]
	v_cndmask_b32_e64 v181, 0, 32, s[52:53]
	v_cndmask_b32_e64 v182, 0, 32, s[54:55]
	v_cndmask_b32_e64 v183, 0, 32, s[56:57]
	v_ldexp_f32 v90, v90, v180
	v_ldexp_f32 v91, v91, v181
	v_ldexp_f32 v92, v92, v182
	v_ldexp_f32 v93, v93, v183
	v_log_f32_e32 v90, v90
	v_log_f32_e32 v91, v91
	v_log_f32_e32 v92, v92
	v_log_f32_e32 v93, v93
	v_cndmask_b32_e64 v180, 0, v213, s[50:51]
	v_cndmask_b32_e64 v181, 0, v213, s[52:53]
	v_cndmask_b32_e64 v182, 0, v213, s[54:55]
	v_cndmask_b32_e64 v183, 0, v213, s[56:57]
	v_mul_f32_e32 v176, 0x3f317217, v90
	v_mul_f32_e32 v177, 0x3f317217, v91
	v_mul_f32_e32 v178, 0x3f317217, v92
	v_mul_f32_e32 v179, 0x3f317217, v93
	v_fma_f32 v176, v90, s24, -v176
	v_fma_f32 v177, v91, s24, -v177
	v_fma_f32 v178, v92, s24, -v178
	v_fma_f32 v179, v93, s24, -v179
	v_fmac_f32_e32 v176, 0x3377d1cf, v90
	v_fmac_f32_e32 v177, 0x3377d1cf, v91
	v_fmac_f32_e32 v178, 0x3377d1cf, v92
	v_fmac_f32_e32 v179, 0x3377d1cf, v93
	v_fmac_f32_e32 v176, 0x3f317217, v90
	v_fmac_f32_e32 v177, 0x3f317217, v91
	v_fmac_f32_e32 v178, 0x3f317217, v92
	v_fmac_f32_e32 v179, 0x3f317217, v93
	v_cmp_lt_f32_e64 s[58:59], |v90|, s15
	v_cmp_lt_f32_e64 s[60:61], |v91|, s15
	v_cmp_lt_f32_e64 s[62:63], |v92|, s15
	v_cmp_lt_f32_e64 s[40:41], |v93|, s15
	v_cndmask_b32_e64 v90, v90, v176, s[58:59]
	v_cndmask_b32_e64 v91, v91, v177, s[60:61]
	v_cndmask_b32_e64 v92, v92, v178, s[62:63]
	v_cndmask_b32_e64 v93, v93, v179, s[40:41]
	v_sub_f32_e32 v90, v90, v180
	v_sub_f32_e32 v91, v91, v181
	v_sub_f32_e32 v92, v92, v182
	v_sub_f32_e32 v93, v93, v183
	v_cvt_pk_f16_f32 v94, v94, v95
	v_cvt_pk_f16_f32 v95, v96, v97
	v_cvt_pk_f16_f32 v96, v90, v91
	v_cvt_pk_f16_f32 v97, v92, v93
	s_nop 1
	v_permlane16_swap_b32_e32 v94, v96
	v_permlane16_swap_b32_e32 v95, v97
	global_store_dwordx4 v[132:133], v[94:97], off
	v_mul_f32_e32 v176, 0xbfb8aa3b, v86
	v_mul_f32_e32 v177, 0xbfb8aa3b, v87
	v_mul_f32_e32 v178, 0xbfb8aa3b, v88
	v_mul_f32_e32 v179, 0xbfb8aa3b, v89
	v_exp_f32_e32 v176, v176
	v_exp_f32_e32 v177, v177
	v_exp_f32_e32 v178, v178
	v_exp_f32_e32 v179, v179
	v_add_f32_e32 v176, 1.0, v176
	v_add_f32_e32 v177, 1.0, v177
	v_add_f32_e32 v178, 1.0, v178
	v_add_f32_e32 v179, 1.0, v179
	v_rcp_f32_e32 v176, v176
	v_rcp_f32_e32 v177, v177
	v_rcp_f32_e32 v178, v178
	v_rcp_f32_e32 v179, v179
	v_fma_f32 v86, v176, v168, v134
	v_fma_f32 v87, v177, v169, v135
	v_fma_f32 v88, v178, v170, v136
	v_fma_f32 v89, v179, v171, v137
	v_cmp_gt_f32_e64 s[50:51], s14, v86
	v_cmp_gt_f32_e64 s[52:53], s14, v87
	v_cmp_gt_f32_e64 s[54:55], s14, v88
	v_cmp_gt_f32_e64 s[56:57], s14, v89
	v_cndmask_b32_e64 v180, 0, 32, s[50:51]
	v_cndmask_b32_e64 v181, 0, 32, s[52:53]
	v_cndmask_b32_e64 v182, 0, 32, s[54:55]
	v_cndmask_b32_e64 v183, 0, 32, s[56:57]
	v_ldexp_f32 v86, v86, v180
	v_ldexp_f32 v87, v87, v181
	v_ldexp_f32 v88, v88, v182
	v_ldexp_f32 v89, v89, v183
	v_log_f32_e32 v86, v86
	v_log_f32_e32 v87, v87
	v_log_f32_e32 v88, v88
	v_log_f32_e32 v89, v89
	v_cndmask_b32_e64 v180, 0, v213, s[50:51]
	v_cndmask_b32_e64 v181, 0, v213, s[52:53]
	v_cndmask_b32_e64 v182, 0, v213, s[54:55]
	v_cndmask_b32_e64 v183, 0, v213, s[56:57]
	v_mul_f32_e32 v176, 0x3f317217, v86
	v_mul_f32_e32 v177, 0x3f317217, v87
	v_mul_f32_e32 v178, 0x3f317217, v88
	v_mul_f32_e32 v179, 0x3f317217, v89
	v_fma_f32 v176, v86, s24, -v176
	v_fma_f32 v177, v87, s24, -v177
	v_fma_f32 v178, v88, s24, -v178
	v_fma_f32 v179, v89, s24, -v179
	v_fmac_f32_e32 v176, 0x3377d1cf, v86
	v_fmac_f32_e32 v177, 0x3377d1cf, v87
	v_fmac_f32_e32 v178, 0x3377d1cf, v88
	v_fmac_f32_e32 v179, 0x3377d1cf, v89
	v_fmac_f32_e32 v176, 0x3f317217, v86
	v_fmac_f32_e32 v177, 0x3f317217, v87
	v_fmac_f32_e32 v178, 0x3f317217, v88
	v_fmac_f32_e32 v179, 0x3f317217, v89
	v_cmp_lt_f32_e64 s[58:59], |v86|, s15
	v_cmp_lt_f32_e64 s[60:61], |v87|, s15
	v_cmp_lt_f32_e64 s[62:63], |v88|, s15
	v_cmp_lt_f32_e64 s[40:41], |v89|, s15
	v_cndmask_b32_e64 v86, v86, v176, s[58:59]
	v_cndmask_b32_e64 v87, v87, v177, s[60:61]
	v_cndmask_b32_e64 v88, v88, v178, s[62:63]
	v_cndmask_b32_e64 v89, v89, v179, s[40:41]
	v_sub_f32_e32 v86, v86, v180
	v_sub_f32_e32 v87, v87, v181
	v_sub_f32_e32 v88, v88, v182
	v_sub_f32_e32 v89, v89, v183
	v_mul_f32_e32 v176, 0xbfb8aa3b, v82
	v_mul_f32_e32 v177, 0xbfb8aa3b, v83
	v_mul_f32_e32 v178, 0xbfb8aa3b, v84
	v_mul_f32_e32 v179, 0xbfb8aa3b, v85
	v_exp_f32_e32 v176, v176
	v_exp_f32_e32 v177, v177
	v_exp_f32_e32 v178, v178
	v_exp_f32_e32 v179, v179
	v_add_f32_e32 v176, 1.0, v176
	v_add_f32_e32 v177, 1.0, v177
	v_add_f32_e32 v178, 1.0, v178
	v_add_f32_e32 v179, 1.0, v179
	v_rcp_f32_e32 v176, v176
	v_rcp_f32_e32 v177, v177
	v_rcp_f32_e32 v178, v178
	v_rcp_f32_e32 v179, v179
	v_fma_f32 v82, v176, v172, v184
	v_fma_f32 v83, v177, v173, v185
	v_fma_f32 v84, v178, v174, v186
	v_fma_f32 v85, v179, v175, v187
	v_cmp_gt_f32_e64 s[50:51], s14, v82
	v_cmp_gt_f32_e64 s[52:53], s14, v83
	v_cmp_gt_f32_e64 s[54:55], s14, v84
	v_cmp_gt_f32_e64 s[56:57], s14, v85
	v_cndmask_b32_e64 v180, 0, 32, s[50:51]
	v_cndmask_b32_e64 v181, 0, 32, s[52:53]
	v_cndmask_b32_e64 v182, 0, 32, s[54:55]
	v_cndmask_b32_e64 v183, 0, 32, s[56:57]
	v_ldexp_f32 v82, v82, v180
	v_ldexp_f32 v83, v83, v181
	v_ldexp_f32 v84, v84, v182
	v_ldexp_f32 v85, v85, v183
	v_log_f32_e32 v82, v82
	v_log_f32_e32 v83, v83
	v_log_f32_e32 v84, v84
	v_log_f32_e32 v85, v85
	v_cndmask_b32_e64 v180, 0, v213, s[50:51]
	v_cndmask_b32_e64 v181, 0, v213, s[52:53]
	v_cndmask_b32_e64 v182, 0, v213, s[54:55]
	v_cndmask_b32_e64 v183, 0, v213, s[56:57]
	v_mul_f32_e32 v176, 0x3f317217, v82
	v_mul_f32_e32 v177, 0x3f317217, v83
	v_mul_f32_e32 v178, 0x3f317217, v84
	v_mul_f32_e32 v179, 0x3f317217, v85
	v_fma_f32 v176, v82, s24, -v176
	v_fma_f32 v177, v83, s24, -v177
	v_fma_f32 v178, v84, s24, -v178
	v_fma_f32 v179, v85, s24, -v179
	v_fmac_f32_e32 v176, 0x3377d1cf, v82
	v_fmac_f32_e32 v177, 0x3377d1cf, v83
	v_fmac_f32_e32 v178, 0x3377d1cf, v84
	v_fmac_f32_e32 v179, 0x3377d1cf, v85
	v_fmac_f32_e32 v176, 0x3f317217, v82
	v_fmac_f32_e32 v177, 0x3f317217, v83
	v_fmac_f32_e32 v178, 0x3f317217, v84
	v_fmac_f32_e32 v179, 0x3f317217, v85
	v_cmp_lt_f32_e64 s[58:59], |v82|, s15
	v_cmp_lt_f32_e64 s[60:61], |v83|, s15
	v_cmp_lt_f32_e64 s[62:63], |v84|, s15
	v_cmp_lt_f32_e64 s[40:41], |v85|, s15
	v_cndmask_b32_e64 v82, v82, v176, s[58:59]
	v_cndmask_b32_e64 v83, v83, v177, s[60:61]
	v_cndmask_b32_e64 v84, v84, v178, s[62:63]
	v_cndmask_b32_e64 v85, v85, v179, s[40:41]
	v_sub_f32_e32 v82, v82, v180
	v_sub_f32_e32 v83, v83, v181
	v_sub_f32_e32 v84, v84, v182
	v_sub_f32_e32 v85, v85, v183
	v_cvt_pk_f16_f32 v86, v86, v87
	v_cvt_pk_f16_f32 v87, v88, v89
	v_cvt_pk_f16_f32 v88, v82, v83
	v_cvt_pk_f16_f32 v89, v84, v85
	s_nop 1
	v_permlane16_swap_b32_e32 v86, v88
	v_permlane16_swap_b32_e32 v87, v89
	global_store_dwordx4 v[132:133], v[86:89], off offset:64
	v_lshl_add_u64 v[132:133], v[132:133], 0, s[4:5]
	v_mul_f32_e32 v176, 0xbfb8aa3b, v78
	v_mul_f32_e32 v177, 0xbfb8aa3b, v79
	v_mul_f32_e32 v178, 0xbfb8aa3b, v80
	v_mul_f32_e32 v179, 0xbfb8aa3b, v81
	v_exp_f32_e32 v176, v176
	v_exp_f32_e32 v177, v177
	v_exp_f32_e32 v178, v178
	v_exp_f32_e32 v179, v179
	v_add_f32_e32 v176, 1.0, v176
	v_add_f32_e32 v177, 1.0, v177
	v_add_f32_e32 v178, 1.0, v178
	v_add_f32_e32 v179, 1.0, v179
	v_rcp_f32_e32 v176, v176
	v_rcp_f32_e32 v177, v177
	v_rcp_f32_e32 v178, v178
	v_rcp_f32_e32 v179, v179
	v_fma_f32 v78, v176, v156, v142
	v_fma_f32 v79, v177, v157, v143
	v_fma_f32 v80, v178, v158, v144
	v_fma_f32 v81, v179, v159, v145
	v_cmp_gt_f32_e64 s[50:51], s14, v78
	v_cmp_gt_f32_e64 s[52:53], s14, v79
	v_cmp_gt_f32_e64 s[54:55], s14, v80
	v_cmp_gt_f32_e64 s[56:57], s14, v81
	v_cndmask_b32_e64 v180, 0, 32, s[50:51]
	v_cndmask_b32_e64 v181, 0, 32, s[52:53]
	v_cndmask_b32_e64 v182, 0, 32, s[54:55]
	v_cndmask_b32_e64 v183, 0, 32, s[56:57]
	v_ldexp_f32 v78, v78, v180
	v_ldexp_f32 v79, v79, v181
	v_ldexp_f32 v80, v80, v182
	v_ldexp_f32 v81, v81, v183
	v_log_f32_e32 v78, v78
	v_log_f32_e32 v79, v79
	v_log_f32_e32 v80, v80
	v_log_f32_e32 v81, v81
	v_cndmask_b32_e64 v180, 0, v213, s[50:51]
	v_cndmask_b32_e64 v181, 0, v213, s[52:53]
	v_cndmask_b32_e64 v182, 0, v213, s[54:55]
	v_cndmask_b32_e64 v183, 0, v213, s[56:57]
	v_mul_f32_e32 v176, 0x3f317217, v78
	v_mul_f32_e32 v177, 0x3f317217, v79
	v_mul_f32_e32 v178, 0x3f317217, v80
	v_mul_f32_e32 v179, 0x3f317217, v81
	v_fma_f32 v176, v78, s24, -v176
	v_fma_f32 v177, v79, s24, -v177
	v_fma_f32 v178, v80, s24, -v178
	v_fma_f32 v179, v81, s24, -v179
	v_fmac_f32_e32 v176, 0x3377d1cf, v78
	v_fmac_f32_e32 v177, 0x3377d1cf, v79
	v_fmac_f32_e32 v178, 0x3377d1cf, v80
	v_fmac_f32_e32 v179, 0x3377d1cf, v81
	v_fmac_f32_e32 v176, 0x3f317217, v78
	v_fmac_f32_e32 v177, 0x3f317217, v79
	v_fmac_f32_e32 v178, 0x3f317217, v80
	v_fmac_f32_e32 v179, 0x3f317217, v81
	v_cmp_lt_f32_e64 s[58:59], |v78|, s15
	v_cmp_lt_f32_e64 s[60:61], |v79|, s15
	v_cmp_lt_f32_e64 s[62:63], |v80|, s15
	v_cmp_lt_f32_e64 s[40:41], |v81|, s15
	v_cndmask_b32_e64 v78, v78, v176, s[58:59]
	v_cndmask_b32_e64 v79, v79, v177, s[60:61]
	v_cndmask_b32_e64 v80, v80, v178, s[62:63]
	v_cndmask_b32_e64 v81, v81, v179, s[40:41]
	v_sub_f32_e32 v78, v78, v180
	v_sub_f32_e32 v79, v79, v181
	v_sub_f32_e32 v80, v80, v182
	v_sub_f32_e32 v81, v81, v183
	v_mul_f32_e32 v176, 0xbfb8aa3b, v74
	v_mul_f32_e32 v177, 0xbfb8aa3b, v75
	v_mul_f32_e32 v178, 0xbfb8aa3b, v76
	v_mul_f32_e32 v179, 0xbfb8aa3b, v77
	v_exp_f32_e32 v176, v176
	v_exp_f32_e32 v177, v177
	v_exp_f32_e32 v178, v178
	v_exp_f32_e32 v179, v179
	v_add_f32_e32 v176, 1.0, v176
	v_add_f32_e32 v177, 1.0, v177
	v_add_f32_e32 v178, 1.0, v178
	v_add_f32_e32 v179, 1.0, v179
	v_rcp_f32_e32 v176, v176
	v_rcp_f32_e32 v177, v177
	v_rcp_f32_e32 v178, v178
	v_rcp_f32_e32 v179, v179
	v_fma_f32 v74, v176, v164, v138
	v_fma_f32 v75, v177, v165, v139
	v_fma_f32 v76, v178, v166, v140
	v_fma_f32 v77, v179, v167, v141
	v_cmp_gt_f32_e64 s[50:51], s14, v74
	v_cmp_gt_f32_e64 s[52:53], s14, v75
	v_cmp_gt_f32_e64 s[54:55], s14, v76
	v_cmp_gt_f32_e64 s[56:57], s14, v77
	v_cndmask_b32_e64 v180, 0, 32, s[50:51]
	v_cndmask_b32_e64 v181, 0, 32, s[52:53]
	v_cndmask_b32_e64 v182, 0, 32, s[54:55]
	v_cndmask_b32_e64 v183, 0, 32, s[56:57]
	v_ldexp_f32 v74, v74, v180
	v_ldexp_f32 v75, v75, v181
	v_ldexp_f32 v76, v76, v182
	v_ldexp_f32 v77, v77, v183
	v_log_f32_e32 v74, v74
	v_log_f32_e32 v75, v75
	v_log_f32_e32 v76, v76
	v_log_f32_e32 v77, v77
	v_cndmask_b32_e64 v180, 0, v213, s[50:51]
	v_cndmask_b32_e64 v181, 0, v213, s[52:53]
	v_cndmask_b32_e64 v182, 0, v213, s[54:55]
	v_cndmask_b32_e64 v183, 0, v213, s[56:57]
	v_mul_f32_e32 v176, 0x3f317217, v74
	v_mul_f32_e32 v177, 0x3f317217, v75
	v_mul_f32_e32 v178, 0x3f317217, v76
	v_mul_f32_e32 v179, 0x3f317217, v77
	v_fma_f32 v176, v74, s24, -v176
	v_fma_f32 v177, v75, s24, -v177
	v_fma_f32 v178, v76, s24, -v178
	v_fma_f32 v179, v77, s24, -v179
	v_fmac_f32_e32 v176, 0x3377d1cf, v74
	v_fmac_f32_e32 v177, 0x3377d1cf, v75
	v_fmac_f32_e32 v178, 0x3377d1cf, v76
	v_fmac_f32_e32 v179, 0x3377d1cf, v77
	v_fmac_f32_e32 v176, 0x3f317217, v74
	v_fmac_f32_e32 v177, 0x3f317217, v75
	v_fmac_f32_e32 v178, 0x3f317217, v76
	v_fmac_f32_e32 v179, 0x3f317217, v77
	v_cmp_lt_f32_e64 s[58:59], |v74|, s15
	v_cmp_lt_f32_e64 s[60:61], |v75|, s15
	v_cmp_lt_f32_e64 s[62:63], |v76|, s15
	v_cmp_lt_f32_e64 s[40:41], |v77|, s15
	v_cndmask_b32_e64 v74, v74, v176, s[58:59]
	v_cndmask_b32_e64 v75, v75, v177, s[60:61]
	v_cndmask_b32_e64 v76, v76, v178, s[62:63]
	v_cndmask_b32_e64 v77, v77, v179, s[40:41]
	v_sub_f32_e32 v74, v74, v180
	v_sub_f32_e32 v75, v75, v181
	v_sub_f32_e32 v76, v76, v182
	v_sub_f32_e32 v77, v77, v183
	v_cvt_pk_f16_f32 v78, v78, v79
	v_cvt_pk_f16_f32 v79, v80, v81
	v_cvt_pk_f16_f32 v80, v74, v75
	v_cvt_pk_f16_f32 v81, v76, v77
	s_nop 1
	v_permlane16_swap_b32_e32 v78, v80
	v_permlane16_swap_b32_e32 v79, v81
	global_store_dwordx4 v[132:133], v[78:81], off
	v_mul_f32_e32 v176, 0xbfb8aa3b, v70
	v_mul_f32_e32 v177, 0xbfb8aa3b, v71
	v_mul_f32_e32 v178, 0xbfb8aa3b, v72
	v_mul_f32_e32 v179, 0xbfb8aa3b, v73
	v_exp_f32_e32 v176, v176
	v_exp_f32_e32 v177, v177
	v_exp_f32_e32 v178, v178
	v_exp_f32_e32 v179, v179
	v_add_f32_e32 v176, 1.0, v176
	v_add_f32_e32 v177, 1.0, v177
	v_add_f32_e32 v178, 1.0, v178
	v_add_f32_e32 v179, 1.0, v179
	v_rcp_f32_e32 v176, v176
	v_rcp_f32_e32 v177, v177
	v_rcp_f32_e32 v178, v178
	v_rcp_f32_e32 v179, v179
	v_fma_f32 v70, v176, v168, v134
	v_fma_f32 v71, v177, v169, v135
	v_fma_f32 v72, v178, v170, v136
	v_fma_f32 v73, v179, v171, v137
	v_cmp_gt_f32_e64 s[50:51], s14, v70
	v_cmp_gt_f32_e64 s[52:53], s14, v71
	v_cmp_gt_f32_e64 s[54:55], s14, v72
	v_cmp_gt_f32_e64 s[56:57], s14, v73
	v_cndmask_b32_e64 v180, 0, 32, s[50:51]
	v_cndmask_b32_e64 v181, 0, 32, s[52:53]
	v_cndmask_b32_e64 v182, 0, 32, s[54:55]
	v_cndmask_b32_e64 v183, 0, 32, s[56:57]
	v_ldexp_f32 v70, v70, v180
	v_ldexp_f32 v71, v71, v181
	v_ldexp_f32 v72, v72, v182
	v_ldexp_f32 v73, v73, v183
	v_log_f32_e32 v70, v70
	v_log_f32_e32 v71, v71
	v_log_f32_e32 v72, v72
	v_log_f32_e32 v73, v73
	v_cndmask_b32_e64 v180, 0, v213, s[50:51]
	v_cndmask_b32_e64 v181, 0, v213, s[52:53]
	v_cndmask_b32_e64 v182, 0, v213, s[54:55]
	v_cndmask_b32_e64 v183, 0, v213, s[56:57]
	v_mul_f32_e32 v176, 0x3f317217, v70
	v_mul_f32_e32 v177, 0x3f317217, v71
	v_mul_f32_e32 v178, 0x3f317217, v72
	v_mul_f32_e32 v179, 0x3f317217, v73
	v_fma_f32 v176, v70, s24, -v176
	v_fma_f32 v177, v71, s24, -v177
	v_fma_f32 v178, v72, s24, -v178
	v_fma_f32 v179, v73, s24, -v179
	v_fmac_f32_e32 v176, 0x3377d1cf, v70
	v_fmac_f32_e32 v177, 0x3377d1cf, v71
	v_fmac_f32_e32 v178, 0x3377d1cf, v72
	v_fmac_f32_e32 v179, 0x3377d1cf, v73
	v_fmac_f32_e32 v176, 0x3f317217, v70
	v_fmac_f32_e32 v177, 0x3f317217, v71
	v_fmac_f32_e32 v178, 0x3f317217, v72
	v_fmac_f32_e32 v179, 0x3f317217, v73
	v_cmp_lt_f32_e64 s[58:59], |v70|, s15
	v_cmp_lt_f32_e64 s[60:61], |v71|, s15
	v_cmp_lt_f32_e64 s[62:63], |v72|, s15
	v_cmp_lt_f32_e64 s[40:41], |v73|, s15
	v_cndmask_b32_e64 v70, v70, v176, s[58:59]
	v_cndmask_b32_e64 v71, v71, v177, s[60:61]
	v_cndmask_b32_e64 v72, v72, v178, s[62:63]
	v_cndmask_b32_e64 v73, v73, v179, s[40:41]
	v_sub_f32_e32 v70, v70, v180
	v_sub_f32_e32 v71, v71, v181
	v_sub_f32_e32 v72, v72, v182
	v_sub_f32_e32 v73, v73, v183
	v_mul_f32_e32 v176, 0xbfb8aa3b, v66
	v_mul_f32_e32 v177, 0xbfb8aa3b, v67
	v_mul_f32_e32 v178, 0xbfb8aa3b, v68
	v_mul_f32_e32 v179, 0xbfb8aa3b, v69
	v_exp_f32_e32 v176, v176
	v_exp_f32_e32 v177, v177
	v_exp_f32_e32 v178, v178
	v_exp_f32_e32 v179, v179
	v_add_f32_e32 v176, 1.0, v176
	v_add_f32_e32 v177, 1.0, v177
	v_add_f32_e32 v178, 1.0, v178
	v_add_f32_e32 v179, 1.0, v179
	v_rcp_f32_e32 v176, v176
	v_rcp_f32_e32 v177, v177
	v_rcp_f32_e32 v178, v178
	v_rcp_f32_e32 v179, v179
	v_fma_f32 v66, v176, v172, v184
	v_fma_f32 v67, v177, v173, v185
	v_fma_f32 v68, v178, v174, v186
	v_fma_f32 v69, v179, v175, v187
	v_cmp_gt_f32_e64 s[50:51], s14, v66
	v_cmp_gt_f32_e64 s[52:53], s14, v67
	v_cmp_gt_f32_e64 s[54:55], s14, v68
	v_cmp_gt_f32_e64 s[56:57], s14, v69
	v_cndmask_b32_e64 v180, 0, 32, s[50:51]
	v_cndmask_b32_e64 v181, 0, 32, s[52:53]
	v_cndmask_b32_e64 v182, 0, 32, s[54:55]
	v_cndmask_b32_e64 v183, 0, 32, s[56:57]
	v_ldexp_f32 v66, v66, v180
	v_ldexp_f32 v67, v67, v181
	v_ldexp_f32 v68, v68, v182
	v_ldexp_f32 v69, v69, v183
	v_log_f32_e32 v66, v66
	v_log_f32_e32 v67, v67
	v_log_f32_e32 v68, v68
	v_log_f32_e32 v69, v69
	v_cndmask_b32_e64 v180, 0, v213, s[50:51]
	v_cndmask_b32_e64 v181, 0, v213, s[52:53]
	v_cndmask_b32_e64 v182, 0, v213, s[54:55]
	v_cndmask_b32_e64 v183, 0, v213, s[56:57]
	v_mul_f32_e32 v176, 0x3f317217, v66
	v_mul_f32_e32 v177, 0x3f317217, v67
	v_mul_f32_e32 v178, 0x3f317217, v68
	v_mul_f32_e32 v179, 0x3f317217, v69
	v_fma_f32 v176, v66, s24, -v176
	v_fma_f32 v177, v67, s24, -v177
	v_fma_f32 v178, v68, s24, -v178
	v_fma_f32 v179, v69, s24, -v179
	v_fmac_f32_e32 v176, 0x3377d1cf, v66
	v_fmac_f32_e32 v177, 0x3377d1cf, v67
	v_fmac_f32_e32 v178, 0x3377d1cf, v68
	v_fmac_f32_e32 v179, 0x3377d1cf, v69
	v_fmac_f32_e32 v176, 0x3f317217, v66
	v_fmac_f32_e32 v177, 0x3f317217, v67
	v_fmac_f32_e32 v178, 0x3f317217, v68
	v_fmac_f32_e32 v179, 0x3f317217, v69
	v_cmp_lt_f32_e64 s[58:59], |v66|, s15
	v_cmp_lt_f32_e64 s[60:61], |v67|, s15
	v_cmp_lt_f32_e64 s[62:63], |v68|, s15
	v_cmp_lt_f32_e64 s[40:41], |v69|, s15
	v_cndmask_b32_e64 v66, v66, v176, s[58:59]
	v_cndmask_b32_e64 v67, v67, v177, s[60:61]
	v_cndmask_b32_e64 v68, v68, v178, s[62:63]
	v_cndmask_b32_e64 v69, v69, v179, s[40:41]
	v_sub_f32_e32 v66, v66, v180
	v_sub_f32_e32 v67, v67, v181
	v_sub_f32_e32 v68, v68, v182
	v_sub_f32_e32 v69, v69, v183
	v_cvt_pk_f16_f32 v70, v70, v71
	v_cvt_pk_f16_f32 v71, v72, v73
	v_cvt_pk_f16_f32 v72, v66, v67
	v_cvt_pk_f16_f32 v73, v68, v69
	s_nop 1
	v_permlane16_swap_b32_e32 v70, v72
	v_permlane16_swap_b32_e32 v71, v73
	global_store_dwordx4 v[132:133], v[70:73], off offset:64
	v_lshl_add_u64 v[132:133], v[132:133], 0, s[4:5]
	v_mul_f32_e32 v176, 0xbfb8aa3b, v62
	v_mul_f32_e32 v177, 0xbfb8aa3b, v63
	v_mul_f32_e32 v178, 0xbfb8aa3b, v64
	v_mul_f32_e32 v179, 0xbfb8aa3b, v65
	v_exp_f32_e32 v176, v176
	v_exp_f32_e32 v177, v177
	v_exp_f32_e32 v178, v178
	v_exp_f32_e32 v179, v179
	v_add_f32_e32 v176, 1.0, v176
	v_add_f32_e32 v177, 1.0, v177
	v_add_f32_e32 v178, 1.0, v178
	v_add_f32_e32 v179, 1.0, v179
	v_rcp_f32_e32 v176, v176
	v_rcp_f32_e32 v177, v177
	v_rcp_f32_e32 v178, v178
	v_rcp_f32_e32 v179, v179
	v_fma_f32 v62, v176, v156, v142
	v_fma_f32 v63, v177, v157, v143
	v_fma_f32 v64, v178, v158, v144
	v_fma_f32 v65, v179, v159, v145
	v_cmp_gt_f32_e64 s[50:51], s14, v62
	v_cmp_gt_f32_e64 s[52:53], s14, v63
	v_cmp_gt_f32_e64 s[54:55], s14, v64
	v_cmp_gt_f32_e64 s[56:57], s14, v65
	v_cndmask_b32_e64 v180, 0, 32, s[50:51]
	v_cndmask_b32_e64 v181, 0, 32, s[52:53]
	v_cndmask_b32_e64 v182, 0, 32, s[54:55]
	v_cndmask_b32_e64 v183, 0, 32, s[56:57]
	v_ldexp_f32 v62, v62, v180
	v_ldexp_f32 v63, v63, v181
	v_ldexp_f32 v64, v64, v182
	v_ldexp_f32 v65, v65, v183
	v_log_f32_e32 v62, v62
	v_log_f32_e32 v63, v63
	v_log_f32_e32 v64, v64
	v_log_f32_e32 v65, v65
	v_cndmask_b32_e64 v180, 0, v213, s[50:51]
	v_cndmask_b32_e64 v181, 0, v213, s[52:53]
	v_cndmask_b32_e64 v182, 0, v213, s[54:55]
	v_cndmask_b32_e64 v183, 0, v213, s[56:57]
	v_mul_f32_e32 v176, 0x3f317217, v62
	v_mul_f32_e32 v177, 0x3f317217, v63
	v_mul_f32_e32 v178, 0x3f317217, v64
	v_mul_f32_e32 v179, 0x3f317217, v65
	v_fma_f32 v176, v62, s24, -v176
	v_fma_f32 v177, v63, s24, -v177
	v_fma_f32 v178, v64, s24, -v178
	v_fma_f32 v179, v65, s24, -v179
	v_fmac_f32_e32 v176, 0x3377d1cf, v62
	v_fmac_f32_e32 v177, 0x3377d1cf, v63
	v_fmac_f32_e32 v178, 0x3377d1cf, v64
	v_fmac_f32_e32 v179, 0x3377d1cf, v65
	v_fmac_f32_e32 v176, 0x3f317217, v62
	v_fmac_f32_e32 v177, 0x3f317217, v63
	v_fmac_f32_e32 v178, 0x3f317217, v64
	v_fmac_f32_e32 v179, 0x3f317217, v65
	v_cmp_lt_f32_e64 s[58:59], |v62|, s15
	v_cmp_lt_f32_e64 s[60:61], |v63|, s15
	v_cmp_lt_f32_e64 s[62:63], |v64|, s15
	v_cmp_lt_f32_e64 s[40:41], |v65|, s15
	v_cndmask_b32_e64 v62, v62, v176, s[58:59]
	v_cndmask_b32_e64 v63, v63, v177, s[60:61]
	v_cndmask_b32_e64 v64, v64, v178, s[62:63]
	v_cndmask_b32_e64 v65, v65, v179, s[40:41]
	v_sub_f32_e32 v62, v62, v180
	v_sub_f32_e32 v63, v63, v181
	v_sub_f32_e32 v64, v64, v182
	v_sub_f32_e32 v65, v65, v183
	v_mul_f32_e32 v176, 0xbfb8aa3b, v58
	v_mul_f32_e32 v177, 0xbfb8aa3b, v59
	v_mul_f32_e32 v178, 0xbfb8aa3b, v60
	v_mul_f32_e32 v179, 0xbfb8aa3b, v61
	v_exp_f32_e32 v176, v176
	v_exp_f32_e32 v177, v177
	v_exp_f32_e32 v178, v178
	v_exp_f32_e32 v179, v179
	v_add_f32_e32 v176, 1.0, v176
	v_add_f32_e32 v177, 1.0, v177
	v_add_f32_e32 v178, 1.0, v178
	v_add_f32_e32 v179, 1.0, v179
	v_rcp_f32_e32 v176, v176
	v_rcp_f32_e32 v177, v177
	v_rcp_f32_e32 v178, v178
	v_rcp_f32_e32 v179, v179
	v_fma_f32 v58, v176, v164, v138
	v_fma_f32 v59, v177, v165, v139
	v_fma_f32 v60, v178, v166, v140
	v_fma_f32 v61, v179, v167, v141
	v_cmp_gt_f32_e64 s[50:51], s14, v58
	v_cmp_gt_f32_e64 s[52:53], s14, v59
	v_cmp_gt_f32_e64 s[54:55], s14, v60
	v_cmp_gt_f32_e64 s[56:57], s14, v61
	v_cndmask_b32_e64 v180, 0, 32, s[50:51]
	v_cndmask_b32_e64 v181, 0, 32, s[52:53]
	v_cndmask_b32_e64 v182, 0, 32, s[54:55]
	v_cndmask_b32_e64 v183, 0, 32, s[56:57]
	v_ldexp_f32 v58, v58, v180
	v_ldexp_f32 v59, v59, v181
	v_ldexp_f32 v60, v60, v182
	v_ldexp_f32 v61, v61, v183
	v_log_f32_e32 v58, v58
	v_log_f32_e32 v59, v59
	v_log_f32_e32 v60, v60
	v_log_f32_e32 v61, v61
	v_cndmask_b32_e64 v180, 0, v213, s[50:51]
	v_cndmask_b32_e64 v181, 0, v213, s[52:53]
	v_cndmask_b32_e64 v182, 0, v213, s[54:55]
	v_cndmask_b32_e64 v183, 0, v213, s[56:57]
	v_mul_f32_e32 v176, 0x3f317217, v58
	v_mul_f32_e32 v177, 0x3f317217, v59
	v_mul_f32_e32 v178, 0x3f317217, v60
	v_mul_f32_e32 v179, 0x3f317217, v61
	v_fma_f32 v176, v58, s24, -v176
	v_fma_f32 v177, v59, s24, -v177
	v_fma_f32 v178, v60, s24, -v178
	v_fma_f32 v179, v61, s24, -v179
	v_fmac_f32_e32 v176, 0x3377d1cf, v58
	v_fmac_f32_e32 v177, 0x3377d1cf, v59
	v_fmac_f32_e32 v178, 0x3377d1cf, v60
	v_fmac_f32_e32 v179, 0x3377d1cf, v61
	v_fmac_f32_e32 v176, 0x3f317217, v58
	v_fmac_f32_e32 v177, 0x3f317217, v59
	v_fmac_f32_e32 v178, 0x3f317217, v60
	v_fmac_f32_e32 v179, 0x3f317217, v61
	v_cmp_lt_f32_e64 s[58:59], |v58|, s15
	v_cmp_lt_f32_e64 s[60:61], |v59|, s15
	v_cmp_lt_f32_e64 s[62:63], |v60|, s15
	v_cmp_lt_f32_e64 s[40:41], |v61|, s15
	v_cndmask_b32_e64 v58, v58, v176, s[58:59]
	v_cndmask_b32_e64 v59, v59, v177, s[60:61]
	v_cndmask_b32_e64 v60, v60, v178, s[62:63]
	v_cndmask_b32_e64 v61, v61, v179, s[40:41]
	v_sub_f32_e32 v58, v58, v180
	v_sub_f32_e32 v59, v59, v181
	v_sub_f32_e32 v60, v60, v182
	v_sub_f32_e32 v61, v61, v183
	v_cvt_pk_f16_f32 v62, v62, v63
	v_cvt_pk_f16_f32 v63, v64, v65
	v_cvt_pk_f16_f32 v64, v58, v59
	v_cvt_pk_f16_f32 v65, v60, v61
	s_nop 1
	v_permlane16_swap_b32_e32 v62, v64
	v_permlane16_swap_b32_e32 v63, v65
	global_store_dwordx4 v[132:133], v[62:65], off
	v_mul_f32_e32 v176, 0xbfb8aa3b, v54
	v_mul_f32_e32 v177, 0xbfb8aa3b, v55
	v_mul_f32_e32 v178, 0xbfb8aa3b, v56
	v_mul_f32_e32 v179, 0xbfb8aa3b, v57
	v_exp_f32_e32 v176, v176
	v_exp_f32_e32 v177, v177
	v_exp_f32_e32 v178, v178
	v_exp_f32_e32 v179, v179
	v_add_f32_e32 v176, 1.0, v176
	v_add_f32_e32 v177, 1.0, v177
	v_add_f32_e32 v178, 1.0, v178
	v_add_f32_e32 v179, 1.0, v179
	v_rcp_f32_e32 v176, v176
	v_rcp_f32_e32 v177, v177
	v_rcp_f32_e32 v178, v178
	v_rcp_f32_e32 v179, v179
	v_fma_f32 v54, v176, v168, v134
	v_fma_f32 v55, v177, v169, v135
	v_fma_f32 v56, v178, v170, v136
	v_fma_f32 v57, v179, v171, v137
	v_cmp_gt_f32_e64 s[50:51], s14, v54
	v_cmp_gt_f32_e64 s[52:53], s14, v55
	v_cmp_gt_f32_e64 s[54:55], s14, v56
	v_cmp_gt_f32_e64 s[56:57], s14, v57
	v_cndmask_b32_e64 v180, 0, 32, s[50:51]
	v_cndmask_b32_e64 v181, 0, 32, s[52:53]
	v_cndmask_b32_e64 v182, 0, 32, s[54:55]
	v_cndmask_b32_e64 v183, 0, 32, s[56:57]
	v_ldexp_f32 v54, v54, v180
	v_ldexp_f32 v55, v55, v181
	v_ldexp_f32 v56, v56, v182
	v_ldexp_f32 v57, v57, v183
	v_log_f32_e32 v54, v54
	v_log_f32_e32 v55, v55
	v_log_f32_e32 v56, v56
	v_log_f32_e32 v57, v57
	v_cndmask_b32_e64 v180, 0, v213, s[50:51]
	v_cndmask_b32_e64 v181, 0, v213, s[52:53]
	v_cndmask_b32_e64 v182, 0, v213, s[54:55]
	v_cndmask_b32_e64 v183, 0, v213, s[56:57]
	v_mul_f32_e32 v176, 0x3f317217, v54
	v_mul_f32_e32 v177, 0x3f317217, v55
	v_mul_f32_e32 v178, 0x3f317217, v56
	v_mul_f32_e32 v179, 0x3f317217, v57
	v_fma_f32 v176, v54, s24, -v176
	v_fma_f32 v177, v55, s24, -v177
	v_fma_f32 v178, v56, s24, -v178
	v_fma_f32 v179, v57, s24, -v179
	v_fmac_f32_e32 v176, 0x3377d1cf, v54
	v_fmac_f32_e32 v177, 0x3377d1cf, v55
	v_fmac_f32_e32 v178, 0x3377d1cf, v56
	v_fmac_f32_e32 v179, 0x3377d1cf, v57
	v_fmac_f32_e32 v176, 0x3f317217, v54
	v_fmac_f32_e32 v177, 0x3f317217, v55
	v_fmac_f32_e32 v178, 0x3f317217, v56
	v_fmac_f32_e32 v179, 0x3f317217, v57
	v_cmp_lt_f32_e64 s[58:59], |v54|, s15
	v_cmp_lt_f32_e64 s[60:61], |v55|, s15
	v_cmp_lt_f32_e64 s[62:63], |v56|, s15
	v_cmp_lt_f32_e64 s[40:41], |v57|, s15
	v_cndmask_b32_e64 v54, v54, v176, s[58:59]
	v_cndmask_b32_e64 v55, v55, v177, s[60:61]
	v_cndmask_b32_e64 v56, v56, v178, s[62:63]
	v_cndmask_b32_e64 v57, v57, v179, s[40:41]
	v_sub_f32_e32 v54, v54, v180
	v_sub_f32_e32 v55, v55, v181
	v_sub_f32_e32 v56, v56, v182
	v_sub_f32_e32 v57, v57, v183
	v_mul_f32_e32 v176, 0xbfb8aa3b, v50
	v_mul_f32_e32 v177, 0xbfb8aa3b, v51
	v_mul_f32_e32 v178, 0xbfb8aa3b, v52
	v_mul_f32_e32 v179, 0xbfb8aa3b, v53
	v_exp_f32_e32 v176, v176
	v_exp_f32_e32 v177, v177
	v_exp_f32_e32 v178, v178
	v_exp_f32_e32 v179, v179
	v_add_f32_e32 v176, 1.0, v176
	v_add_f32_e32 v177, 1.0, v177
	v_add_f32_e32 v178, 1.0, v178
	v_add_f32_e32 v179, 1.0, v179
	v_rcp_f32_e32 v176, v176
	v_rcp_f32_e32 v177, v177
	v_rcp_f32_e32 v178, v178
	v_rcp_f32_e32 v179, v179
	v_fma_f32 v50, v176, v172, v184
	v_fma_f32 v51, v177, v173, v185
	v_fma_f32 v52, v178, v174, v186
	v_fma_f32 v53, v179, v175, v187
	v_cmp_gt_f32_e64 s[50:51], s14, v50
	v_cmp_gt_f32_e64 s[52:53], s14, v51
	v_cmp_gt_f32_e64 s[54:55], s14, v52
	v_cmp_gt_f32_e64 s[56:57], s14, v53
	v_cndmask_b32_e64 v180, 0, 32, s[50:51]
	v_cndmask_b32_e64 v181, 0, 32, s[52:53]
	v_cndmask_b32_e64 v182, 0, 32, s[54:55]
	v_cndmask_b32_e64 v183, 0, 32, s[56:57]
	v_ldexp_f32 v50, v50, v180
	v_ldexp_f32 v51, v51, v181
	v_ldexp_f32 v52, v52, v182
	v_ldexp_f32 v53, v53, v183
	v_log_f32_e32 v50, v50
	v_log_f32_e32 v51, v51
	v_log_f32_e32 v52, v52
	v_log_f32_e32 v53, v53
	v_cndmask_b32_e64 v180, 0, v213, s[50:51]
	v_cndmask_b32_e64 v181, 0, v213, s[52:53]
	v_cndmask_b32_e64 v182, 0, v213, s[54:55]
	v_cndmask_b32_e64 v183, 0, v213, s[56:57]
	v_mul_f32_e32 v176, 0x3f317217, v50
	v_mul_f32_e32 v177, 0x3f317217, v51
	v_mul_f32_e32 v178, 0x3f317217, v52
	v_mul_f32_e32 v179, 0x3f317217, v53
	v_fma_f32 v176, v50, s24, -v176
	v_fma_f32 v177, v51, s24, -v177
	v_fma_f32 v178, v52, s24, -v178
	v_fma_f32 v179, v53, s24, -v179
	v_fmac_f32_e32 v176, 0x3377d1cf, v50
	v_fmac_f32_e32 v177, 0x3377d1cf, v51
	v_fmac_f32_e32 v178, 0x3377d1cf, v52
	v_fmac_f32_e32 v179, 0x3377d1cf, v53
	v_fmac_f32_e32 v176, 0x3f317217, v50
	v_fmac_f32_e32 v177, 0x3f317217, v51
	v_fmac_f32_e32 v178, 0x3f317217, v52
	v_fmac_f32_e32 v179, 0x3f317217, v53
	v_cmp_lt_f32_e64 s[58:59], |v50|, s15
	v_cmp_lt_f32_e64 s[60:61], |v51|, s15
	v_cmp_lt_f32_e64 s[62:63], |v52|, s15
	v_cmp_lt_f32_e64 s[40:41], |v53|, s15
	v_cndmask_b32_e64 v50, v50, v176, s[58:59]
	v_cndmask_b32_e64 v51, v51, v177, s[60:61]
	v_cndmask_b32_e64 v52, v52, v178, s[62:63]
	v_cndmask_b32_e64 v53, v53, v179, s[40:41]
	v_sub_f32_e32 v50, v50, v180
	v_sub_f32_e32 v51, v51, v181
	v_sub_f32_e32 v52, v52, v182
	v_sub_f32_e32 v53, v53, v183
	v_cvt_pk_f16_f32 v54, v54, v55
	v_cvt_pk_f16_f32 v55, v56, v57
	v_cvt_pk_f16_f32 v56, v50, v51
	v_cvt_pk_f16_f32 v57, v52, v53
	s_nop 1
	v_permlane16_swap_b32_e32 v54, v56
	v_permlane16_swap_b32_e32 v55, v57
	global_store_dwordx4 v[132:133], v[54:57], off offset:64
	v_lshl_add_u64 v[132:133], v[132:133], 0, s[4:5]
	v_mul_f32_e32 v176, 0xbfb8aa3b, v46
	v_mul_f32_e32 v177, 0xbfb8aa3b, v47
	v_mul_f32_e32 v178, 0xbfb8aa3b, v48
	v_mul_f32_e32 v179, 0xbfb8aa3b, v49
	v_exp_f32_e32 v176, v176
	v_exp_f32_e32 v177, v177
	v_exp_f32_e32 v178, v178
	v_exp_f32_e32 v179, v179
	v_add_f32_e32 v176, 1.0, v176
	v_add_f32_e32 v177, 1.0, v177
	v_add_f32_e32 v178, 1.0, v178
	v_add_f32_e32 v179, 1.0, v179
	v_rcp_f32_e32 v176, v176
	v_rcp_f32_e32 v177, v177
	v_rcp_f32_e32 v178, v178
	v_rcp_f32_e32 v179, v179
	v_fma_f32 v46, v176, v156, v142
	v_fma_f32 v47, v177, v157, v143
	v_fma_f32 v48, v178, v158, v144
	v_fma_f32 v49, v179, v159, v145
	v_cmp_gt_f32_e64 s[50:51], s14, v46
	v_cmp_gt_f32_e64 s[52:53], s14, v47
	v_cmp_gt_f32_e64 s[54:55], s14, v48
	v_cmp_gt_f32_e64 s[56:57], s14, v49
	v_cndmask_b32_e64 v180, 0, 32, s[50:51]
	v_cndmask_b32_e64 v181, 0, 32, s[52:53]
	v_cndmask_b32_e64 v182, 0, 32, s[54:55]
	v_cndmask_b32_e64 v183, 0, 32, s[56:57]
	v_ldexp_f32 v46, v46, v180
	v_ldexp_f32 v47, v47, v181
	v_ldexp_f32 v48, v48, v182
	v_ldexp_f32 v49, v49, v183
	v_log_f32_e32 v46, v46
	v_log_f32_e32 v47, v47
	v_log_f32_e32 v48, v48
	v_log_f32_e32 v49, v49
	v_cndmask_b32_e64 v180, 0, v213, s[50:51]
	v_cndmask_b32_e64 v181, 0, v213, s[52:53]
	v_cndmask_b32_e64 v182, 0, v213, s[54:55]
	v_cndmask_b32_e64 v183, 0, v213, s[56:57]
	v_mul_f32_e32 v176, 0x3f317217, v46
	v_mul_f32_e32 v177, 0x3f317217, v47
	v_mul_f32_e32 v178, 0x3f317217, v48
	v_mul_f32_e32 v179, 0x3f317217, v49
	v_fma_f32 v176, v46, s24, -v176
	v_fma_f32 v177, v47, s24, -v177
	v_fma_f32 v178, v48, s24, -v178
	v_fma_f32 v179, v49, s24, -v179
	v_fmac_f32_e32 v176, 0x3377d1cf, v46
	v_fmac_f32_e32 v177, 0x3377d1cf, v47
	v_fmac_f32_e32 v178, 0x3377d1cf, v48
	v_fmac_f32_e32 v179, 0x3377d1cf, v49
	v_fmac_f32_e32 v176, 0x3f317217, v46
	v_fmac_f32_e32 v177, 0x3f317217, v47
	v_fmac_f32_e32 v178, 0x3f317217, v48
	v_fmac_f32_e32 v179, 0x3f317217, v49
	v_cmp_lt_f32_e64 s[58:59], |v46|, s15
	v_cmp_lt_f32_e64 s[60:61], |v47|, s15
	v_cmp_lt_f32_e64 s[62:63], |v48|, s15
	v_cmp_lt_f32_e64 s[40:41], |v49|, s15
	v_cndmask_b32_e64 v46, v46, v176, s[58:59]
	v_cndmask_b32_e64 v47, v47, v177, s[60:61]
	v_cndmask_b32_e64 v48, v48, v178, s[62:63]
	v_cndmask_b32_e64 v49, v49, v179, s[40:41]
	v_sub_f32_e32 v46, v46, v180
	v_sub_f32_e32 v47, v47, v181
	v_sub_f32_e32 v48, v48, v182
	v_sub_f32_e32 v49, v49, v183
	v_mul_f32_e32 v176, 0xbfb8aa3b, v42
	v_mul_f32_e32 v177, 0xbfb8aa3b, v43
	v_mul_f32_e32 v178, 0xbfb8aa3b, v44
	v_mul_f32_e32 v179, 0xbfb8aa3b, v45
	v_exp_f32_e32 v176, v176
	v_exp_f32_e32 v177, v177
	v_exp_f32_e32 v178, v178
	v_exp_f32_e32 v179, v179
	v_add_f32_e32 v176, 1.0, v176
	v_add_f32_e32 v177, 1.0, v177
	v_add_f32_e32 v178, 1.0, v178
	v_add_f32_e32 v179, 1.0, v179
	v_rcp_f32_e32 v176, v176
	v_rcp_f32_e32 v177, v177
	v_rcp_f32_e32 v178, v178
	v_rcp_f32_e32 v179, v179
	v_fma_f32 v42, v176, v164, v138
	v_fma_f32 v43, v177, v165, v139
	v_fma_f32 v44, v178, v166, v140
	v_fma_f32 v45, v179, v167, v141
	v_cmp_gt_f32_e64 s[50:51], s14, v42
	v_cmp_gt_f32_e64 s[52:53], s14, v43
	v_cmp_gt_f32_e64 s[54:55], s14, v44
	v_cmp_gt_f32_e64 s[56:57], s14, v45
	v_cndmask_b32_e64 v180, 0, 32, s[50:51]
	v_cndmask_b32_e64 v181, 0, 32, s[52:53]
	v_cndmask_b32_e64 v182, 0, 32, s[54:55]
	v_cndmask_b32_e64 v183, 0, 32, s[56:57]
	v_ldexp_f32 v42, v42, v180
	v_ldexp_f32 v43, v43, v181
	v_ldexp_f32 v44, v44, v182
	v_ldexp_f32 v45, v45, v183
	v_log_f32_e32 v42, v42
	v_log_f32_e32 v43, v43
	v_log_f32_e32 v44, v44
	v_log_f32_e32 v45, v45
	v_cndmask_b32_e64 v180, 0, v213, s[50:51]
	v_cndmask_b32_e64 v181, 0, v213, s[52:53]
	v_cndmask_b32_e64 v182, 0, v213, s[54:55]
	v_cndmask_b32_e64 v183, 0, v213, s[56:57]
	v_mul_f32_e32 v176, 0x3f317217, v42
	v_mul_f32_e32 v177, 0x3f317217, v43
	v_mul_f32_e32 v178, 0x3f317217, v44
	v_mul_f32_e32 v179, 0x3f317217, v45
	v_fma_f32 v176, v42, s24, -v176
	v_fma_f32 v177, v43, s24, -v177
	v_fma_f32 v178, v44, s24, -v178
	v_fma_f32 v179, v45, s24, -v179
	v_fmac_f32_e32 v176, 0x3377d1cf, v42
	v_fmac_f32_e32 v177, 0x3377d1cf, v43
	v_fmac_f32_e32 v178, 0x3377d1cf, v44
	v_fmac_f32_e32 v179, 0x3377d1cf, v45
	v_fmac_f32_e32 v176, 0x3f317217, v42
	v_fmac_f32_e32 v177, 0x3f317217, v43
	v_fmac_f32_e32 v178, 0x3f317217, v44
	v_fmac_f32_e32 v179, 0x3f317217, v45
	v_cmp_lt_f32_e64 s[58:59], |v42|, s15
	v_cmp_lt_f32_e64 s[60:61], |v43|, s15
	v_cmp_lt_f32_e64 s[62:63], |v44|, s15
	v_cmp_lt_f32_e64 s[40:41], |v45|, s15
	v_cndmask_b32_e64 v42, v42, v176, s[58:59]
	v_cndmask_b32_e64 v43, v43, v177, s[60:61]
	v_cndmask_b32_e64 v44, v44, v178, s[62:63]
	v_cndmask_b32_e64 v45, v45, v179, s[40:41]
	v_sub_f32_e32 v42, v42, v180
	v_sub_f32_e32 v43, v43, v181
	v_sub_f32_e32 v44, v44, v182
	v_sub_f32_e32 v45, v45, v183
	v_cvt_pk_f16_f32 v46, v46, v47
	v_cvt_pk_f16_f32 v47, v48, v49
	v_cvt_pk_f16_f32 v48, v42, v43
	v_cvt_pk_f16_f32 v49, v44, v45
	s_nop 1
	v_permlane16_swap_b32_e32 v46, v48
	v_permlane16_swap_b32_e32 v47, v49
	global_store_dwordx4 v[132:133], v[46:49], off
	v_mul_f32_e32 v176, 0xbfb8aa3b, v34
	v_mul_f32_e32 v177, 0xbfb8aa3b, v35
	v_mul_f32_e32 v178, 0xbfb8aa3b, v36
	v_mul_f32_e32 v179, 0xbfb8aa3b, v37
	v_exp_f32_e32 v176, v176
	v_exp_f32_e32 v177, v177
	v_exp_f32_e32 v178, v178
	v_exp_f32_e32 v179, v179
	v_add_f32_e32 v176, 1.0, v176
	v_add_f32_e32 v177, 1.0, v177
	v_add_f32_e32 v178, 1.0, v178
	v_add_f32_e32 v179, 1.0, v179
	v_rcp_f32_e32 v176, v176
	v_rcp_f32_e32 v177, v177
	v_rcp_f32_e32 v178, v178
	v_rcp_f32_e32 v179, v179
	v_fma_f32 v34, v176, v168, v134
	v_fma_f32 v35, v177, v169, v135
	v_fma_f32 v36, v178, v170, v136
	v_fma_f32 v37, v179, v171, v137
	v_cmp_gt_f32_e64 s[50:51], s14, v34
	v_cmp_gt_f32_e64 s[52:53], s14, v35
	v_cmp_gt_f32_e64 s[54:55], s14, v36
	v_cmp_gt_f32_e64 s[56:57], s14, v37
	v_cndmask_b32_e64 v180, 0, 32, s[50:51]
	v_cndmask_b32_e64 v181, 0, 32, s[52:53]
	v_cndmask_b32_e64 v182, 0, 32, s[54:55]
	v_cndmask_b32_e64 v183, 0, 32, s[56:57]
	v_ldexp_f32 v34, v34, v180
	v_ldexp_f32 v35, v35, v181
	v_ldexp_f32 v36, v36, v182
	v_ldexp_f32 v37, v37, v183
	v_log_f32_e32 v34, v34
	v_log_f32_e32 v35, v35
	v_log_f32_e32 v36, v36
	v_log_f32_e32 v37, v37
	v_cndmask_b32_e64 v180, 0, v213, s[50:51]
	v_cndmask_b32_e64 v181, 0, v213, s[52:53]
	v_cndmask_b32_e64 v182, 0, v213, s[54:55]
	v_cndmask_b32_e64 v183, 0, v213, s[56:57]
	v_mul_f32_e32 v176, 0x3f317217, v34
	v_mul_f32_e32 v177, 0x3f317217, v35
	v_mul_f32_e32 v178, 0x3f317217, v36
	v_mul_f32_e32 v179, 0x3f317217, v37
	v_fma_f32 v176, v34, s24, -v176
	v_fma_f32 v177, v35, s24, -v177
	v_fma_f32 v178, v36, s24, -v178
	v_fma_f32 v179, v37, s24, -v179
	v_fmac_f32_e32 v176, 0x3377d1cf, v34
	v_fmac_f32_e32 v177, 0x3377d1cf, v35
	v_fmac_f32_e32 v178, 0x3377d1cf, v36
	v_fmac_f32_e32 v179, 0x3377d1cf, v37
	v_fmac_f32_e32 v176, 0x3f317217, v34
	v_fmac_f32_e32 v177, 0x3f317217, v35
	v_fmac_f32_e32 v178, 0x3f317217, v36
	v_fmac_f32_e32 v179, 0x3f317217, v37
	v_cmp_lt_f32_e64 s[58:59], |v34|, s15
	v_cmp_lt_f32_e64 s[60:61], |v35|, s15
	v_cmp_lt_f32_e64 s[62:63], |v36|, s15
	v_cmp_lt_f32_e64 s[40:41], |v37|, s15
	v_cndmask_b32_e64 v34, v34, v176, s[58:59]
	v_cndmask_b32_e64 v35, v35, v177, s[60:61]
	v_cndmask_b32_e64 v36, v36, v178, s[62:63]
	v_cndmask_b32_e64 v37, v37, v179, s[40:41]
	v_sub_f32_e32 v34, v34, v180
	v_sub_f32_e32 v35, v35, v181
	v_sub_f32_e32 v36, v36, v182
	v_sub_f32_e32 v37, v37, v183
	v_mul_f32_e32 v176, 0xbfb8aa3b, v30
	v_mul_f32_e32 v177, 0xbfb8aa3b, v31
	v_mul_f32_e32 v178, 0xbfb8aa3b, v32
	v_mul_f32_e32 v179, 0xbfb8aa3b, v33
	v_exp_f32_e32 v176, v176
	v_exp_f32_e32 v177, v177
	v_exp_f32_e32 v178, v178
	v_exp_f32_e32 v179, v179
	v_add_f32_e32 v176, 1.0, v176
	v_add_f32_e32 v177, 1.0, v177
	v_add_f32_e32 v178, 1.0, v178
	v_add_f32_e32 v179, 1.0, v179
	v_rcp_f32_e32 v176, v176
	v_rcp_f32_e32 v177, v177
	v_rcp_f32_e32 v178, v178
	v_rcp_f32_e32 v179, v179
	v_fma_f32 v30, v176, v172, v184
	v_fma_f32 v31, v177, v173, v185
	v_fma_f32 v32, v178, v174, v186
	v_fma_f32 v33, v179, v175, v187
	v_cmp_gt_f32_e64 s[50:51], s14, v30
	v_cmp_gt_f32_e64 s[52:53], s14, v31
	v_cmp_gt_f32_e64 s[54:55], s14, v32
	v_cmp_gt_f32_e64 s[56:57], s14, v33
	v_cndmask_b32_e64 v180, 0, 32, s[50:51]
	v_cndmask_b32_e64 v181, 0, 32, s[52:53]
	v_cndmask_b32_e64 v182, 0, 32, s[54:55]
	v_cndmask_b32_e64 v183, 0, 32, s[56:57]
	v_ldexp_f32 v30, v30, v180
	v_ldexp_f32 v31, v31, v181
	v_ldexp_f32 v32, v32, v182
	v_ldexp_f32 v33, v33, v183
	v_log_f32_e32 v30, v30
	v_log_f32_e32 v31, v31
	v_log_f32_e32 v32, v32
	v_log_f32_e32 v33, v33
	v_cndmask_b32_e64 v180, 0, v213, s[50:51]
	v_cndmask_b32_e64 v181, 0, v213, s[52:53]
	v_cndmask_b32_e64 v182, 0, v213, s[54:55]
	v_cndmask_b32_e64 v183, 0, v213, s[56:57]
	v_mul_f32_e32 v176, 0x3f317217, v30
	v_mul_f32_e32 v177, 0x3f317217, v31
	v_mul_f32_e32 v178, 0x3f317217, v32
	v_mul_f32_e32 v179, 0x3f317217, v33
	v_fma_f32 v176, v30, s24, -v176
	v_fma_f32 v177, v31, s24, -v177
	v_fma_f32 v178, v32, s24, -v178
	v_fma_f32 v179, v33, s24, -v179
	v_fmac_f32_e32 v176, 0x3377d1cf, v30
	v_fmac_f32_e32 v177, 0x3377d1cf, v31
	v_fmac_f32_e32 v178, 0x3377d1cf, v32
	v_fmac_f32_e32 v179, 0x3377d1cf, v33
	v_fmac_f32_e32 v176, 0x3f317217, v30
	v_fmac_f32_e32 v177, 0x3f317217, v31
	v_fmac_f32_e32 v178, 0x3f317217, v32
	v_fmac_f32_e32 v179, 0x3f317217, v33
	v_cmp_lt_f32_e64 s[58:59], |v30|, s15
	v_cmp_lt_f32_e64 s[60:61], |v31|, s15
	v_cmp_lt_f32_e64 s[62:63], |v32|, s15
	v_cmp_lt_f32_e64 s[40:41], |v33|, s15
	v_cndmask_b32_e64 v30, v30, v176, s[58:59]
	v_cndmask_b32_e64 v31, v31, v177, s[60:61]
	v_cndmask_b32_e64 v32, v32, v178, s[62:63]
	v_cndmask_b32_e64 v33, v33, v179, s[40:41]
	v_sub_f32_e32 v30, v30, v180
	v_sub_f32_e32 v31, v31, v181
	v_sub_f32_e32 v32, v32, v182
	v_sub_f32_e32 v33, v33, v183
	v_cvt_pk_f16_f32 v34, v34, v35
	v_cvt_pk_f16_f32 v35, v36, v37
	v_cvt_pk_f16_f32 v36, v30, v31
	v_cvt_pk_f16_f32 v37, v32, v33
	s_nop 1
	v_permlane16_swap_b32_e32 v34, v36
	v_permlane16_swap_b32_e32 v35, v37
	global_store_dwordx4 v[132:133], v[34:37], off offset:64
	v_lshl_add_u64 v[132:133], v[132:133], 0, s[4:5]
	v_mul_f32_e32 v176, 0xbfb8aa3b, v38
	v_mul_f32_e32 v177, 0xbfb8aa3b, v39
	v_mul_f32_e32 v178, 0xbfb8aa3b, v40
	v_mul_f32_e32 v179, 0xbfb8aa3b, v41
	v_exp_f32_e32 v176, v176
	v_exp_f32_e32 v177, v177
	v_exp_f32_e32 v178, v178
	v_exp_f32_e32 v179, v179
	v_add_f32_e32 v176, 1.0, v176
	v_add_f32_e32 v177, 1.0, v177
	v_add_f32_e32 v178, 1.0, v178
	v_add_f32_e32 v179, 1.0, v179
	v_rcp_f32_e32 v176, v176
	v_rcp_f32_e32 v177, v177
	v_rcp_f32_e32 v178, v178
	v_rcp_f32_e32 v179, v179
	v_fma_f32 v38, v176, v156, v142
	v_fma_f32 v39, v177, v157, v143
	v_fma_f32 v40, v178, v158, v144
	v_fma_f32 v41, v179, v159, v145
	v_cmp_gt_f32_e64 s[50:51], s14, v38
	v_cmp_gt_f32_e64 s[52:53], s14, v39
	v_cmp_gt_f32_e64 s[54:55], s14, v40
	v_cmp_gt_f32_e64 s[56:57], s14, v41
	v_cndmask_b32_e64 v180, 0, 32, s[50:51]
	v_cndmask_b32_e64 v181, 0, 32, s[52:53]
	v_cndmask_b32_e64 v182, 0, 32, s[54:55]
	v_cndmask_b32_e64 v183, 0, 32, s[56:57]
	v_ldexp_f32 v38, v38, v180
	v_ldexp_f32 v39, v39, v181
	v_ldexp_f32 v40, v40, v182
	v_ldexp_f32 v41, v41, v183
	v_log_f32_e32 v38, v38
	v_log_f32_e32 v39, v39
	v_log_f32_e32 v40, v40
	v_log_f32_e32 v41, v41
	v_cndmask_b32_e64 v180, 0, v213, s[50:51]
	v_cndmask_b32_e64 v181, 0, v213, s[52:53]
	v_cndmask_b32_e64 v182, 0, v213, s[54:55]
	v_cndmask_b32_e64 v183, 0, v213, s[56:57]
	v_mul_f32_e32 v176, 0x3f317217, v38
	v_mul_f32_e32 v177, 0x3f317217, v39
	v_mul_f32_e32 v178, 0x3f317217, v40
	v_mul_f32_e32 v179, 0x3f317217, v41
	v_fma_f32 v176, v38, s24, -v176
	v_fma_f32 v177, v39, s24, -v177
	v_fma_f32 v178, v40, s24, -v178
	v_fma_f32 v179, v41, s24, -v179
	v_fmac_f32_e32 v176, 0x3377d1cf, v38
	v_fmac_f32_e32 v177, 0x3377d1cf, v39
	v_fmac_f32_e32 v178, 0x3377d1cf, v40
	v_fmac_f32_e32 v179, 0x3377d1cf, v41
	v_fmac_f32_e32 v176, 0x3f317217, v38
	v_fmac_f32_e32 v177, 0x3f317217, v39
	v_fmac_f32_e32 v178, 0x3f317217, v40
	v_fmac_f32_e32 v179, 0x3f317217, v41
	v_cmp_lt_f32_e64 s[58:59], |v38|, s15
	v_cmp_lt_f32_e64 s[60:61], |v39|, s15
	v_cmp_lt_f32_e64 s[62:63], |v40|, s15
	v_cmp_lt_f32_e64 s[40:41], |v41|, s15
	v_cndmask_b32_e64 v38, v38, v176, s[58:59]
	v_cndmask_b32_e64 v39, v39, v177, s[60:61]
	v_cndmask_b32_e64 v40, v40, v178, s[62:63]
	v_cndmask_b32_e64 v41, v41, v179, s[40:41]
	v_sub_f32_e32 v38, v38, v180
	v_sub_f32_e32 v39, v39, v181
	v_sub_f32_e32 v40, v40, v182
	v_sub_f32_e32 v41, v41, v183
	v_mul_f32_e32 v176, 0xbfb8aa3b, v26
	v_mul_f32_e32 v177, 0xbfb8aa3b, v27
	v_mul_f32_e32 v178, 0xbfb8aa3b, v28
	v_mul_f32_e32 v179, 0xbfb8aa3b, v29
	v_exp_f32_e32 v176, v176
	v_exp_f32_e32 v177, v177
	v_exp_f32_e32 v178, v178
	v_exp_f32_e32 v179, v179
	v_add_f32_e32 v176, 1.0, v176
	v_add_f32_e32 v177, 1.0, v177
	v_add_f32_e32 v178, 1.0, v178
	v_add_f32_e32 v179, 1.0, v179
	v_rcp_f32_e32 v176, v176
	v_rcp_f32_e32 v177, v177
	v_rcp_f32_e32 v178, v178
	v_rcp_f32_e32 v179, v179
	v_fma_f32 v26, v176, v164, v138
	v_fma_f32 v27, v177, v165, v139
	v_fma_f32 v28, v178, v166, v140
	v_fma_f32 v29, v179, v167, v141
	v_cmp_gt_f32_e64 s[50:51], s14, v26
	v_cmp_gt_f32_e64 s[52:53], s14, v27
	v_cmp_gt_f32_e64 s[54:55], s14, v28
	v_cmp_gt_f32_e64 s[56:57], s14, v29
	v_cndmask_b32_e64 v180, 0, 32, s[50:51]
	v_cndmask_b32_e64 v181, 0, 32, s[52:53]
	v_cndmask_b32_e64 v182, 0, 32, s[54:55]
	v_cndmask_b32_e64 v183, 0, 32, s[56:57]
	v_ldexp_f32 v26, v26, v180
	v_ldexp_f32 v27, v27, v181
	v_ldexp_f32 v28, v28, v182
	v_ldexp_f32 v29, v29, v183
	v_log_f32_e32 v26, v26
	v_log_f32_e32 v27, v27
	v_log_f32_e32 v28, v28
	v_log_f32_e32 v29, v29
	v_cndmask_b32_e64 v180, 0, v213, s[50:51]
	v_cndmask_b32_e64 v181, 0, v213, s[52:53]
	v_cndmask_b32_e64 v182, 0, v213, s[54:55]
	v_cndmask_b32_e64 v183, 0, v213, s[56:57]
	v_mul_f32_e32 v176, 0x3f317217, v26
	v_mul_f32_e32 v177, 0x3f317217, v27
	v_mul_f32_e32 v178, 0x3f317217, v28
	v_mul_f32_e32 v179, 0x3f317217, v29
	v_fma_f32 v176, v26, s24, -v176
	v_fma_f32 v177, v27, s24, -v177
	v_fma_f32 v178, v28, s24, -v178
	v_fma_f32 v179, v29, s24, -v179
	v_fmac_f32_e32 v176, 0x3377d1cf, v26
	v_fmac_f32_e32 v177, 0x3377d1cf, v27
	v_fmac_f32_e32 v178, 0x3377d1cf, v28
	v_fmac_f32_e32 v179, 0x3377d1cf, v29
	v_fmac_f32_e32 v176, 0x3f317217, v26
	v_fmac_f32_e32 v177, 0x3f317217, v27
	v_fmac_f32_e32 v178, 0x3f317217, v28
	v_fmac_f32_e32 v179, 0x3f317217, v29
	v_cmp_lt_f32_e64 s[58:59], |v26|, s15
	v_cmp_lt_f32_e64 s[60:61], |v27|, s15
	v_cmp_lt_f32_e64 s[62:63], |v28|, s15
	v_cmp_lt_f32_e64 s[40:41], |v29|, s15
	v_cndmask_b32_e64 v26, v26, v176, s[58:59]
	v_cndmask_b32_e64 v27, v27, v177, s[60:61]
	v_cndmask_b32_e64 v28, v28, v178, s[62:63]
	v_cndmask_b32_e64 v29, v29, v179, s[40:41]
	v_sub_f32_e32 v26, v26, v180
	v_sub_f32_e32 v27, v27, v181
	v_sub_f32_e32 v28, v28, v182
	v_sub_f32_e32 v29, v29, v183
	v_cvt_pk_f16_f32 v38, v38, v39
	v_cvt_pk_f16_f32 v39, v40, v41
	v_cvt_pk_f16_f32 v40, v26, v27
	v_cvt_pk_f16_f32 v41, v28, v29
	s_nop 1
	v_permlane16_swap_b32_e32 v38, v40
	v_permlane16_swap_b32_e32 v39, v41
	global_store_dwordx4 v[132:133], v[38:41], off
	v_mul_f32_e32 v176, 0xbfb8aa3b, v22
	v_mul_f32_e32 v177, 0xbfb8aa3b, v23
	v_mul_f32_e32 v178, 0xbfb8aa3b, v24
	v_mul_f32_e32 v179, 0xbfb8aa3b, v25
	v_exp_f32_e32 v176, v176
	v_exp_f32_e32 v177, v177
	v_exp_f32_e32 v178, v178
	v_exp_f32_e32 v179, v179
	v_add_f32_e32 v176, 1.0, v176
	v_add_f32_e32 v177, 1.0, v177
	v_add_f32_e32 v178, 1.0, v178
	v_add_f32_e32 v179, 1.0, v179
	v_rcp_f32_e32 v176, v176
	v_rcp_f32_e32 v177, v177
	v_rcp_f32_e32 v178, v178
	v_rcp_f32_e32 v179, v179
	v_fma_f32 v22, v176, v168, v134
	v_fma_f32 v23, v177, v169, v135
	v_fma_f32 v24, v178, v170, v136
	v_fma_f32 v25, v179, v171, v137
	v_cmp_gt_f32_e64 s[50:51], s14, v22
	v_cmp_gt_f32_e64 s[52:53], s14, v23
	v_cmp_gt_f32_e64 s[54:55], s14, v24
	v_cmp_gt_f32_e64 s[56:57], s14, v25
	v_cndmask_b32_e64 v180, 0, 32, s[50:51]
	v_cndmask_b32_e64 v181, 0, 32, s[52:53]
	v_cndmask_b32_e64 v182, 0, 32, s[54:55]
	v_cndmask_b32_e64 v183, 0, 32, s[56:57]
	v_ldexp_f32 v22, v22, v180
	v_ldexp_f32 v23, v23, v181
	v_ldexp_f32 v24, v24, v182
	v_ldexp_f32 v25, v25, v183
	v_log_f32_e32 v22, v22
	v_log_f32_e32 v23, v23
	v_log_f32_e32 v24, v24
	v_log_f32_e32 v25, v25
	v_cndmask_b32_e64 v180, 0, v213, s[50:51]
	v_cndmask_b32_e64 v181, 0, v213, s[52:53]
	v_cndmask_b32_e64 v182, 0, v213, s[54:55]
	v_cndmask_b32_e64 v183, 0, v213, s[56:57]
	v_mul_f32_e32 v176, 0x3f317217, v22
	v_mul_f32_e32 v177, 0x3f317217, v23
	v_mul_f32_e32 v178, 0x3f317217, v24
	v_mul_f32_e32 v179, 0x3f317217, v25
	v_fma_f32 v176, v22, s24, -v176
	v_fma_f32 v177, v23, s24, -v177
	v_fma_f32 v178, v24, s24, -v178
	v_fma_f32 v179, v25, s24, -v179
	v_fmac_f32_e32 v176, 0x3377d1cf, v22
	v_fmac_f32_e32 v177, 0x3377d1cf, v23
	v_fmac_f32_e32 v178, 0x3377d1cf, v24
	v_fmac_f32_e32 v179, 0x3377d1cf, v25
	v_fmac_f32_e32 v176, 0x3f317217, v22
	v_fmac_f32_e32 v177, 0x3f317217, v23
	v_fmac_f32_e32 v178, 0x3f317217, v24
	v_fmac_f32_e32 v179, 0x3f317217, v25
	v_cmp_lt_f32_e64 s[58:59], |v22|, s15
	v_cmp_lt_f32_e64 s[60:61], |v23|, s15
	v_cmp_lt_f32_e64 s[62:63], |v24|, s15
	v_cmp_lt_f32_e64 s[40:41], |v25|, s15
	v_cndmask_b32_e64 v22, v22, v176, s[58:59]
	v_cndmask_b32_e64 v23, v23, v177, s[60:61]
	v_cndmask_b32_e64 v24, v24, v178, s[62:63]
	v_cndmask_b32_e64 v25, v25, v179, s[40:41]
	v_sub_f32_e32 v22, v22, v180
	v_sub_f32_e32 v23, v23, v181
	v_sub_f32_e32 v24, v24, v182
	v_sub_f32_e32 v25, v25, v183
	v_mul_f32_e32 v176, 0xbfb8aa3b, v18
	v_mul_f32_e32 v177, 0xbfb8aa3b, v19
	v_mul_f32_e32 v178, 0xbfb8aa3b, v20
	v_mul_f32_e32 v179, 0xbfb8aa3b, v21
	v_exp_f32_e32 v176, v176
	v_exp_f32_e32 v177, v177
	v_exp_f32_e32 v178, v178
	v_exp_f32_e32 v179, v179
	v_add_f32_e32 v176, 1.0, v176
	v_add_f32_e32 v177, 1.0, v177
	v_add_f32_e32 v178, 1.0, v178
	v_add_f32_e32 v179, 1.0, v179
	v_rcp_f32_e32 v176, v176
	v_rcp_f32_e32 v177, v177
	v_rcp_f32_e32 v178, v178
	v_rcp_f32_e32 v179, v179
	v_fma_f32 v18, v176, v172, v184
	v_fma_f32 v19, v177, v173, v185
	v_fma_f32 v20, v178, v174, v186
	v_fma_f32 v21, v179, v175, v187
	v_cmp_gt_f32_e64 s[50:51], s14, v18
	v_cmp_gt_f32_e64 s[52:53], s14, v19
	v_cmp_gt_f32_e64 s[54:55], s14, v20
	v_cmp_gt_f32_e64 s[56:57], s14, v21
	v_cndmask_b32_e64 v180, 0, 32, s[50:51]
	v_cndmask_b32_e64 v181, 0, 32, s[52:53]
	v_cndmask_b32_e64 v182, 0, 32, s[54:55]
	v_cndmask_b32_e64 v183, 0, 32, s[56:57]
	v_ldexp_f32 v18, v18, v180
	v_ldexp_f32 v19, v19, v181
	v_ldexp_f32 v20, v20, v182
	v_ldexp_f32 v21, v21, v183
	v_log_f32_e32 v18, v18
	v_log_f32_e32 v19, v19
	v_log_f32_e32 v20, v20
	v_log_f32_e32 v21, v21
	v_cndmask_b32_e64 v180, 0, v213, s[50:51]
	v_cndmask_b32_e64 v181, 0, v213, s[52:53]
	v_cndmask_b32_e64 v182, 0, v213, s[54:55]
	v_cndmask_b32_e64 v183, 0, v213, s[56:57]
	v_mul_f32_e32 v176, 0x3f317217, v18
	v_mul_f32_e32 v177, 0x3f317217, v19
	v_mul_f32_e32 v178, 0x3f317217, v20
	v_mul_f32_e32 v179, 0x3f317217, v21
	v_fma_f32 v176, v18, s24, -v176
	v_fma_f32 v177, v19, s24, -v177
	v_fma_f32 v178, v20, s24, -v178
	v_fma_f32 v179, v21, s24, -v179
	v_fmac_f32_e32 v176, 0x3377d1cf, v18
	v_fmac_f32_e32 v177, 0x3377d1cf, v19
	v_fmac_f32_e32 v178, 0x3377d1cf, v20
	v_fmac_f32_e32 v179, 0x3377d1cf, v21
	v_fmac_f32_e32 v176, 0x3f317217, v18
	v_fmac_f32_e32 v177, 0x3f317217, v19
	v_fmac_f32_e32 v178, 0x3f317217, v20
	v_fmac_f32_e32 v179, 0x3f317217, v21
	v_cmp_lt_f32_e64 s[58:59], |v18|, s15
	v_cmp_lt_f32_e64 s[60:61], |v19|, s15
	v_cmp_lt_f32_e64 s[62:63], |v20|, s15
	v_cmp_lt_f32_e64 s[40:41], |v21|, s15
	v_cndmask_b32_e64 v18, v18, v176, s[58:59]
	v_cndmask_b32_e64 v19, v19, v177, s[60:61]
	v_cndmask_b32_e64 v20, v20, v178, s[62:63]
	v_cndmask_b32_e64 v21, v21, v179, s[40:41]
	v_sub_f32_e32 v18, v18, v180
	v_sub_f32_e32 v19, v19, v181
	v_sub_f32_e32 v20, v20, v182
	v_sub_f32_e32 v21, v21, v183
	v_cvt_pk_f16_f32 v22, v22, v23
	v_cvt_pk_f16_f32 v23, v24, v25
	v_cvt_pk_f16_f32 v24, v18, v19
	v_cvt_pk_f16_f32 v25, v20, v21
	s_nop 1
	v_permlane16_swap_b32_e32 v22, v24
	v_permlane16_swap_b32_e32 v23, v25
	global_store_dwordx4 v[132:133], v[22:25], off offset:64
	v_lshl_add_u64 v[132:133], v[132:133], 0, s[4:5]
	v_mul_f32_e32 v176, 0xbfb8aa3b, v14
	v_mul_f32_e32 v177, 0xbfb8aa3b, v15
	v_mul_f32_e32 v178, 0xbfb8aa3b, v16
	v_mul_f32_e32 v179, 0xbfb8aa3b, v17
	v_exp_f32_e32 v176, v176
	v_exp_f32_e32 v177, v177
	v_exp_f32_e32 v178, v178
	v_exp_f32_e32 v179, v179
	v_add_f32_e32 v176, 1.0, v176
	v_add_f32_e32 v177, 1.0, v177
	v_add_f32_e32 v178, 1.0, v178
	v_add_f32_e32 v179, 1.0, v179
	v_rcp_f32_e32 v176, v176
	v_rcp_f32_e32 v177, v177
	v_rcp_f32_e32 v178, v178
	v_rcp_f32_e32 v179, v179
	v_fma_f32 v14, v176, v156, v142
	v_fma_f32 v15, v177, v157, v143
	v_fma_f32 v16, v178, v158, v144
	v_fma_f32 v17, v179, v159, v145
	v_cmp_gt_f32_e64 s[50:51], s14, v14
	v_cmp_gt_f32_e64 s[52:53], s14, v15
	v_cmp_gt_f32_e64 s[54:55], s14, v16
	v_cmp_gt_f32_e64 s[56:57], s14, v17
	v_cndmask_b32_e64 v180, 0, 32, s[50:51]
	v_cndmask_b32_e64 v181, 0, 32, s[52:53]
	v_cndmask_b32_e64 v182, 0, 32, s[54:55]
	v_cndmask_b32_e64 v183, 0, 32, s[56:57]
	v_ldexp_f32 v14, v14, v180
	v_ldexp_f32 v15, v15, v181
	v_ldexp_f32 v16, v16, v182
	v_ldexp_f32 v17, v17, v183
	v_log_f32_e32 v14, v14
	v_log_f32_e32 v15, v15
	v_log_f32_e32 v16, v16
	v_log_f32_e32 v17, v17
	v_cndmask_b32_e64 v180, 0, v213, s[50:51]
	v_cndmask_b32_e64 v181, 0, v213, s[52:53]
	v_cndmask_b32_e64 v182, 0, v213, s[54:55]
	v_cndmask_b32_e64 v183, 0, v213, s[56:57]
	v_mul_f32_e32 v176, 0x3f317217, v14
	v_mul_f32_e32 v177, 0x3f317217, v15
	v_mul_f32_e32 v178, 0x3f317217, v16
	v_mul_f32_e32 v179, 0x3f317217, v17
	v_fma_f32 v176, v14, s24, -v176
	v_fma_f32 v177, v15, s24, -v177
	v_fma_f32 v178, v16, s24, -v178
	v_fma_f32 v179, v17, s24, -v179
	v_fmac_f32_e32 v176, 0x3377d1cf, v14
	v_fmac_f32_e32 v177, 0x3377d1cf, v15
	v_fmac_f32_e32 v178, 0x3377d1cf, v16
	v_fmac_f32_e32 v179, 0x3377d1cf, v17
	v_fmac_f32_e32 v176, 0x3f317217, v14
	v_fmac_f32_e32 v177, 0x3f317217, v15
	v_fmac_f32_e32 v178, 0x3f317217, v16
	v_fmac_f32_e32 v179, 0x3f317217, v17
	v_cmp_lt_f32_e64 s[58:59], |v14|, s15
	v_cmp_lt_f32_e64 s[60:61], |v15|, s15
	v_cmp_lt_f32_e64 s[62:63], |v16|, s15
	v_cmp_lt_f32_e64 s[40:41], |v17|, s15
	v_cndmask_b32_e64 v14, v14, v176, s[58:59]
	v_cndmask_b32_e64 v15, v15, v177, s[60:61]
	v_cndmask_b32_e64 v16, v16, v178, s[62:63]
	v_cndmask_b32_e64 v17, v17, v179, s[40:41]
	v_sub_f32_e32 v14, v14, v180
	v_sub_f32_e32 v15, v15, v181
	v_sub_f32_e32 v16, v16, v182
	v_sub_f32_e32 v17, v17, v183
	v_mul_f32_e32 v176, 0xbfb8aa3b, v10
	v_mul_f32_e32 v177, 0xbfb8aa3b, v11
	v_mul_f32_e32 v178, 0xbfb8aa3b, v12
	v_mul_f32_e32 v179, 0xbfb8aa3b, v13
	v_exp_f32_e32 v176, v176
	v_exp_f32_e32 v177, v177
	v_exp_f32_e32 v178, v178
	v_exp_f32_e32 v179, v179
	v_add_f32_e32 v176, 1.0, v176
	v_add_f32_e32 v177, 1.0, v177
	v_add_f32_e32 v178, 1.0, v178
	v_add_f32_e32 v179, 1.0, v179
	v_rcp_f32_e32 v176, v176
	v_rcp_f32_e32 v177, v177
	v_rcp_f32_e32 v178, v178
	v_rcp_f32_e32 v179, v179
	v_fma_f32 v10, v176, v164, v138
	v_fma_f32 v11, v177, v165, v139
	v_fma_f32 v12, v178, v166, v140
	v_fma_f32 v13, v179, v167, v141
	v_cmp_gt_f32_e64 s[50:51], s14, v10
	v_cmp_gt_f32_e64 s[52:53], s14, v11
	v_cmp_gt_f32_e64 s[54:55], s14, v12
	v_cmp_gt_f32_e64 s[56:57], s14, v13
	v_cndmask_b32_e64 v180, 0, 32, s[50:51]
	v_cndmask_b32_e64 v181, 0, 32, s[52:53]
	v_cndmask_b32_e64 v182, 0, 32, s[54:55]
	v_cndmask_b32_e64 v183, 0, 32, s[56:57]
	v_ldexp_f32 v10, v10, v180
	v_ldexp_f32 v11, v11, v181
	v_ldexp_f32 v12, v12, v182
	v_ldexp_f32 v13, v13, v183
	v_log_f32_e32 v10, v10
	v_log_f32_e32 v11, v11
	v_log_f32_e32 v12, v12
	v_log_f32_e32 v13, v13
	v_cndmask_b32_e64 v180, 0, v213, s[50:51]
	v_cndmask_b32_e64 v181, 0, v213, s[52:53]
	v_cndmask_b32_e64 v182, 0, v213, s[54:55]
	v_cndmask_b32_e64 v183, 0, v213, s[56:57]
	v_mul_f32_e32 v176, 0x3f317217, v10
	v_mul_f32_e32 v177, 0x3f317217, v11
	v_mul_f32_e32 v178, 0x3f317217, v12
	v_mul_f32_e32 v179, 0x3f317217, v13
	v_fma_f32 v176, v10, s24, -v176
	v_fma_f32 v177, v11, s24, -v177
	v_fma_f32 v178, v12, s24, -v178
	v_fma_f32 v179, v13, s24, -v179
	v_fmac_f32_e32 v176, 0x3377d1cf, v10
	v_fmac_f32_e32 v177, 0x3377d1cf, v11
	v_fmac_f32_e32 v178, 0x3377d1cf, v12
	v_fmac_f32_e32 v179, 0x3377d1cf, v13
	v_fmac_f32_e32 v176, 0x3f317217, v10
	v_fmac_f32_e32 v177, 0x3f317217, v11
	v_fmac_f32_e32 v178, 0x3f317217, v12
	v_fmac_f32_e32 v179, 0x3f317217, v13
	v_cmp_lt_f32_e64 s[58:59], |v10|, s15
	v_cmp_lt_f32_e64 s[60:61], |v11|, s15
	v_cmp_lt_f32_e64 s[62:63], |v12|, s15
	v_cmp_lt_f32_e64 s[40:41], |v13|, s15
	v_cndmask_b32_e64 v10, v10, v176, s[58:59]
	v_cndmask_b32_e64 v11, v11, v177, s[60:61]
	v_cndmask_b32_e64 v12, v12, v178, s[62:63]
	v_cndmask_b32_e64 v13, v13, v179, s[40:41]
	v_sub_f32_e32 v10, v10, v180
	v_sub_f32_e32 v11, v11, v181
	v_sub_f32_e32 v12, v12, v182
	v_sub_f32_e32 v13, v13, v183
	v_cvt_pk_f16_f32 v14, v14, v15
	v_cvt_pk_f16_f32 v15, v16, v17
	v_cvt_pk_f16_f32 v16, v10, v11
	v_cvt_pk_f16_f32 v17, v12, v13
	s_nop 1
	v_permlane16_swap_b32_e32 v14, v16
	v_permlane16_swap_b32_e32 v15, v17
	global_store_dwordx4 v[132:133], v[14:17], off
	v_mul_f32_e32 v176, 0xbfb8aa3b, v6
	v_mul_f32_e32 v177, 0xbfb8aa3b, v7
	v_mul_f32_e32 v178, 0xbfb8aa3b, v8
	v_mul_f32_e32 v179, 0xbfb8aa3b, v9
	v_exp_f32_e32 v176, v176
	v_exp_f32_e32 v177, v177
	v_exp_f32_e32 v178, v178
	v_exp_f32_e32 v179, v179
	v_add_f32_e32 v176, 1.0, v176
	v_add_f32_e32 v177, 1.0, v177
	v_add_f32_e32 v178, 1.0, v178
	v_add_f32_e32 v179, 1.0, v179
	v_rcp_f32_e32 v176, v176
	v_rcp_f32_e32 v177, v177
	v_rcp_f32_e32 v178, v178
	v_rcp_f32_e32 v179, v179
	v_fma_f32 v6, v176, v168, v134
	v_fma_f32 v7, v177, v169, v135
	v_fma_f32 v8, v178, v170, v136
	v_fma_f32 v9, v179, v171, v137
	v_cmp_gt_f32_e64 s[50:51], s14, v6
	v_cmp_gt_f32_e64 s[52:53], s14, v7
	v_cmp_gt_f32_e64 s[54:55], s14, v8
	v_cmp_gt_f32_e64 s[56:57], s14, v9
	v_cndmask_b32_e64 v180, 0, 32, s[50:51]
	v_cndmask_b32_e64 v181, 0, 32, s[52:53]
	v_cndmask_b32_e64 v182, 0, 32, s[54:55]
	v_cndmask_b32_e64 v183, 0, 32, s[56:57]
	v_ldexp_f32 v6, v6, v180
	v_ldexp_f32 v7, v7, v181
	v_ldexp_f32 v8, v8, v182
	v_ldexp_f32 v9, v9, v183
	v_log_f32_e32 v6, v6
	v_log_f32_e32 v7, v7
	v_log_f32_e32 v8, v8
	v_log_f32_e32 v9, v9
	v_cndmask_b32_e64 v180, 0, v213, s[50:51]
	v_cndmask_b32_e64 v181, 0, v213, s[52:53]
	v_cndmask_b32_e64 v182, 0, v213, s[54:55]
	v_cndmask_b32_e64 v183, 0, v213, s[56:57]
	v_mul_f32_e32 v176, 0x3f317217, v6
	v_mul_f32_e32 v177, 0x3f317217, v7
	v_mul_f32_e32 v178, 0x3f317217, v8
	v_mul_f32_e32 v179, 0x3f317217, v9
	v_fma_f32 v176, v6, s24, -v176
	v_fma_f32 v177, v7, s24, -v177
	v_fma_f32 v178, v8, s24, -v178
	v_fma_f32 v179, v9, s24, -v179
	v_fmac_f32_e32 v176, 0x3377d1cf, v6
	v_fmac_f32_e32 v177, 0x3377d1cf, v7
	v_fmac_f32_e32 v178, 0x3377d1cf, v8
	v_fmac_f32_e32 v179, 0x3377d1cf, v9
	v_fmac_f32_e32 v176, 0x3f317217, v6
	v_fmac_f32_e32 v177, 0x3f317217, v7
	v_fmac_f32_e32 v178, 0x3f317217, v8
	v_fmac_f32_e32 v179, 0x3f317217, v9
	v_cmp_lt_f32_e64 s[58:59], |v6|, s15
	v_cmp_lt_f32_e64 s[60:61], |v7|, s15
	v_cmp_lt_f32_e64 s[62:63], |v8|, s15
	v_cmp_lt_f32_e64 s[40:41], |v9|, s15
	v_cndmask_b32_e64 v6, v6, v176, s[58:59]
	v_cndmask_b32_e64 v7, v7, v177, s[60:61]
	v_cndmask_b32_e64 v8, v8, v178, s[62:63]
	v_cndmask_b32_e64 v9, v9, v179, s[40:41]
	v_sub_f32_e32 v6, v6, v180
	v_sub_f32_e32 v7, v7, v181
	v_sub_f32_e32 v8, v8, v182
	v_sub_f32_e32 v9, v9, v183
	v_mul_f32_e32 v176, 0xbfb8aa3b, v2
	v_mul_f32_e32 v177, 0xbfb8aa3b, v3
	v_mul_f32_e32 v178, 0xbfb8aa3b, v4
	v_mul_f32_e32 v179, 0xbfb8aa3b, v5
	v_exp_f32_e32 v176, v176
	v_exp_f32_e32 v177, v177
	v_exp_f32_e32 v178, v178
	v_exp_f32_e32 v179, v179
	v_add_f32_e32 v176, 1.0, v176
	v_add_f32_e32 v177, 1.0, v177
	v_add_f32_e32 v178, 1.0, v178
	v_add_f32_e32 v179, 1.0, v179
	v_rcp_f32_e32 v176, v176
	v_rcp_f32_e32 v177, v177
	v_rcp_f32_e32 v178, v178
	v_rcp_f32_e32 v179, v179
	v_fma_f32 v2, v176, v172, v184
	v_fma_f32 v3, v177, v173, v185
	v_fma_f32 v4, v178, v174, v186
	v_fma_f32 v5, v179, v175, v187
	v_cmp_gt_f32_e64 s[50:51], s14, v2
	v_cmp_gt_f32_e64 s[52:53], s14, v3
	v_cmp_gt_f32_e64 s[54:55], s14, v4
	v_cmp_gt_f32_e64 s[56:57], s14, v5
	v_cndmask_b32_e64 v180, 0, 32, s[50:51]
	v_cndmask_b32_e64 v181, 0, 32, s[52:53]
	v_cndmask_b32_e64 v182, 0, 32, s[54:55]
	v_cndmask_b32_e64 v183, 0, 32, s[56:57]
	v_ldexp_f32 v2, v2, v180
	v_ldexp_f32 v3, v3, v181
	v_ldexp_f32 v4, v4, v182
	v_ldexp_f32 v5, v5, v183
	v_log_f32_e32 v2, v2
	v_log_f32_e32 v3, v3
	v_log_f32_e32 v4, v4
	v_log_f32_e32 v5, v5
	v_cndmask_b32_e64 v180, 0, v213, s[50:51]
	v_cndmask_b32_e64 v181, 0, v213, s[52:53]
	v_cndmask_b32_e64 v182, 0, v213, s[54:55]
	v_cndmask_b32_e64 v183, 0, v213, s[56:57]
	v_mul_f32_e32 v176, 0x3f317217, v2
	v_mul_f32_e32 v177, 0x3f317217, v3
	v_mul_f32_e32 v178, 0x3f317217, v4
	v_mul_f32_e32 v179, 0x3f317217, v5
	v_fma_f32 v176, v2, s24, -v176
	v_fma_f32 v177, v3, s24, -v177
	v_fma_f32 v178, v4, s24, -v178
	v_fma_f32 v179, v5, s24, -v179
	v_fmac_f32_e32 v176, 0x3377d1cf, v2
	v_fmac_f32_e32 v177, 0x3377d1cf, v3
	v_fmac_f32_e32 v178, 0x3377d1cf, v4
	v_fmac_f32_e32 v179, 0x3377d1cf, v5
	v_fmac_f32_e32 v176, 0x3f317217, v2
	v_fmac_f32_e32 v177, 0x3f317217, v3
	v_fmac_f32_e32 v178, 0x3f317217, v4
	v_fmac_f32_e32 v179, 0x3f317217, v5
	v_cmp_lt_f32_e64 s[58:59], |v2|, s15
	v_cmp_lt_f32_e64 s[60:61], |v3|, s15
	v_cmp_lt_f32_e64 s[62:63], |v4|, s15
	v_cmp_lt_f32_e64 s[40:41], |v5|, s15
	v_cndmask_b32_e64 v2, v2, v176, s[58:59]
	v_cndmask_b32_e64 v3, v3, v177, s[60:61]
	v_cndmask_b32_e64 v4, v4, v178, s[62:63]
	v_cndmask_b32_e64 v5, v5, v179, s[40:41]
	v_sub_f32_e32 v2, v2, v180
	v_sub_f32_e32 v3, v3, v181
	v_sub_f32_e32 v4, v4, v182
	v_sub_f32_e32 v5, v5, v183
	v_cvt_pk_f16_f32 v6, v6, v7
	v_cvt_pk_f16_f32 v7, v8, v9
	v_cvt_pk_f16_f32 v8, v2, v3
	v_cvt_pk_f16_f32 v9, v4, v5
	s_nop 1
	v_permlane16_swap_b32_e32 v6, v8
	v_permlane16_swap_b32_e32 v7, v9
	global_store_dwordx4 v[132:133], v[6:9], off offset:64
	s_branch .LBB0_1040
.Lhg_part0:
	s_mov_b32 s14, 0x3db504f3
	v_readlane_b32 s48, v252, 26
	v_readlane_b32 s49, v252, 27
	s_nop 1
	v_lshl_add_u64 v[132:133], s[48:49], 0, v[150:151]
	v_mul_f32_e32 v176, 0xbfb8aa3b, v126
	v_mul_f32_e32 v177, 0xbfb8aa3b, v127
	v_mul_f32_e32 v178, 0xbfb8aa3b, v128
	v_mul_f32_e32 v179, 0xbfb8aa3b, v129
	v_exp_f32_e32 v176, v176
	v_exp_f32_e32 v177, v177
	v_exp_f32_e32 v178, v178
	v_exp_f32_e32 v179, v179
	v_add_f32_e32 v176, 1.0, v176
	v_add_f32_e32 v177, 1.0, v177
	v_add_f32_e32 v178, 1.0, v178
	v_add_f32_e32 v179, 1.0, v179
	v_rcp_f32_e32 v176, v176
	v_rcp_f32_e32 v177, v177
	v_rcp_f32_e32 v178, v178
	v_rcp_f32_e32 v179, v179
	v_mul_f32_e32 v126, v126, v176
	v_mul_f32_e32 v127, v127, v177
	v_mul_f32_e32 v128, v128, v178
	v_mul_f32_e32 v129, v129, v179
	v_mul_f32_e32 v126, s14, v126
	v_mul_f32_e32 v127, s14, v127
	v_mul_f32_e32 v128, s14, v128
	v_mul_f32_e32 v129, s14, v129
	v_mul_f32_e32 v176, 0xbfb8aa3b, v122
	v_mul_f32_e32 v177, 0xbfb8aa3b, v123
	v_mul_f32_e32 v178, 0xbfb8aa3b, v124
	v_mul_f32_e32 v179, 0xbfb8aa3b, v125
	v_exp_f32_e32 v176, v176
	v_exp_f32_e32 v177, v177
	v_exp_f32_e32 v178, v178
	v_exp_f32_e32 v179, v179
	v_add_f32_e32 v176, 1.0, v176
	v_add_f32_e32 v177, 1.0, v177
	v_add_f32_e32 v178, 1.0, v178
	v_add_f32_e32 v179, 1.0, v179
	v_rcp_f32_e32 v176, v176
	v_rcp_f32_e32 v177, v177
	v_rcp_f32_e32 v178, v178
	v_rcp_f32_e32 v179, v179
	v_mul_f32_e32 v122, v122, v176
	v_mul_f32_e32 v123, v123, v177
	v_mul_f32_e32 v124, v124, v178
	v_mul_f32_e32 v125, v125, v179
	v_mul_f32_e32 v122, s14, v122
	v_mul_f32_e32 v123, s14, v123
	v_mul_f32_e32 v124, s14, v124
	v_mul_f32_e32 v125, s14, v125
	v_cvt_pk_bf16_f32 v126, v126, v127
	v_cvt_pk_bf16_f32 v127, v128, v129
	v_cvt_pk_bf16_f32 v128, v122, v123
	v_cvt_pk_bf16_f32 v129, v124, v125
	s_nop 1
	v_permlane16_swap_b32_e32 v126, v128
	v_permlane16_swap_b32_e32 v127, v129
	global_store_dwordx4 v[132:133], v[126:129], off
	v_mul_f32_e32 v176, 0xbfb8aa3b, v118
	v_mul_f32_e32 v177, 0xbfb8aa3b, v119
	v_mul_f32_e32 v178, 0xbfb8aa3b, v120
	v_mul_f32_e32 v179, 0xbfb8aa3b, v121
	v_exp_f32_e32 v176, v176
	v_exp_f32_e32 v177, v177
	v_exp_f32_e32 v178, v178
	v_exp_f32_e32 v179, v179
	v_add_f32_e32 v176, 1.0, v176
	v_add_f32_e32 v177, 1.0, v177
	v_add_f32_e32 v178, 1.0, v178
	v_add_f32_e32 v179, 1.0, v179
	v_rcp_f32_e32 v176, v176
	v_rcp_f32_e32 v177, v177
	v_rcp_f32_e32 v178, v178
	v_rcp_f32_e32 v179, v179
	v_mul_f32_e32 v118, v118, v176
	v_mul_f32_e32 v119, v119, v177
	v_mul_f32_e32 v120, v120, v178
	v_mul_f32_e32 v121, v121, v179
	v_mul_f32_e32 v118, s14, v118
	v_mul_f32_e32 v119, s14, v119
	v_mul_f32_e32 v120, s14, v120
	v_mul_f32_e32 v121, s14, v121
	v_mul_f32_e32 v176, 0xbfb8aa3b, v114
	v_mul_f32_e32 v177, 0xbfb8aa3b, v115
	v_mul_f32_e32 v178, 0xbfb8aa3b, v116
	v_mul_f32_e32 v179, 0xbfb8aa3b, v117
	v_exp_f32_e32 v176, v176
	v_exp_f32_e32 v177, v177
	v_exp_f32_e32 v178, v178
	v_exp_f32_e32 v179, v179
	v_add_f32_e32 v176, 1.0, v176
	v_add_f32_e32 v177, 1.0, v177
	v_add_f32_e32 v178, 1.0, v178
	v_add_f32_e32 v179, 1.0, v179
	v_rcp_f32_e32 v176, v176
	v_rcp_f32_e32 v177, v177
	v_rcp_f32_e32 v178, v178
	v_rcp_f32_e32 v179, v179
	v_mul_f32_e32 v114, v114, v176
	v_mul_f32_e32 v115, v115, v177
	v_mul_f32_e32 v116, v116, v178
	v_mul_f32_e32 v117, v117, v179
	v_mul_f32_e32 v114, s14, v114
	v_mul_f32_e32 v115, s14, v115
	v_mul_f32_e32 v116, s14, v116
	v_mul_f32_e32 v117, s14, v117
	v_cvt_pk_bf16_f32 v118, v118, v119
	v_cvt_pk_bf16_f32 v119, v120, v121
	v_cvt_pk_bf16_f32 v120, v114, v115
	v_cvt_pk_bf16_f32 v121, v116, v117
	s_nop 1
	v_permlane16_swap_b32_e32 v118, v120
	v_permlane16_swap_b32_e32 v119, v121
	global_store_dwordx4 v[132:133], v[118:121], off offset:64
	v_lshl_add_u64 v[132:133], v[132:133], 0, s[4:5]
	v_mul_f32_e32 v176, 0xbfb8aa3b, v110
	v_mul_f32_e32 v177, 0xbfb8aa3b, v111
	v_mul_f32_e32 v178, 0xbfb8aa3b, v112
	v_mul_f32_e32 v179, 0xbfb8aa3b, v113
	v_exp_f32_e32 v176, v176
	v_exp_f32_e32 v177, v177
	v_exp_f32_e32 v178, v178
	v_exp_f32_e32 v179, v179
	v_add_f32_e32 v176, 1.0, v176
	v_add_f32_e32 v177, 1.0, v177
	v_add_f32_e32 v178, 1.0, v178
	v_add_f32_e32 v179, 1.0, v179
	v_rcp_f32_e32 v176, v176
	v_rcp_f32_e32 v177, v177
	v_rcp_f32_e32 v178, v178
	v_rcp_f32_e32 v179, v179
	v_mul_f32_e32 v110, v110, v176
	v_mul_f32_e32 v111, v111, v177
	v_mul_f32_e32 v112, v112, v178
	v_mul_f32_e32 v113, v113, v179
	v_mul_f32_e32 v110, s14, v110
	v_mul_f32_e32 v111, s14, v111
	v_mul_f32_e32 v112, s14, v112
	v_mul_f32_e32 v113, s14, v113
	v_mul_f32_e32 v176, 0xbfb8aa3b, v106
	v_mul_f32_e32 v177, 0xbfb8aa3b, v107
	v_mul_f32_e32 v178, 0xbfb8aa3b, v108
	v_mul_f32_e32 v179, 0xbfb8aa3b, v109
	v_exp_f32_e32 v176, v176
	v_exp_f32_e32 v177, v177
	v_exp_f32_e32 v178, v178
	v_exp_f32_e32 v179, v179
	v_add_f32_e32 v176, 1.0, v176
	v_add_f32_e32 v177, 1.0, v177
	v_add_f32_e32 v178, 1.0, v178
	v_add_f32_e32 v179, 1.0, v179
	v_rcp_f32_e32 v176, v176
	v_rcp_f32_e32 v177, v177
	v_rcp_f32_e32 v178, v178
	v_rcp_f32_e32 v179, v179
	v_mul_f32_e32 v106, v106, v176
	v_mul_f32_e32 v107, v107, v177
	v_mul_f32_e32 v108, v108, v178
	v_mul_f32_e32 v109, v109, v179
	v_mul_f32_e32 v106, s14, v106
	v_mul_f32_e32 v107, s14, v107
	v_mul_f32_e32 v108, s14, v108
	v_mul_f32_e32 v109, s14, v109
	v_cvt_pk_bf16_f32 v110, v110, v111
	v_cvt_pk_bf16_f32 v111, v112, v113
	v_cvt_pk_bf16_f32 v112, v106, v107
	v_cvt_pk_bf16_f32 v113, v108, v109
	s_nop 1
	v_permlane16_swap_b32_e32 v110, v112
	v_permlane16_swap_b32_e32 v111, v113
	global_store_dwordx4 v[132:133], v[110:113], off
	v_mul_f32_e32 v176, 0xbfb8aa3b, v102
	v_mul_f32_e32 v177, 0xbfb8aa3b, v103
	v_mul_f32_e32 v178, 0xbfb8aa3b, v104
	v_mul_f32_e32 v179, 0xbfb8aa3b, v105
	v_exp_f32_e32 v176, v176
	v_exp_f32_e32 v177, v177
	v_exp_f32_e32 v178, v178
	v_exp_f32_e32 v179, v179
	v_add_f32_e32 v176, 1.0, v176
	v_add_f32_e32 v177, 1.0, v177
	v_add_f32_e32 v178, 1.0, v178
	v_add_f32_e32 v179, 1.0, v179
	v_rcp_f32_e32 v176, v176
	v_rcp_f32_e32 v177, v177
	v_rcp_f32_e32 v178, v178
	v_rcp_f32_e32 v179, v179
	v_mul_f32_e32 v102, v102, v176
	v_mul_f32_e32 v103, v103, v177
	v_mul_f32_e32 v104, v104, v178
	v_mul_f32_e32 v105, v105, v179
	v_mul_f32_e32 v102, s14, v102
	v_mul_f32_e32 v103, s14, v103
	v_mul_f32_e32 v104, s14, v104
	v_mul_f32_e32 v105, s14, v105
	v_mul_f32_e32 v176, 0xbfb8aa3b, v98
	v_mul_f32_e32 v177, 0xbfb8aa3b, v99
	v_mul_f32_e32 v178, 0xbfb8aa3b, v100
	v_mul_f32_e32 v179, 0xbfb8aa3b, v101
	v_exp_f32_e32 v176, v176
	v_exp_f32_e32 v177, v177
	v_exp_f32_e32 v178, v178
	v_exp_f32_e32 v179, v179
	v_add_f32_e32 v176, 1.0, v176
	v_add_f32_e32 v177, 1.0, v177
	v_add_f32_e32 v178, 1.0, v178
	v_add_f32_e32 v179, 1.0, v179
	v_rcp_f32_e32 v176, v176
	v_rcp_f32_e32 v177, v177
	v_rcp_f32_e32 v178, v178
	v_rcp_f32_e32 v179, v179
	v_mul_f32_e32 v98, v98, v176
	v_mul_f32_e32 v99, v99, v177
	v_mul_f32_e32 v100, v100, v178
	v_mul_f32_e32 v101, v101, v179
	v_mul_f32_e32 v98, s14, v98
	v_mul_f32_e32 v99, s14, v99
	v_mul_f32_e32 v100, s14, v100
	v_mul_f32_e32 v101, s14, v101
	v_cvt_pk_bf16_f32 v102, v102, v103
	v_cvt_pk_bf16_f32 v103, v104, v105
	v_cvt_pk_bf16_f32 v104, v98, v99
	v_cvt_pk_bf16_f32 v105, v100, v101
	s_nop 1
	v_permlane16_swap_b32_e32 v102, v104
	v_permlane16_swap_b32_e32 v103, v105
	global_store_dwordx4 v[132:133], v[102:105], off offset:64
	v_lshl_add_u64 v[132:133], v[132:133], 0, s[4:5]
	v_mul_f32_e32 v176, 0xbfb8aa3b, v94
	v_mul_f32_e32 v177, 0xbfb8aa3b, v95
	v_mul_f32_e32 v178, 0xbfb8aa3b, v96
	v_mul_f32_e32 v179, 0xbfb8aa3b, v97
	v_exp_f32_e32 v176, v176
	v_exp_f32_e32 v177, v177
	v_exp_f32_e32 v178, v178
	v_exp_f32_e32 v179, v179
	v_add_f32_e32 v176, 1.0, v176
	v_add_f32_e32 v177, 1.0, v177
	v_add_f32_e32 v178, 1.0, v178
	v_add_f32_e32 v179, 1.0, v179
	v_rcp_f32_e32 v176, v176
	v_rcp_f32_e32 v177, v177
	v_rcp_f32_e32 v178, v178
	v_rcp_f32_e32 v179, v179
	v_mul_f32_e32 v94, v94, v176
	v_mul_f32_e32 v95, v95, v177
	v_mul_f32_e32 v96, v96, v178
	v_mul_f32_e32 v97, v97, v179
	v_mul_f32_e32 v94, s14, v94
	v_mul_f32_e32 v95, s14, v95
	v_mul_f32_e32 v96, s14, v96
	v_mul_f32_e32 v97, s14, v97
	v_mul_f32_e32 v176, 0xbfb8aa3b, v90
	v_mul_f32_e32 v177, 0xbfb8aa3b, v91
	v_mul_f32_e32 v178, 0xbfb8aa3b, v92
	v_mul_f32_e32 v179, 0xbfb8aa3b, v93
	v_exp_f32_e32 v176, v176
	v_exp_f32_e32 v177, v177
	v_exp_f32_e32 v178, v178
	v_exp_f32_e32 v179, v179
	v_add_f32_e32 v176, 1.0, v176
	v_add_f32_e32 v177, 1.0, v177
	v_add_f32_e32 v178, 1.0, v178
	v_add_f32_e32 v179, 1.0, v179
	v_rcp_f32_e32 v176, v176
	v_rcp_f32_e32 v177, v177
	v_rcp_f32_e32 v178, v178
	v_rcp_f32_e32 v179, v179
	v_mul_f32_e32 v90, v90, v176
	v_mul_f32_e32 v91, v91, v177
	v_mul_f32_e32 v92, v92, v178
	v_mul_f32_e32 v93, v93, v179
	v_mul_f32_e32 v90, s14, v90
	v_mul_f32_e32 v91, s14, v91
	v_mul_f32_e32 v92, s14, v92
	v_mul_f32_e32 v93, s14, v93
	v_cvt_pk_bf16_f32 v94, v94, v95
	v_cvt_pk_bf16_f32 v95, v96, v97
	v_cvt_pk_bf16_f32 v96, v90, v91
	v_cvt_pk_bf16_f32 v97, v92, v93
	s_nop 1
	v_permlane16_swap_b32_e32 v94, v96
	v_permlane16_swap_b32_e32 v95, v97
	global_store_dwordx4 v[132:133], v[94:97], off
	v_mul_f32_e32 v176, 0xbfb8aa3b, v86
	v_mul_f32_e32 v177, 0xbfb8aa3b, v87
	v_mul_f32_e32 v178, 0xbfb8aa3b, v88
	v_mul_f32_e32 v179, 0xbfb8aa3b, v89
	v_exp_f32_e32 v176, v176
	v_exp_f32_e32 v177, v177
	v_exp_f32_e32 v178, v178
	v_exp_f32_e32 v179, v179
	v_add_f32_e32 v176, 1.0, v176
	v_add_f32_e32 v177, 1.0, v177
	v_add_f32_e32 v178, 1.0, v178
	v_add_f32_e32 v179, 1.0, v179
	v_rcp_f32_e32 v176, v176
	v_rcp_f32_e32 v177, v177
	v_rcp_f32_e32 v178, v178
	v_rcp_f32_e32 v179, v179
	v_mul_f32_e32 v86, v86, v176
	v_mul_f32_e32 v87, v87, v177
	v_mul_f32_e32 v88, v88, v178
	v_mul_f32_e32 v89, v89, v179
	v_mul_f32_e32 v86, s14, v86
	v_mul_f32_e32 v87, s14, v87
	v_mul_f32_e32 v88, s14, v88
	v_mul_f32_e32 v89, s14, v89
	v_mul_f32_e32 v176, 0xbfb8aa3b, v82
	v_mul_f32_e32 v177, 0xbfb8aa3b, v83
	v_mul_f32_e32 v178, 0xbfb8aa3b, v84
	v_mul_f32_e32 v179, 0xbfb8aa3b, v85
	v_exp_f32_e32 v176, v176
	v_exp_f32_e32 v177, v177
	v_exp_f32_e32 v178, v178
	v_exp_f32_e32 v179, v179
	v_add_f32_e32 v176, 1.0, v176
	v_add_f32_e32 v177, 1.0, v177
	v_add_f32_e32 v178, 1.0, v178
	v_add_f32_e32 v179, 1.0, v179
	v_rcp_f32_e32 v176, v176
	v_rcp_f32_e32 v177, v177
	v_rcp_f32_e32 v178, v178
	v_rcp_f32_e32 v179, v179
	v_mul_f32_e32 v82, v82, v176
	v_mul_f32_e32 v83, v83, v177
	v_mul_f32_e32 v84, v84, v178
	v_mul_f32_e32 v85, v85, v179
	v_mul_f32_e32 v82, s14, v82
	v_mul_f32_e32 v83, s14, v83
	v_mul_f32_e32 v84, s14, v84
	v_mul_f32_e32 v85, s14, v85
	v_cvt_pk_bf16_f32 v86, v86, v87
	v_cvt_pk_bf16_f32 v87, v88, v89
	v_cvt_pk_bf16_f32 v88, v82, v83
	v_cvt_pk_bf16_f32 v89, v84, v85
	s_nop 1
	v_permlane16_swap_b32_e32 v86, v88
	v_permlane16_swap_b32_e32 v87, v89
	global_store_dwordx4 v[132:133], v[86:89], off offset:64
	v_lshl_add_u64 v[132:133], v[132:133], 0, s[4:5]
	v_mul_f32_e32 v176, 0xbfb8aa3b, v78
	v_mul_f32_e32 v177, 0xbfb8aa3b, v79
	v_mul_f32_e32 v178, 0xbfb8aa3b, v80
	v_mul_f32_e32 v179, 0xbfb8aa3b, v81
	v_exp_f32_e32 v176, v176
	v_exp_f32_e32 v177, v177
	v_exp_f32_e32 v178, v178
	v_exp_f32_e32 v179, v179
	v_add_f32_e32 v176, 1.0, v176
	v_add_f32_e32 v177, 1.0, v177
	v_add_f32_e32 v178, 1.0, v178
	v_add_f32_e32 v179, 1.0, v179
	v_rcp_f32_e32 v176, v176
	v_rcp_f32_e32 v177, v177
	v_rcp_f32_e32 v178, v178
	v_rcp_f32_e32 v179, v179
	v_mul_f32_e32 v78, v78, v176
	v_mul_f32_e32 v79, v79, v177
	v_mul_f32_e32 v80, v80, v178
	v_mul_f32_e32 v81, v81, v179
	v_mul_f32_e32 v78, s14, v78
	v_mul_f32_e32 v79, s14, v79
	v_mul_f32_e32 v80, s14, v80
	v_mul_f32_e32 v81, s14, v81
	v_mul_f32_e32 v176, 0xbfb8aa3b, v74
	v_mul_f32_e32 v177, 0xbfb8aa3b, v75
	v_mul_f32_e32 v178, 0xbfb8aa3b, v76
	v_mul_f32_e32 v179, 0xbfb8aa3b, v77
	v_exp_f32_e32 v176, v176
	v_exp_f32_e32 v177, v177
	v_exp_f32_e32 v178, v178
	v_exp_f32_e32 v179, v179
	v_add_f32_e32 v176, 1.0, v176
	v_add_f32_e32 v177, 1.0, v177
	v_add_f32_e32 v178, 1.0, v178
	v_add_f32_e32 v179, 1.0, v179
	v_rcp_f32_e32 v176, v176
	v_rcp_f32_e32 v177, v177
	v_rcp_f32_e32 v178, v178
	v_rcp_f32_e32 v179, v179
	v_mul_f32_e32 v74, v74, v176
	v_mul_f32_e32 v75, v75, v177
	v_mul_f32_e32 v76, v76, v178
	v_mul_f32_e32 v77, v77, v179
	v_mul_f32_e32 v74, s14, v74
	v_mul_f32_e32 v75, s14, v75
	v_mul_f32_e32 v76, s14, v76
	v_mul_f32_e32 v77, s14, v77
	v_cvt_pk_bf16_f32 v78, v78, v79
	v_cvt_pk_bf16_f32 v79, v80, v81
	v_cvt_pk_bf16_f32 v80, v74, v75
	v_cvt_pk_bf16_f32 v81, v76, v77
	s_nop 1
	v_permlane16_swap_b32_e32 v78, v80
	v_permlane16_swap_b32_e32 v79, v81
	global_store_dwordx4 v[132:133], v[78:81], off
	v_mul_f32_e32 v176, 0xbfb8aa3b, v70
	v_mul_f32_e32 v177, 0xbfb8aa3b, v71
	v_mul_f32_e32 v178, 0xbfb8aa3b, v72
	v_mul_f32_e32 v179, 0xbfb8aa3b, v73
	v_exp_f32_e32 v176, v176
	v_exp_f32_e32 v177, v177
	v_exp_f32_e32 v178, v178
	v_exp_f32_e32 v179, v179
	v_add_f32_e32 v176, 1.0, v176
	v_add_f32_e32 v177, 1.0, v177
	v_add_f32_e32 v178, 1.0, v178
	v_add_f32_e32 v179, 1.0, v179
	v_rcp_f32_e32 v176, v176
	v_rcp_f32_e32 v177, v177
	v_rcp_f32_e32 v178, v178
	v_rcp_f32_e32 v179, v179
	v_mul_f32_e32 v70, v70, v176
	v_mul_f32_e32 v71, v71, v177
	v_mul_f32_e32 v72, v72, v178
	v_mul_f32_e32 v73, v73, v179
	v_mul_f32_e32 v70, s14, v70
	v_mul_f32_e32 v71, s14, v71
	v_mul_f32_e32 v72, s14, v72
	v_mul_f32_e32 v73, s14, v73
	v_mul_f32_e32 v176, 0xbfb8aa3b, v66
	v_mul_f32_e32 v177, 0xbfb8aa3b, v67
	v_mul_f32_e32 v178, 0xbfb8aa3b, v68
	v_mul_f32_e32 v179, 0xbfb8aa3b, v69
	v_exp_f32_e32 v176, v176
	v_exp_f32_e32 v177, v177
	v_exp_f32_e32 v178, v178
	v_exp_f32_e32 v179, v179
	v_add_f32_e32 v176, 1.0, v176
	v_add_f32_e32 v177, 1.0, v177
	v_add_f32_e32 v178, 1.0, v178
	v_add_f32_e32 v179, 1.0, v179
	v_rcp_f32_e32 v176, v176
	v_rcp_f32_e32 v177, v177
	v_rcp_f32_e32 v178, v178
	v_rcp_f32_e32 v179, v179
	v_mul_f32_e32 v66, v66, v176
	v_mul_f32_e32 v67, v67, v177
	v_mul_f32_e32 v68, v68, v178
	v_mul_f32_e32 v69, v69, v179
	v_mul_f32_e32 v66, s14, v66
	v_mul_f32_e32 v67, s14, v67
	v_mul_f32_e32 v68, s14, v68
	v_mul_f32_e32 v69, s14, v69
	v_cvt_pk_bf16_f32 v70, v70, v71
	v_cvt_pk_bf16_f32 v71, v72, v73
	v_cvt_pk_bf16_f32 v72, v66, v67
	v_cvt_pk_bf16_f32 v73, v68, v69
	s_nop 1
	v_permlane16_swap_b32_e32 v70, v72
	v_permlane16_swap_b32_e32 v71, v73
	global_store_dwordx4 v[132:133], v[70:73], off offset:64
	v_lshl_add_u64 v[132:133], v[132:133], 0, s[4:5]
	v_mul_f32_e32 v176, 0xbfb8aa3b, v62
	v_mul_f32_e32 v177, 0xbfb8aa3b, v63
	v_mul_f32_e32 v178, 0xbfb8aa3b, v64
	v_mul_f32_e32 v179, 0xbfb8aa3b, v65
	v_exp_f32_e32 v176, v176
	v_exp_f32_e32 v177, v177
	v_exp_f32_e32 v178, v178
	v_exp_f32_e32 v179, v179
	v_add_f32_e32 v176, 1.0, v176
	v_add_f32_e32 v177, 1.0, v177
	v_add_f32_e32 v178, 1.0, v178
	v_add_f32_e32 v179, 1.0, v179
	v_rcp_f32_e32 v176, v176
	v_rcp_f32_e32 v177, v177
	v_rcp_f32_e32 v178, v178
	v_rcp_f32_e32 v179, v179
	v_mul_f32_e32 v62, v62, v176
	v_mul_f32_e32 v63, v63, v177
	v_mul_f32_e32 v64, v64, v178
	v_mul_f32_e32 v65, v65, v179
	v_mul_f32_e32 v62, s14, v62
	v_mul_f32_e32 v63, s14, v63
	v_mul_f32_e32 v64, s14, v64
	v_mul_f32_e32 v65, s14, v65
	v_mul_f32_e32 v176, 0xbfb8aa3b, v58
	v_mul_f32_e32 v177, 0xbfb8aa3b, v59
	v_mul_f32_e32 v178, 0xbfb8aa3b, v60
	v_mul_f32_e32 v179, 0xbfb8aa3b, v61
	v_exp_f32_e32 v176, v176
	v_exp_f32_e32 v177, v177
	v_exp_f32_e32 v178, v178
	v_exp_f32_e32 v179, v179
	v_add_f32_e32 v176, 1.0, v176
	v_add_f32_e32 v177, 1.0, v177
	v_add_f32_e32 v178, 1.0, v178
	v_add_f32_e32 v179, 1.0, v179
	v_rcp_f32_e32 v176, v176
	v_rcp_f32_e32 v177, v177
	v_rcp_f32_e32 v178, v178
	v_rcp_f32_e32 v179, v179
	v_mul_f32_e32 v58, v58, v176
	v_mul_f32_e32 v59, v59, v177
	v_mul_f32_e32 v60, v60, v178
	v_mul_f32_e32 v61, v61, v179
	v_mul_f32_e32 v58, s14, v58
	v_mul_f32_e32 v59, s14, v59
	v_mul_f32_e32 v60, s14, v60
	v_mul_f32_e32 v61, s14, v61
	v_cvt_pk_bf16_f32 v62, v62, v63
	v_cvt_pk_bf16_f32 v63, v64, v65
	v_cvt_pk_bf16_f32 v64, v58, v59
	v_cvt_pk_bf16_f32 v65, v60, v61
	s_nop 1
	v_permlane16_swap_b32_e32 v62, v64
	v_permlane16_swap_b32_e32 v63, v65
	global_store_dwordx4 v[132:133], v[62:65], off
	v_mul_f32_e32 v176, 0xbfb8aa3b, v54
	v_mul_f32_e32 v177, 0xbfb8aa3b, v55
	v_mul_f32_e32 v178, 0xbfb8aa3b, v56
	v_mul_f32_e32 v179, 0xbfb8aa3b, v57
	v_exp_f32_e32 v176, v176
	v_exp_f32_e32 v177, v177
	v_exp_f32_e32 v178, v178
	v_exp_f32_e32 v179, v179
	v_add_f32_e32 v176, 1.0, v176
	v_add_f32_e32 v177, 1.0, v177
	v_add_f32_e32 v178, 1.0, v178
	v_add_f32_e32 v179, 1.0, v179
	v_rcp_f32_e32 v176, v176
	v_rcp_f32_e32 v177, v177
	v_rcp_f32_e32 v178, v178
	v_rcp_f32_e32 v179, v179
	v_mul_f32_e32 v54, v54, v176
	v_mul_f32_e32 v55, v55, v177
	v_mul_f32_e32 v56, v56, v178
	v_mul_f32_e32 v57, v57, v179
	v_mul_f32_e32 v54, s14, v54
	v_mul_f32_e32 v55, s14, v55
	v_mul_f32_e32 v56, s14, v56
	v_mul_f32_e32 v57, s14, v57
	v_mul_f32_e32 v176, 0xbfb8aa3b, v50
	v_mul_f32_e32 v177, 0xbfb8aa3b, v51
	v_mul_f32_e32 v178, 0xbfb8aa3b, v52
	v_mul_f32_e32 v179, 0xbfb8aa3b, v53
	v_exp_f32_e32 v176, v176
	v_exp_f32_e32 v177, v177
	v_exp_f32_e32 v178, v178
	v_exp_f32_e32 v179, v179
	v_add_f32_e32 v176, 1.0, v176
	v_add_f32_e32 v177, 1.0, v177
	v_add_f32_e32 v178, 1.0, v178
	v_add_f32_e32 v179, 1.0, v179
	v_rcp_f32_e32 v176, v176
	v_rcp_f32_e32 v177, v177
	v_rcp_f32_e32 v178, v178
	v_rcp_f32_e32 v179, v179
	v_mul_f32_e32 v50, v50, v176
	v_mul_f32_e32 v51, v51, v177
	v_mul_f32_e32 v52, v52, v178
	v_mul_f32_e32 v53, v53, v179
	v_mul_f32_e32 v50, s14, v50
	v_mul_f32_e32 v51, s14, v51
	v_mul_f32_e32 v52, s14, v52
	v_mul_f32_e32 v53, s14, v53
	v_cvt_pk_bf16_f32 v54, v54, v55
	v_cvt_pk_bf16_f32 v55, v56, v57
	v_cvt_pk_bf16_f32 v56, v50, v51
	v_cvt_pk_bf16_f32 v57, v52, v53
	s_nop 1
	v_permlane16_swap_b32_e32 v54, v56
	v_permlane16_swap_b32_e32 v55, v57
	global_store_dwordx4 v[132:133], v[54:57], off offset:64
	v_lshl_add_u64 v[132:133], v[132:133], 0, s[4:5]
	v_mul_f32_e32 v176, 0xbfb8aa3b, v46
	v_mul_f32_e32 v177, 0xbfb8aa3b, v47
	v_mul_f32_e32 v178, 0xbfb8aa3b, v48
	v_mul_f32_e32 v179, 0xbfb8aa3b, v49
	v_exp_f32_e32 v176, v176
	v_exp_f32_e32 v177, v177
	v_exp_f32_e32 v178, v178
	v_exp_f32_e32 v179, v179
	v_add_f32_e32 v176, 1.0, v176
	v_add_f32_e32 v177, 1.0, v177
	v_add_f32_e32 v178, 1.0, v178
	v_add_f32_e32 v179, 1.0, v179
	v_rcp_f32_e32 v176, v176
	v_rcp_f32_e32 v177, v177
	v_rcp_f32_e32 v178, v178
	v_rcp_f32_e32 v179, v179
	v_mul_f32_e32 v46, v46, v176
	v_mul_f32_e32 v47, v47, v177
	v_mul_f32_e32 v48, v48, v178
	v_mul_f32_e32 v49, v49, v179
	v_mul_f32_e32 v46, s14, v46
	v_mul_f32_e32 v47, s14, v47
	v_mul_f32_e32 v48, s14, v48
	v_mul_f32_e32 v49, s14, v49
	v_mul_f32_e32 v176, 0xbfb8aa3b, v42
	v_mul_f32_e32 v177, 0xbfb8aa3b, v43
	v_mul_f32_e32 v178, 0xbfb8aa3b, v44
	v_mul_f32_e32 v179, 0xbfb8aa3b, v45
	v_exp_f32_e32 v176, v176
	v_exp_f32_e32 v177, v177
	v_exp_f32_e32 v178, v178
	v_exp_f32_e32 v179, v179
	v_add_f32_e32 v176, 1.0, v176
	v_add_f32_e32 v177, 1.0, v177
	v_add_f32_e32 v178, 1.0, v178
	v_add_f32_e32 v179, 1.0, v179
	v_rcp_f32_e32 v176, v176
	v_rcp_f32_e32 v177, v177
	v_rcp_f32_e32 v178, v178
	v_rcp_f32_e32 v179, v179
	v_mul_f32_e32 v42, v42, v176
	v_mul_f32_e32 v43, v43, v177
	v_mul_f32_e32 v44, v44, v178
	v_mul_f32_e32 v45, v45, v179
	v_mul_f32_e32 v42, s14, v42
	v_mul_f32_e32 v43, s14, v43
	v_mul_f32_e32 v44, s14, v44
	v_mul_f32_e32 v45, s14, v45
	v_cvt_pk_bf16_f32 v46, v46, v47
	v_cvt_pk_bf16_f32 v47, v48, v49
	v_cvt_pk_bf16_f32 v48, v42, v43
	v_cvt_pk_bf16_f32 v49, v44, v45
	s_nop 1
	v_permlane16_swap_b32_e32 v46, v48
	v_permlane16_swap_b32_e32 v47, v49
	global_store_dwordx4 v[132:133], v[46:49], off
	v_mul_f32_e32 v176, 0xbfb8aa3b, v34
	v_mul_f32_e32 v177, 0xbfb8aa3b, v35
	v_mul_f32_e32 v178, 0xbfb8aa3b, v36
	v_mul_f32_e32 v179, 0xbfb8aa3b, v37
	v_exp_f32_e32 v176, v176
	v_exp_f32_e32 v177, v177
	v_exp_f32_e32 v178, v178
	v_exp_f32_e32 v179, v179
	v_add_f32_e32 v176, 1.0, v176
	v_add_f32_e32 v177, 1.0, v177
	v_add_f32_e32 v178, 1.0, v178
	v_add_f32_e32 v179, 1.0, v179
	v_rcp_f32_e32 v176, v176
	v_rcp_f32_e32 v177, v177
	v_rcp_f32_e32 v178, v178
	v_rcp_f32_e32 v179, v179
	v_mul_f32_e32 v34, v34, v176
	v_mul_f32_e32 v35, v35, v177
	v_mul_f32_e32 v36, v36, v178
	v_mul_f32_e32 v37, v37, v179
	v_mul_f32_e32 v34, s14, v34
	v_mul_f32_e32 v35, s14, v35
	v_mul_f32_e32 v36, s14, v36
	v_mul_f32_e32 v37, s14, v37
	v_mul_f32_e32 v176, 0xbfb8aa3b, v30
	v_mul_f32_e32 v177, 0xbfb8aa3b, v31
	v_mul_f32_e32 v178, 0xbfb8aa3b, v32
	v_mul_f32_e32 v179, 0xbfb8aa3b, v33
	v_exp_f32_e32 v176, v176
	v_exp_f32_e32 v177, v177
	v_exp_f32_e32 v178, v178
	v_exp_f32_e32 v179, v179
	v_add_f32_e32 v176, 1.0, v176
	v_add_f32_e32 v177, 1.0, v177
	v_add_f32_e32 v178, 1.0, v178
	v_add_f32_e32 v179, 1.0, v179
	v_rcp_f32_e32 v176, v176
	v_rcp_f32_e32 v177, v177
	v_rcp_f32_e32 v178, v178
	v_rcp_f32_e32 v179, v179
	v_mul_f32_e32 v30, v30, v176
	v_mul_f32_e32 v31, v31, v177
	v_mul_f32_e32 v32, v32, v178
	v_mul_f32_e32 v33, v33, v179
	v_mul_f32_e32 v30, s14, v30
	v_mul_f32_e32 v31, s14, v31
	v_mul_f32_e32 v32, s14, v32
	v_mul_f32_e32 v33, s14, v33
	v_cvt_pk_bf16_f32 v34, v34, v35
	v_cvt_pk_bf16_f32 v35, v36, v37
	v_cvt_pk_bf16_f32 v36, v30, v31
	v_cvt_pk_bf16_f32 v37, v32, v33
	s_nop 1
	v_permlane16_swap_b32_e32 v34, v36
	v_permlane16_swap_b32_e32 v35, v37
	global_store_dwordx4 v[132:133], v[34:37], off offset:64
	v_lshl_add_u64 v[132:133], v[132:133], 0, s[4:5]
	v_mul_f32_e32 v176, 0xbfb8aa3b, v38
	v_mul_f32_e32 v177, 0xbfb8aa3b, v39
	v_mul_f32_e32 v178, 0xbfb8aa3b, v40
	v_mul_f32_e32 v179, 0xbfb8aa3b, v41
	v_exp_f32_e32 v176, v176
	v_exp_f32_e32 v177, v177
	v_exp_f32_e32 v178, v178
	v_exp_f32_e32 v179, v179
	v_add_f32_e32 v176, 1.0, v176
	v_add_f32_e32 v177, 1.0, v177
	v_add_f32_e32 v178, 1.0, v178
	v_add_f32_e32 v179, 1.0, v179
	v_rcp_f32_e32 v176, v176
	v_rcp_f32_e32 v177, v177
	v_rcp_f32_e32 v178, v178
	v_rcp_f32_e32 v179, v179
	v_mul_f32_e32 v38, v38, v176
	v_mul_f32_e32 v39, v39, v177
	v_mul_f32_e32 v40, v40, v178
	v_mul_f32_e32 v41, v41, v179
	v_mul_f32_e32 v38, s14, v38
	v_mul_f32_e32 v39, s14, v39
	v_mul_f32_e32 v40, s14, v40
	v_mul_f32_e32 v41, s14, v41
	v_mul_f32_e32 v176, 0xbfb8aa3b, v26
	v_mul_f32_e32 v177, 0xbfb8aa3b, v27
	v_mul_f32_e32 v178, 0xbfb8aa3b, v28
	v_mul_f32_e32 v179, 0xbfb8aa3b, v29
	v_exp_f32_e32 v176, v176
	v_exp_f32_e32 v177, v177
	v_exp_f32_e32 v178, v178
	v_exp_f32_e32 v179, v179
	v_add_f32_e32 v176, 1.0, v176
	v_add_f32_e32 v177, 1.0, v177
	v_add_f32_e32 v178, 1.0, v178
	v_add_f32_e32 v179, 1.0, v179
	v_rcp_f32_e32 v176, v176
	v_rcp_f32_e32 v177, v177
	v_rcp_f32_e32 v178, v178
	v_rcp_f32_e32 v179, v179
	v_mul_f32_e32 v26, v26, v176
	v_mul_f32_e32 v27, v27, v177
	v_mul_f32_e32 v28, v28, v178
	v_mul_f32_e32 v29, v29, v179
	v_mul_f32_e32 v26, s14, v26
	v_mul_f32_e32 v27, s14, v27
	v_mul_f32_e32 v28, s14, v28
	v_mul_f32_e32 v29, s14, v29
	v_cvt_pk_bf16_f32 v38, v38, v39
	v_cvt_pk_bf16_f32 v39, v40, v41
	v_cvt_pk_bf16_f32 v40, v26, v27
	v_cvt_pk_bf16_f32 v41, v28, v29
	s_nop 1
	v_permlane16_swap_b32_e32 v38, v40
	v_permlane16_swap_b32_e32 v39, v41
	global_store_dwordx4 v[132:133], v[38:41], off
	v_mul_f32_e32 v176, 0xbfb8aa3b, v22
	v_mul_f32_e32 v177, 0xbfb8aa3b, v23
	v_mul_f32_e32 v178, 0xbfb8aa3b, v24
	v_mul_f32_e32 v179, 0xbfb8aa3b, v25
	v_exp_f32_e32 v176, v176
	v_exp_f32_e32 v177, v177
	v_exp_f32_e32 v178, v178
	v_exp_f32_e32 v179, v179
	v_add_f32_e32 v176, 1.0, v176
	v_add_f32_e32 v177, 1.0, v177
	v_add_f32_e32 v178, 1.0, v178
	v_add_f32_e32 v179, 1.0, v179
	v_rcp_f32_e32 v176, v176
	v_rcp_f32_e32 v177, v177
	v_rcp_f32_e32 v178, v178
	v_rcp_f32_e32 v179, v179
	v_mul_f32_e32 v22, v22, v176
	v_mul_f32_e32 v23, v23, v177
	v_mul_f32_e32 v24, v24, v178
	v_mul_f32_e32 v25, v25, v179
	v_mul_f32_e32 v22, s14, v22
	v_mul_f32_e32 v23, s14, v23
	v_mul_f32_e32 v24, s14, v24
	v_mul_f32_e32 v25, s14, v25
	v_mul_f32_e32 v176, 0xbfb8aa3b, v18
	v_mul_f32_e32 v177, 0xbfb8aa3b, v19
	v_mul_f32_e32 v178, 0xbfb8aa3b, v20
	v_mul_f32_e32 v179, 0xbfb8aa3b, v21
	v_exp_f32_e32 v176, v176
	v_exp_f32_e32 v177, v177
	v_exp_f32_e32 v178, v178
	v_exp_f32_e32 v179, v179
	v_add_f32_e32 v176, 1.0, v176
	v_add_f32_e32 v177, 1.0, v177
	v_add_f32_e32 v178, 1.0, v178
	v_add_f32_e32 v179, 1.0, v179
	v_rcp_f32_e32 v176, v176
	v_rcp_f32_e32 v177, v177
	v_rcp_f32_e32 v178, v178
	v_rcp_f32_e32 v179, v179
	v_mul_f32_e32 v18, v18, v176
	v_mul_f32_e32 v19, v19, v177
	v_mul_f32_e32 v20, v20, v178
	v_mul_f32_e32 v21, v21, v179
	v_mul_f32_e32 v18, s14, v18
	v_mul_f32_e32 v19, s14, v19
	v_mul_f32_e32 v20, s14, v20
	v_mul_f32_e32 v21, s14, v21
	v_cvt_pk_bf16_f32 v22, v22, v23
	v_cvt_pk_bf16_f32 v23, v24, v25
	v_cvt_pk_bf16_f32 v24, v18, v19
	v_cvt_pk_bf16_f32 v25, v20, v21
	s_nop 1
	v_permlane16_swap_b32_e32 v22, v24
	v_permlane16_swap_b32_e32 v23, v25
	global_store_dwordx4 v[132:133], v[22:25], off offset:64
	v_lshl_add_u64 v[132:133], v[132:133], 0, s[4:5]
	v_mul_f32_e32 v176, 0xbfb8aa3b, v14
	v_mul_f32_e32 v177, 0xbfb8aa3b, v15
	v_mul_f32_e32 v178, 0xbfb8aa3b, v16
	v_mul_f32_e32 v179, 0xbfb8aa3b, v17
	v_exp_f32_e32 v176, v176
	v_exp_f32_e32 v177, v177
	v_exp_f32_e32 v178, v178
	v_exp_f32_e32 v179, v179
	v_add_f32_e32 v176, 1.0, v176
	v_add_f32_e32 v177, 1.0, v177
	v_add_f32_e32 v178, 1.0, v178
	v_add_f32_e32 v179, 1.0, v179
	v_rcp_f32_e32 v176, v176
	v_rcp_f32_e32 v177, v177
	v_rcp_f32_e32 v178, v178
	v_rcp_f32_e32 v179, v179
	v_mul_f32_e32 v14, v14, v176
	v_mul_f32_e32 v15, v15, v177
	v_mul_f32_e32 v16, v16, v178
	v_mul_f32_e32 v17, v17, v179
	v_mul_f32_e32 v14, s14, v14
	v_mul_f32_e32 v15, s14, v15
	v_mul_f32_e32 v16, s14, v16
	v_mul_f32_e32 v17, s14, v17
	v_mul_f32_e32 v176, 0xbfb8aa3b, v10
	v_mul_f32_e32 v177, 0xbfb8aa3b, v11
	v_mul_f32_e32 v178, 0xbfb8aa3b, v12
	v_mul_f32_e32 v179, 0xbfb8aa3b, v13
	v_exp_f32_e32 v176, v176
	v_exp_f32_e32 v177, v177
	v_exp_f32_e32 v178, v178
	v_exp_f32_e32 v179, v179
	v_add_f32_e32 v176, 1.0, v176
	v_add_f32_e32 v177, 1.0, v177
	v_add_f32_e32 v178, 1.0, v178
	v_add_f32_e32 v179, 1.0, v179
	v_rcp_f32_e32 v176, v176
	v_rcp_f32_e32 v177, v177
	v_rcp_f32_e32 v178, v178
	v_rcp_f32_e32 v179, v179
	v_mul_f32_e32 v10, v10, v176
	v_mul_f32_e32 v11, v11, v177
	v_mul_f32_e32 v12, v12, v178
	v_mul_f32_e32 v13, v13, v179
	v_mul_f32_e32 v10, s14, v10
	v_mul_f32_e32 v11, s14, v11
	v_mul_f32_e32 v12, s14, v12
	v_mul_f32_e32 v13, s14, v13
	v_cvt_pk_bf16_f32 v14, v14, v15
	v_cvt_pk_bf16_f32 v15, v16, v17
	v_cvt_pk_bf16_f32 v16, v10, v11
	v_cvt_pk_bf16_f32 v17, v12, v13
	s_nop 1
	v_permlane16_swap_b32_e32 v14, v16
	v_permlane16_swap_b32_e32 v15, v17
	global_store_dwordx4 v[132:133], v[14:17], off
	v_mul_f32_e32 v176, 0xbfb8aa3b, v6
	v_mul_f32_e32 v177, 0xbfb8aa3b, v7
	v_mul_f32_e32 v178, 0xbfb8aa3b, v8
	v_mul_f32_e32 v179, 0xbfb8aa3b, v9
	v_exp_f32_e32 v176, v176
	v_exp_f32_e32 v177, v177
	v_exp_f32_e32 v178, v178
	v_exp_f32_e32 v179, v179
	v_add_f32_e32 v176, 1.0, v176
	v_add_f32_e32 v177, 1.0, v177
	v_add_f32_e32 v178, 1.0, v178
	v_add_f32_e32 v179, 1.0, v179
	v_rcp_f32_e32 v176, v176
	v_rcp_f32_e32 v177, v177
	v_rcp_f32_e32 v178, v178
	v_rcp_f32_e32 v179, v179
	v_mul_f32_e32 v6, v6, v176
	v_mul_f32_e32 v7, v7, v177
	v_mul_f32_e32 v8, v8, v178
	v_mul_f32_e32 v9, v9, v179
	v_mul_f32_e32 v6, s14, v6
	v_mul_f32_e32 v7, s14, v7
	v_mul_f32_e32 v8, s14, v8
	v_mul_f32_e32 v9, s14, v9
	v_mul_f32_e32 v176, 0xbfb8aa3b, v2
	v_mul_f32_e32 v177, 0xbfb8aa3b, v3
	v_mul_f32_e32 v178, 0xbfb8aa3b, v4
	v_mul_f32_e32 v179, 0xbfb8aa3b, v5
	v_exp_f32_e32 v176, v176
	v_exp_f32_e32 v177, v177
	v_exp_f32_e32 v178, v178
	v_exp_f32_e32 v179, v179
	v_add_f32_e32 v176, 1.0, v176
	v_add_f32_e32 v177, 1.0, v177
	v_add_f32_e32 v178, 1.0, v178
	v_add_f32_e32 v179, 1.0, v179
	v_rcp_f32_e32 v176, v176
	v_rcp_f32_e32 v177, v177
	v_rcp_f32_e32 v178, v178
	v_rcp_f32_e32 v179, v179
	v_mul_f32_e32 v2, v2, v176
	v_mul_f32_e32 v3, v3, v177
	v_mul_f32_e32 v4, v4, v178
	v_mul_f32_e32 v5, v5, v179
	v_mul_f32_e32 v2, s14, v2
	v_mul_f32_e32 v3, s14, v3
	v_mul_f32_e32 v4, s14, v4
	v_mul_f32_e32 v5, s14, v5
	v_cvt_pk_bf16_f32 v6, v6, v7
	v_cvt_pk_bf16_f32 v7, v8, v9
	v_cvt_pk_bf16_f32 v8, v2, v3
	v_cvt_pk_bf16_f32 v9, v4, v5
	s_nop 1
	v_permlane16_swap_b32_e32 v6, v8
	v_permlane16_swap_b32_e32 v7, v9
	global_store_dwordx4 v[132:133], v[6:9], off offset:64
	s_branch .LBB0_1040
.Lhg_part3:
	v_readlane_b32 s48, v252, 30
	v_readlane_b32 s49, v252, 31
	s_nop 1
	v_lshl_add_u64 v[132:133], s[48:49], 0, v[150:151]
	v_cvt_pk_bf16_f32 v126, v126, v127
	v_cvt_pk_bf16_f32 v127, v128, v129
	v_cvt_pk_bf16_f32 v128, v122, v123
	v_cvt_pk_bf16_f32 v129, v124, v125
	s_nop 1
	v_permlane16_swap_b32_e32 v126, v128
	v_permlane16_swap_b32_e32 v127, v129
	global_store_dwordx4 v[132:133], v[126:129], off
	v_cvt_pk_bf16_f32 v118, v118, v119
	v_cvt_pk_bf16_f32 v119, v120, v121
	v_cvt_pk_bf16_f32 v120, v114, v115
	v_cvt_pk_bf16_f32 v121, v116, v117
	s_nop 1
	v_permlane16_swap_b32_e32 v118, v120
	v_permlane16_swap_b32_e32 v119, v121
	global_store_dwordx4 v[132:133], v[118:121], off offset:64
	v_lshl_add_u64 v[132:133], v[132:133], 0, s[4:5]
	v_cvt_pk_bf16_f32 v110, v110, v111
	v_cvt_pk_bf16_f32 v111, v112, v113
	v_cvt_pk_bf16_f32 v112, v106, v107
	v_cvt_pk_bf16_f32 v113, v108, v109
	s_nop 1
	v_permlane16_swap_b32_e32 v110, v112
	v_permlane16_swap_b32_e32 v111, v113
	global_store_dwordx4 v[132:133], v[110:113], off
	v_cvt_pk_bf16_f32 v102, v102, v103
	v_cvt_pk_bf16_f32 v103, v104, v105
	v_cvt_pk_bf16_f32 v104, v98, v99
	v_cvt_pk_bf16_f32 v105, v100, v101
	s_nop 1
	v_permlane16_swap_b32_e32 v102, v104
	v_permlane16_swap_b32_e32 v103, v105
	global_store_dwordx4 v[132:133], v[102:105], off offset:64
	v_lshl_add_u64 v[132:133], v[132:133], 0, s[4:5]
	v_cvt_pk_bf16_f32 v94, v94, v95
	v_cvt_pk_bf16_f32 v95, v96, v97
	v_cvt_pk_bf16_f32 v96, v90, v91
	v_cvt_pk_bf16_f32 v97, v92, v93
	s_nop 1
	v_permlane16_swap_b32_e32 v94, v96
	v_permlane16_swap_b32_e32 v95, v97
	global_store_dwordx4 v[132:133], v[94:97], off
	v_cvt_pk_bf16_f32 v86, v86, v87
	v_cvt_pk_bf16_f32 v87, v88, v89
	v_cvt_pk_bf16_f32 v88, v82, v83
	v_cvt_pk_bf16_f32 v89, v84, v85
	s_nop 1
	v_permlane16_swap_b32_e32 v86, v88
	v_permlane16_swap_b32_e32 v87, v89
	global_store_dwordx4 v[132:133], v[86:89], off offset:64
	v_lshl_add_u64 v[132:133], v[132:133], 0, s[4:5]
	v_cvt_pk_bf16_f32 v78, v78, v79
	v_cvt_pk_bf16_f32 v79, v80, v81
	v_cvt_pk_bf16_f32 v80, v74, v75
	v_cvt_pk_bf16_f32 v81, v76, v77
	s_nop 1
	v_permlane16_swap_b32_e32 v78, v80
	v_permlane16_swap_b32_e32 v79, v81
	global_store_dwordx4 v[132:133], v[78:81], off
	v_cvt_pk_bf16_f32 v70, v70, v71
	v_cvt_pk_bf16_f32 v71, v72, v73
	v_cvt_pk_bf16_f32 v72, v66, v67
	v_cvt_pk_bf16_f32 v73, v68, v69
	s_nop 1
	v_permlane16_swap_b32_e32 v70, v72
	v_permlane16_swap_b32_e32 v71, v73
	global_store_dwordx4 v[132:133], v[70:73], off offset:64
	v_lshl_add_u64 v[132:133], v[132:133], 0, s[4:5]
	v_cvt_pk_bf16_f32 v62, v62, v63
	v_cvt_pk_bf16_f32 v63, v64, v65
	v_cvt_pk_bf16_f32 v64, v58, v59
	v_cvt_pk_bf16_f32 v65, v60, v61
	s_nop 1
	v_permlane16_swap_b32_e32 v62, v64
	v_permlane16_swap_b32_e32 v63, v65
	global_store_dwordx4 v[132:133], v[62:65], off
	v_cvt_pk_bf16_f32 v54, v54, v55
	v_cvt_pk_bf16_f32 v55, v56, v57
	v_cvt_pk_bf16_f32 v56, v50, v51
	v_cvt_pk_bf16_f32 v57, v52, v53
	s_nop 1
	v_permlane16_swap_b32_e32 v54, v56
	v_permlane16_swap_b32_e32 v55, v57
	global_store_dwordx4 v[132:133], v[54:57], off offset:64
	v_lshl_add_u64 v[132:133], v[132:133], 0, s[4:5]
	v_cvt_pk_bf16_f32 v46, v46, v47
	v_cvt_pk_bf16_f32 v47, v48, v49
	v_cvt_pk_bf16_f32 v48, v42, v43
	v_cvt_pk_bf16_f32 v49, v44, v45
	s_nop 1
	v_permlane16_swap_b32_e32 v46, v48
	v_permlane16_swap_b32_e32 v47, v49
	global_store_dwordx4 v[132:133], v[46:49], off
	v_cvt_pk_bf16_f32 v34, v34, v35
	v_cvt_pk_bf16_f32 v35, v36, v37
	v_cvt_pk_bf16_f32 v36, v30, v31
	v_cvt_pk_bf16_f32 v37, v32, v33
	s_nop 1
	v_permlane16_swap_b32_e32 v34, v36
	v_permlane16_swap_b32_e32 v35, v37
	global_store_dwordx4 v[132:133], v[34:37], off offset:64
	v_lshl_add_u64 v[132:133], v[132:133], 0, s[4:5]
	v_cvt_pk_bf16_f32 v38, v38, v39
	v_cvt_pk_bf16_f32 v39, v40, v41
	v_cvt_pk_bf16_f32 v40, v26, v27
	v_cvt_pk_bf16_f32 v41, v28, v29
	s_nop 1
	v_permlane16_swap_b32_e32 v38, v40
	v_permlane16_swap_b32_e32 v39, v41
	global_store_dwordx4 v[132:133], v[38:41], off
	v_cvt_pk_bf16_f32 v22, v22, v23
	v_cvt_pk_bf16_f32 v23, v24, v25
	v_cvt_pk_bf16_f32 v24, v18, v19
	v_cvt_pk_bf16_f32 v25, v20, v21
	s_nop 1
	v_permlane16_swap_b32_e32 v22, v24
	v_permlane16_swap_b32_e32 v23, v25
	global_store_dwordx4 v[132:133], v[22:25], off offset:64
	v_lshl_add_u64 v[132:133], v[132:133], 0, s[4:5]
	v_cvt_pk_bf16_f32 v14, v14, v15
	v_cvt_pk_bf16_f32 v15, v16, v17
	v_cvt_pk_bf16_f32 v16, v10, v11
	v_cvt_pk_bf16_f32 v17, v12, v13
	s_nop 1
	v_permlane16_swap_b32_e32 v14, v16
	v_permlane16_swap_b32_e32 v15, v17
	global_store_dwordx4 v[132:133], v[14:17], off
	v_cvt_pk_bf16_f32 v6, v6, v7
	v_cvt_pk_bf16_f32 v7, v8, v9
	v_cvt_pk_bf16_f32 v8, v2, v3
	v_cvt_pk_bf16_f32 v9, v4, v5
	s_nop 1
	v_permlane16_swap_b32_e32 v6, v8
	v_permlane16_swap_b32_e32 v7, v9
	global_store_dwordx4 v[132:133], v[6:9], off offset:64
	s_branch .LBB0_1040
.Lhg_part4:
	v_readlane_b32 s48, v253, 4
	v_readlane_b32 s49, v253, 5
	s_nop 1
	v_lshl_add_u64 v[132:133], s[48:49], 0, v[150:151]
	v_mul_f32_e32 v176, 0xbfb8aa3b, v126
	v_mul_f32_e32 v177, 0xbfb8aa3b, v127
	v_mul_f32_e32 v178, 0xbfb8aa3b, v128
	v_mul_f32_e32 v179, 0xbfb8aa3b, v129
	v_exp_f32_e32 v176, v176
	v_exp_f32_e32 v177, v177
	v_exp_f32_e32 v178, v178
	v_exp_f32_e32 v179, v179
	v_add_f32_e32 v176, 1.0, v176
	v_add_f32_e32 v177, 1.0, v177
	v_add_f32_e32 v178, 1.0, v178
	v_add_f32_e32 v179, 1.0, v179
	v_rcp_f32_e32 v176, v176
	v_rcp_f32_e32 v177, v177
	v_rcp_f32_e32 v178, v178
	v_rcp_f32_e32 v179, v179
	v_mul_f32_e32 v126, v126, v176
	v_mul_f32_e32 v127, v127, v177
	v_mul_f32_e32 v128, v128, v178
	v_mul_f32_e32 v129, v129, v179
	v_mul_f32_e32 v176, 0xbfb8aa3b, v122
	v_mul_f32_e32 v177, 0xbfb8aa3b, v123
	v_mul_f32_e32 v178, 0xbfb8aa3b, v124
	v_mul_f32_e32 v179, 0xbfb8aa3b, v125
	v_exp_f32_e32 v176, v176
	v_exp_f32_e32 v177, v177
	v_exp_f32_e32 v178, v178
	v_exp_f32_e32 v179, v179
	v_add_f32_e32 v176, 1.0, v176
	v_add_f32_e32 v177, 1.0, v177
	v_add_f32_e32 v178, 1.0, v178
	v_add_f32_e32 v179, 1.0, v179
	v_rcp_f32_e32 v176, v176
	v_rcp_f32_e32 v177, v177
	v_rcp_f32_e32 v178, v178
	v_rcp_f32_e32 v179, v179
	v_mul_f32_e32 v122, v122, v176
	v_mul_f32_e32 v123, v123, v177
	v_mul_f32_e32 v124, v124, v178
	v_mul_f32_e32 v125, v125, v179
	v_cvt_pk_bf16_f32 v126, v126, v127
	v_cvt_pk_bf16_f32 v127, v128, v129
	v_cvt_pk_bf16_f32 v128, v122, v123
	v_cvt_pk_bf16_f32 v129, v124, v125
	s_nop 1
	v_permlane16_swap_b32_e32 v126, v128
	v_permlane16_swap_b32_e32 v127, v129
	global_store_dwordx4 v[132:133], v[126:129], off
	v_mul_f32_e32 v176, 0xbfb8aa3b, v118
	v_mul_f32_e32 v177, 0xbfb8aa3b, v119
	v_mul_f32_e32 v178, 0xbfb8aa3b, v120
	v_mul_f32_e32 v179, 0xbfb8aa3b, v121
	v_exp_f32_e32 v176, v176
	v_exp_f32_e32 v177, v177
	v_exp_f32_e32 v178, v178
	v_exp_f32_e32 v179, v179
	v_add_f32_e32 v176, 1.0, v176
	v_add_f32_e32 v177, 1.0, v177
	v_add_f32_e32 v178, 1.0, v178
	v_add_f32_e32 v179, 1.0, v179
	v_rcp_f32_e32 v176, v176
	v_rcp_f32_e32 v177, v177
	v_rcp_f32_e32 v178, v178
	v_rcp_f32_e32 v179, v179
	v_mul_f32_e32 v118, v118, v176
	v_mul_f32_e32 v119, v119, v177
	v_mul_f32_e32 v120, v120, v178
	v_mul_f32_e32 v121, v121, v179
	v_mul_f32_e32 v176, 0xbfb8aa3b, v114
	v_mul_f32_e32 v177, 0xbfb8aa3b, v115
	v_mul_f32_e32 v178, 0xbfb8aa3b, v116
	v_mul_f32_e32 v179, 0xbfb8aa3b, v117
	v_exp_f32_e32 v176, v176
	v_exp_f32_e32 v177, v177
	v_exp_f32_e32 v178, v178
	v_exp_f32_e32 v179, v179
	v_add_f32_e32 v176, 1.0, v176
	v_add_f32_e32 v177, 1.0, v177
	v_add_f32_e32 v178, 1.0, v178
	v_add_f32_e32 v179, 1.0, v179
	v_rcp_f32_e32 v176, v176
	v_rcp_f32_e32 v177, v177
	v_rcp_f32_e32 v178, v178
	v_rcp_f32_e32 v179, v179
	v_mul_f32_e32 v114, v114, v176
	v_mul_f32_e32 v115, v115, v177
	v_mul_f32_e32 v116, v116, v178
	v_mul_f32_e32 v117, v117, v179
	v_cvt_pk_bf16_f32 v118, v118, v119
	v_cvt_pk_bf16_f32 v119, v120, v121
	v_cvt_pk_bf16_f32 v120, v114, v115
	v_cvt_pk_bf16_f32 v121, v116, v117
	s_nop 1
	v_permlane16_swap_b32_e32 v118, v120
	v_permlane16_swap_b32_e32 v119, v121
	global_store_dwordx4 v[132:133], v[118:121], off offset:64
	v_lshl_add_u64 v[132:133], v[132:133], 0, s[4:5]
	v_mul_f32_e32 v176, 0xbfb8aa3b, v110
	v_mul_f32_e32 v177, 0xbfb8aa3b, v111
	v_mul_f32_e32 v178, 0xbfb8aa3b, v112
	v_mul_f32_e32 v179, 0xbfb8aa3b, v113
	v_exp_f32_e32 v176, v176
	v_exp_f32_e32 v177, v177
	v_exp_f32_e32 v178, v178
	v_exp_f32_e32 v179, v179
	v_add_f32_e32 v176, 1.0, v176
	v_add_f32_e32 v177, 1.0, v177
	v_add_f32_e32 v178, 1.0, v178
	v_add_f32_e32 v179, 1.0, v179
	v_rcp_f32_e32 v176, v176
	v_rcp_f32_e32 v177, v177
	v_rcp_f32_e32 v178, v178
	v_rcp_f32_e32 v179, v179
	v_mul_f32_e32 v110, v110, v176
	v_mul_f32_e32 v111, v111, v177
	v_mul_f32_e32 v112, v112, v178
	v_mul_f32_e32 v113, v113, v179
	v_mul_f32_e32 v176, 0xbfb8aa3b, v106
	v_mul_f32_e32 v177, 0xbfb8aa3b, v107
	v_mul_f32_e32 v178, 0xbfb8aa3b, v108
	v_mul_f32_e32 v179, 0xbfb8aa3b, v109
	v_exp_f32_e32 v176, v176
	v_exp_f32_e32 v177, v177
	v_exp_f32_e32 v178, v178
	v_exp_f32_e32 v179, v179
	v_add_f32_e32 v176, 1.0, v176
	v_add_f32_e32 v177, 1.0, v177
	v_add_f32_e32 v178, 1.0, v178
	v_add_f32_e32 v179, 1.0, v179
	v_rcp_f32_e32 v176, v176
	v_rcp_f32_e32 v177, v177
	v_rcp_f32_e32 v178, v178
	v_rcp_f32_e32 v179, v179
	v_mul_f32_e32 v106, v106, v176
	v_mul_f32_e32 v107, v107, v177
	v_mul_f32_e32 v108, v108, v178
	v_mul_f32_e32 v109, v109, v179
	v_cvt_pk_bf16_f32 v110, v110, v111
	v_cvt_pk_bf16_f32 v111, v112, v113
	v_cvt_pk_bf16_f32 v112, v106, v107
	v_cvt_pk_bf16_f32 v113, v108, v109
	s_nop 1
	v_permlane16_swap_b32_e32 v110, v112
	v_permlane16_swap_b32_e32 v111, v113
	global_store_dwordx4 v[132:133], v[110:113], off
	v_mul_f32_e32 v176, 0xbfb8aa3b, v102
	v_mul_f32_e32 v177, 0xbfb8aa3b, v103
	v_mul_f32_e32 v178, 0xbfb8aa3b, v104
	v_mul_f32_e32 v179, 0xbfb8aa3b, v105
	v_exp_f32_e32 v176, v176
	v_exp_f32_e32 v177, v177
	v_exp_f32_e32 v178, v178
	v_exp_f32_e32 v179, v179
	v_add_f32_e32 v176, 1.0, v176
	v_add_f32_e32 v177, 1.0, v177
	v_add_f32_e32 v178, 1.0, v178
	v_add_f32_e32 v179, 1.0, v179
	v_rcp_f32_e32 v176, v176
	v_rcp_f32_e32 v177, v177
	v_rcp_f32_e32 v178, v178
	v_rcp_f32_e32 v179, v179
	v_mul_f32_e32 v102, v102, v176
	v_mul_f32_e32 v103, v103, v177
	v_mul_f32_e32 v104, v104, v178
	v_mul_f32_e32 v105, v105, v179
	v_mul_f32_e32 v176, 0xbfb8aa3b, v98
	v_mul_f32_e32 v177, 0xbfb8aa3b, v99
	v_mul_f32_e32 v178, 0xbfb8aa3b, v100
	v_mul_f32_e32 v179, 0xbfb8aa3b, v101
	v_exp_f32_e32 v176, v176
	v_exp_f32_e32 v177, v177
	v_exp_f32_e32 v178, v178
	v_exp_f32_e32 v179, v179
	v_add_f32_e32 v176, 1.0, v176
	v_add_f32_e32 v177, 1.0, v177
	v_add_f32_e32 v178, 1.0, v178
	v_add_f32_e32 v179, 1.0, v179
	v_rcp_f32_e32 v176, v176
	v_rcp_f32_e32 v177, v177
	v_rcp_f32_e32 v178, v178
	v_rcp_f32_e32 v179, v179
	v_mul_f32_e32 v98, v98, v176
	v_mul_f32_e32 v99, v99, v177
	v_mul_f32_e32 v100, v100, v178
	v_mul_f32_e32 v101, v101, v179
	v_cvt_pk_bf16_f32 v102, v102, v103
	v_cvt_pk_bf16_f32 v103, v104, v105
	v_cvt_pk_bf16_f32 v104, v98, v99
	v_cvt_pk_bf16_f32 v105, v100, v101
	s_nop 1
	v_permlane16_swap_b32_e32 v102, v104
	v_permlane16_swap_b32_e32 v103, v105
	global_store_dwordx4 v[132:133], v[102:105], off offset:64
	v_lshl_add_u64 v[132:133], v[132:133], 0, s[4:5]
	v_mul_f32_e32 v176, 0xbfb8aa3b, v94
	v_mul_f32_e32 v177, 0xbfb8aa3b, v95
	v_mul_f32_e32 v178, 0xbfb8aa3b, v96
	v_mul_f32_e32 v179, 0xbfb8aa3b, v97
	v_exp_f32_e32 v176, v176
	v_exp_f32_e32 v177, v177
	v_exp_f32_e32 v178, v178
	v_exp_f32_e32 v179, v179
	v_add_f32_e32 v176, 1.0, v176
	v_add_f32_e32 v177, 1.0, v177
	v_add_f32_e32 v178, 1.0, v178
	v_add_f32_e32 v179, 1.0, v179
	v_rcp_f32_e32 v176, v176
	v_rcp_f32_e32 v177, v177
	v_rcp_f32_e32 v178, v178
	v_rcp_f32_e32 v179, v179
	v_mul_f32_e32 v94, v94, v176
	v_mul_f32_e32 v95, v95, v177
	v_mul_f32_e32 v96, v96, v178
	v_mul_f32_e32 v97, v97, v179
	v_mul_f32_e32 v176, 0xbfb8aa3b, v90
	v_mul_f32_e32 v177, 0xbfb8aa3b, v91
	v_mul_f32_e32 v178, 0xbfb8aa3b, v92
	v_mul_f32_e32 v179, 0xbfb8aa3b, v93
	v_exp_f32_e32 v176, v176
	v_exp_f32_e32 v177, v177
	v_exp_f32_e32 v178, v178
	v_exp_f32_e32 v179, v179
	v_add_f32_e32 v176, 1.0, v176
	v_add_f32_e32 v177, 1.0, v177
	v_add_f32_e32 v178, 1.0, v178
	v_add_f32_e32 v179, 1.0, v179
	v_rcp_f32_e32 v176, v176
	v_rcp_f32_e32 v177, v177
	v_rcp_f32_e32 v178, v178
	v_rcp_f32_e32 v179, v179
	v_mul_f32_e32 v90, v90, v176
	v_mul_f32_e32 v91, v91, v177
	v_mul_f32_e32 v92, v92, v178
	v_mul_f32_e32 v93, v93, v179
	v_cvt_pk_bf16_f32 v94, v94, v95
	v_cvt_pk_bf16_f32 v95, v96, v97
	v_cvt_pk_bf16_f32 v96, v90, v91
	v_cvt_pk_bf16_f32 v97, v92, v93
	s_nop 1
	v_permlane16_swap_b32_e32 v94, v96
	v_permlane16_swap_b32_e32 v95, v97
	global_store_dwordx4 v[132:133], v[94:97], off
	v_mul_f32_e32 v176, 0xbfb8aa3b, v86
	v_mul_f32_e32 v177, 0xbfb8aa3b, v87
	v_mul_f32_e32 v178, 0xbfb8aa3b, v88
	v_mul_f32_e32 v179, 0xbfb8aa3b, v89
	v_exp_f32_e32 v176, v176
	v_exp_f32_e32 v177, v177
	v_exp_f32_e32 v178, v178
	v_exp_f32_e32 v179, v179
	v_add_f32_e32 v176, 1.0, v176
	v_add_f32_e32 v177, 1.0, v177
	v_add_f32_e32 v178, 1.0, v178
	v_add_f32_e32 v179, 1.0, v179
	v_rcp_f32_e32 v176, v176
	v_rcp_f32_e32 v177, v177
	v_rcp_f32_e32 v178, v178
	v_rcp_f32_e32 v179, v179
	v_mul_f32_e32 v86, v86, v176
	v_mul_f32_e32 v87, v87, v177
	v_mul_f32_e32 v88, v88, v178
	v_mul_f32_e32 v89, v89, v179
	v_mul_f32_e32 v176, 0xbfb8aa3b, v82
	v_mul_f32_e32 v177, 0xbfb8aa3b, v83
	v_mul_f32_e32 v178, 0xbfb8aa3b, v84
	v_mul_f32_e32 v179, 0xbfb8aa3b, v85
	v_exp_f32_e32 v176, v176
	v_exp_f32_e32 v177, v177
	v_exp_f32_e32 v178, v178
	v_exp_f32_e32 v179, v179
	v_add_f32_e32 v176, 1.0, v176
	v_add_f32_e32 v177, 1.0, v177
	v_add_f32_e32 v178, 1.0, v178
	v_add_f32_e32 v179, 1.0, v179
	v_rcp_f32_e32 v176, v176
	v_rcp_f32_e32 v177, v177
	v_rcp_f32_e32 v178, v178
	v_rcp_f32_e32 v179, v179
	v_mul_f32_e32 v82, v82, v176
	v_mul_f32_e32 v83, v83, v177
	v_mul_f32_e32 v84, v84, v178
	v_mul_f32_e32 v85, v85, v179
	v_cvt_pk_bf16_f32 v86, v86, v87
	v_cvt_pk_bf16_f32 v87, v88, v89
	v_cvt_pk_bf16_f32 v88, v82, v83
	v_cvt_pk_bf16_f32 v89, v84, v85
	s_nop 1
	v_permlane16_swap_b32_e32 v86, v88
	v_permlane16_swap_b32_e32 v87, v89
	global_store_dwordx4 v[132:133], v[86:89], off offset:64
	v_lshl_add_u64 v[132:133], v[132:133], 0, s[4:5]
	v_mul_f32_e32 v176, 0xbfb8aa3b, v78
	v_mul_f32_e32 v177, 0xbfb8aa3b, v79
	v_mul_f32_e32 v178, 0xbfb8aa3b, v80
	v_mul_f32_e32 v179, 0xbfb8aa3b, v81
	v_exp_f32_e32 v176, v176
	v_exp_f32_e32 v177, v177
	v_exp_f32_e32 v178, v178
	v_exp_f32_e32 v179, v179
	v_add_f32_e32 v176, 1.0, v176
	v_add_f32_e32 v177, 1.0, v177
	v_add_f32_e32 v178, 1.0, v178
	v_add_f32_e32 v179, 1.0, v179
	v_rcp_f32_e32 v176, v176
	v_rcp_f32_e32 v177, v177
	v_rcp_f32_e32 v178, v178
	v_rcp_f32_e32 v179, v179
	v_mul_f32_e32 v78, v78, v176
	v_mul_f32_e32 v79, v79, v177
	v_mul_f32_e32 v80, v80, v178
	v_mul_f32_e32 v81, v81, v179
	v_mul_f32_e32 v176, 0xbfb8aa3b, v74
	v_mul_f32_e32 v177, 0xbfb8aa3b, v75
	v_mul_f32_e32 v178, 0xbfb8aa3b, v76
	v_mul_f32_e32 v179, 0xbfb8aa3b, v77
	v_exp_f32_e32 v176, v176
	v_exp_f32_e32 v177, v177
	v_exp_f32_e32 v178, v178
	v_exp_f32_e32 v179, v179
	v_add_f32_e32 v176, 1.0, v176
	v_add_f32_e32 v177, 1.0, v177
	v_add_f32_e32 v178, 1.0, v178
	v_add_f32_e32 v179, 1.0, v179
	v_rcp_f32_e32 v176, v176
	v_rcp_f32_e32 v177, v177
	v_rcp_f32_e32 v178, v178
	v_rcp_f32_e32 v179, v179
	v_mul_f32_e32 v74, v74, v176
	v_mul_f32_e32 v75, v75, v177
	v_mul_f32_e32 v76, v76, v178
	v_mul_f32_e32 v77, v77, v179
	v_cvt_pk_bf16_f32 v78, v78, v79
	v_cvt_pk_bf16_f32 v79, v80, v81
	v_cvt_pk_bf16_f32 v80, v74, v75
	v_cvt_pk_bf16_f32 v81, v76, v77
	s_nop 1
	v_permlane16_swap_b32_e32 v78, v80
	v_permlane16_swap_b32_e32 v79, v81
	global_store_dwordx4 v[132:133], v[78:81], off
	v_mul_f32_e32 v176, 0xbfb8aa3b, v70
	v_mul_f32_e32 v177, 0xbfb8aa3b, v71
	v_mul_f32_e32 v178, 0xbfb8aa3b, v72
	v_mul_f32_e32 v179, 0xbfb8aa3b, v73
	v_exp_f32_e32 v176, v176
	v_exp_f32_e32 v177, v177
	v_exp_f32_e32 v178, v178
	v_exp_f32_e32 v179, v179
	v_add_f32_e32 v176, 1.0, v176
	v_add_f32_e32 v177, 1.0, v177
	v_add_f32_e32 v178, 1.0, v178
	v_add_f32_e32 v179, 1.0, v179
	v_rcp_f32_e32 v176, v176
	v_rcp_f32_e32 v177, v177
	v_rcp_f32_e32 v178, v178
	v_rcp_f32_e32 v179, v179
	v_mul_f32_e32 v70, v70, v176
	v_mul_f32_e32 v71, v71, v177
	v_mul_f32_e32 v72, v72, v178
	v_mul_f32_e32 v73, v73, v179
	v_mul_f32_e32 v176, 0xbfb8aa3b, v66
	v_mul_f32_e32 v177, 0xbfb8aa3b, v67
	v_mul_f32_e32 v178, 0xbfb8aa3b, v68
	v_mul_f32_e32 v179, 0xbfb8aa3b, v69
	v_exp_f32_e32 v176, v176
	v_exp_f32_e32 v177, v177
	v_exp_f32_e32 v178, v178
	v_exp_f32_e32 v179, v179
	v_add_f32_e32 v176, 1.0, v176
	v_add_f32_e32 v177, 1.0, v177
	v_add_f32_e32 v178, 1.0, v178
	v_add_f32_e32 v179, 1.0, v179
	v_rcp_f32_e32 v176, v176
	v_rcp_f32_e32 v177, v177
	v_rcp_f32_e32 v178, v178
	v_rcp_f32_e32 v179, v179
	v_mul_f32_e32 v66, v66, v176
	v_mul_f32_e32 v67, v67, v177
	v_mul_f32_e32 v68, v68, v178
	v_mul_f32_e32 v69, v69, v179
	v_cvt_pk_bf16_f32 v70, v70, v71
	v_cvt_pk_bf16_f32 v71, v72, v73
	v_cvt_pk_bf16_f32 v72, v66, v67
	v_cvt_pk_bf16_f32 v73, v68, v69
	s_nop 1
	v_permlane16_swap_b32_e32 v70, v72
	v_permlane16_swap_b32_e32 v71, v73
	global_store_dwordx4 v[132:133], v[70:73], off offset:64
	v_lshl_add_u64 v[132:133], v[132:133], 0, s[4:5]
	v_mul_f32_e32 v176, 0xbfb8aa3b, v62
	v_mul_f32_e32 v177, 0xbfb8aa3b, v63
	v_mul_f32_e32 v178, 0xbfb8aa3b, v64
	v_mul_f32_e32 v179, 0xbfb8aa3b, v65
	v_exp_f32_e32 v176, v176
	v_exp_f32_e32 v177, v177
	v_exp_f32_e32 v178, v178
	v_exp_f32_e32 v179, v179
	v_add_f32_e32 v176, 1.0, v176
	v_add_f32_e32 v177, 1.0, v177
	v_add_f32_e32 v178, 1.0, v178
	v_add_f32_e32 v179, 1.0, v179
	v_rcp_f32_e32 v176, v176
	v_rcp_f32_e32 v177, v177
	v_rcp_f32_e32 v178, v178
	v_rcp_f32_e32 v179, v179
	v_mul_f32_e32 v62, v62, v176
	v_mul_f32_e32 v63, v63, v177
	v_mul_f32_e32 v64, v64, v178
	v_mul_f32_e32 v65, v65, v179
	v_mul_f32_e32 v176, 0xbfb8aa3b, v58
	v_mul_f32_e32 v177, 0xbfb8aa3b, v59
	v_mul_f32_e32 v178, 0xbfb8aa3b, v60
	v_mul_f32_e32 v179, 0xbfb8aa3b, v61
	v_exp_f32_e32 v176, v176
	v_exp_f32_e32 v177, v177
	v_exp_f32_e32 v178, v178
	v_exp_f32_e32 v179, v179
	v_add_f32_e32 v176, 1.0, v176
	v_add_f32_e32 v177, 1.0, v177
	v_add_f32_e32 v178, 1.0, v178
	v_add_f32_e32 v179, 1.0, v179
	v_rcp_f32_e32 v176, v176
	v_rcp_f32_e32 v177, v177
	v_rcp_f32_e32 v178, v178
	v_rcp_f32_e32 v179, v179
	v_mul_f32_e32 v58, v58, v176
	v_mul_f32_e32 v59, v59, v177
	v_mul_f32_e32 v60, v60, v178
	v_mul_f32_e32 v61, v61, v179
	v_cvt_pk_bf16_f32 v62, v62, v63
	v_cvt_pk_bf16_f32 v63, v64, v65
	v_cvt_pk_bf16_f32 v64, v58, v59
	v_cvt_pk_bf16_f32 v65, v60, v61
	s_nop 1
	v_permlane16_swap_b32_e32 v62, v64
	v_permlane16_swap_b32_e32 v63, v65
	global_store_dwordx4 v[132:133], v[62:65], off
	v_mul_f32_e32 v176, 0xbfb8aa3b, v54
	v_mul_f32_e32 v177, 0xbfb8aa3b, v55
	v_mul_f32_e32 v178, 0xbfb8aa3b, v56
	v_mul_f32_e32 v179, 0xbfb8aa3b, v57
	v_exp_f32_e32 v176, v176
	v_exp_f32_e32 v177, v177
	v_exp_f32_e32 v178, v178
	v_exp_f32_e32 v179, v179
	v_add_f32_e32 v176, 1.0, v176
	v_add_f32_e32 v177, 1.0, v177
	v_add_f32_e32 v178, 1.0, v178
	v_add_f32_e32 v179, 1.0, v179
	v_rcp_f32_e32 v176, v176
	v_rcp_f32_e32 v177, v177
	v_rcp_f32_e32 v178, v178
	v_rcp_f32_e32 v179, v179
	v_mul_f32_e32 v54, v54, v176
	v_mul_f32_e32 v55, v55, v177
	v_mul_f32_e32 v56, v56, v178
	v_mul_f32_e32 v57, v57, v179
	v_mul_f32_e32 v176, 0xbfb8aa3b, v50
	v_mul_f32_e32 v177, 0xbfb8aa3b, v51
	v_mul_f32_e32 v178, 0xbfb8aa3b, v52
	v_mul_f32_e32 v179, 0xbfb8aa3b, v53
	v_exp_f32_e32 v176, v176
	v_exp_f32_e32 v177, v177
	v_exp_f32_e32 v178, v178
	v_exp_f32_e32 v179, v179
	v_add_f32_e32 v176, 1.0, v176
	v_add_f32_e32 v177, 1.0, v177
	v_add_f32_e32 v178, 1.0, v178
	v_add_f32_e32 v179, 1.0, v179
	v_rcp_f32_e32 v176, v176
	v_rcp_f32_e32 v177, v177
	v_rcp_f32_e32 v178, v178
	v_rcp_f32_e32 v179, v179
	v_mul_f32_e32 v50, v50, v176
	v_mul_f32_e32 v51, v51, v177
	v_mul_f32_e32 v52, v52, v178
	v_mul_f32_e32 v53, v53, v179
	v_cvt_pk_bf16_f32 v54, v54, v55
	v_cvt_pk_bf16_f32 v55, v56, v57
	v_cvt_pk_bf16_f32 v56, v50, v51
	v_cvt_pk_bf16_f32 v57, v52, v53
	s_nop 1
	v_permlane16_swap_b32_e32 v54, v56
	v_permlane16_swap_b32_e32 v55, v57
	global_store_dwordx4 v[132:133], v[54:57], off offset:64
	v_lshl_add_u64 v[132:133], v[132:133], 0, s[4:5]
	v_mul_f32_e32 v176, 0xbfb8aa3b, v46
	v_mul_f32_e32 v177, 0xbfb8aa3b, v47
	v_mul_f32_e32 v178, 0xbfb8aa3b, v48
	v_mul_f32_e32 v179, 0xbfb8aa3b, v49
	v_exp_f32_e32 v176, v176
	v_exp_f32_e32 v177, v177
	v_exp_f32_e32 v178, v178
	v_exp_f32_e32 v179, v179
	v_add_f32_e32 v176, 1.0, v176
	v_add_f32_e32 v177, 1.0, v177
	v_add_f32_e32 v178, 1.0, v178
	v_add_f32_e32 v179, 1.0, v179
	v_rcp_f32_e32 v176, v176
	v_rcp_f32_e32 v177, v177
	v_rcp_f32_e32 v178, v178
	v_rcp_f32_e32 v179, v179
	v_mul_f32_e32 v46, v46, v176
	v_mul_f32_e32 v47, v47, v177
	v_mul_f32_e32 v48, v48, v178
	v_mul_f32_e32 v49, v49, v179
	v_mul_f32_e32 v176, 0xbfb8aa3b, v42
	v_mul_f32_e32 v177, 0xbfb8aa3b, v43
	v_mul_f32_e32 v178, 0xbfb8aa3b, v44
	v_mul_f32_e32 v179, 0xbfb8aa3b, v45
	v_exp_f32_e32 v176, v176
	v_exp_f32_e32 v177, v177
	v_exp_f32_e32 v178, v178
	v_exp_f32_e32 v179, v179
	v_add_f32_e32 v176, 1.0, v176
	v_add_f32_e32 v177, 1.0, v177
	v_add_f32_e32 v178, 1.0, v178
	v_add_f32_e32 v179, 1.0, v179
	v_rcp_f32_e32 v176, v176
	v_rcp_f32_e32 v177, v177
	v_rcp_f32_e32 v178, v178
	v_rcp_f32_e32 v179, v179
	v_mul_f32_e32 v42, v42, v176
	v_mul_f32_e32 v43, v43, v177
	v_mul_f32_e32 v44, v44, v178
	v_mul_f32_e32 v45, v45, v179
	v_cvt_pk_bf16_f32 v46, v46, v47
	v_cvt_pk_bf16_f32 v47, v48, v49
	v_cvt_pk_bf16_f32 v48, v42, v43
	v_cvt_pk_bf16_f32 v49, v44, v45
	s_nop 1
	v_permlane16_swap_b32_e32 v46, v48
	v_permlane16_swap_b32_e32 v47, v49
	global_store_dwordx4 v[132:133], v[46:49], off
	v_mul_f32_e32 v176, 0xbfb8aa3b, v34
	v_mul_f32_e32 v177, 0xbfb8aa3b, v35
	v_mul_f32_e32 v178, 0xbfb8aa3b, v36
	v_mul_f32_e32 v179, 0xbfb8aa3b, v37
	v_exp_f32_e32 v176, v176
	v_exp_f32_e32 v177, v177
	v_exp_f32_e32 v178, v178
	v_exp_f32_e32 v179, v179
	v_add_f32_e32 v176, 1.0, v176
	v_add_f32_e32 v177, 1.0, v177
	v_add_f32_e32 v178, 1.0, v178
	v_add_f32_e32 v179, 1.0, v179
	v_rcp_f32_e32 v176, v176
	v_rcp_f32_e32 v177, v177
	v_rcp_f32_e32 v178, v178
	v_rcp_f32_e32 v179, v179
	v_mul_f32_e32 v34, v34, v176
	v_mul_f32_e32 v35, v35, v177
	v_mul_f32_e32 v36, v36, v178
	v_mul_f32_e32 v37, v37, v179
	v_mul_f32_e32 v176, 0xbfb8aa3b, v30
	v_mul_f32_e32 v177, 0xbfb8aa3b, v31
	v_mul_f32_e32 v178, 0xbfb8aa3b, v32
	v_mul_f32_e32 v179, 0xbfb8aa3b, v33
	v_exp_f32_e32 v176, v176
	v_exp_f32_e32 v177, v177
	v_exp_f32_e32 v178, v178
	v_exp_f32_e32 v179, v179
	v_add_f32_e32 v176, 1.0, v176
	v_add_f32_e32 v177, 1.0, v177
	v_add_f32_e32 v178, 1.0, v178
	v_add_f32_e32 v179, 1.0, v179
	v_rcp_f32_e32 v176, v176
	v_rcp_f32_e32 v177, v177
	v_rcp_f32_e32 v178, v178
	v_rcp_f32_e32 v179, v179
	v_mul_f32_e32 v30, v30, v176
	v_mul_f32_e32 v31, v31, v177
	v_mul_f32_e32 v32, v32, v178
	v_mul_f32_e32 v33, v33, v179
	v_cvt_pk_bf16_f32 v34, v34, v35
	v_cvt_pk_bf16_f32 v35, v36, v37
	v_cvt_pk_bf16_f32 v36, v30, v31
	v_cvt_pk_bf16_f32 v37, v32, v33
	s_nop 1
	v_permlane16_swap_b32_e32 v34, v36
	v_permlane16_swap_b32_e32 v35, v37
	global_store_dwordx4 v[132:133], v[34:37], off offset:64
	v_lshl_add_u64 v[132:133], v[132:133], 0, s[4:5]
	v_mul_f32_e32 v176, 0xbfb8aa3b, v38
	v_mul_f32_e32 v177, 0xbfb8aa3b, v39
	v_mul_f32_e32 v178, 0xbfb8aa3b, v40
	v_mul_f32_e32 v179, 0xbfb8aa3b, v41
	v_exp_f32_e32 v176, v176
	v_exp_f32_e32 v177, v177
	v_exp_f32_e32 v178, v178
	v_exp_f32_e32 v179, v179
	v_add_f32_e32 v176, 1.0, v176
	v_add_f32_e32 v177, 1.0, v177
	v_add_f32_e32 v178, 1.0, v178
	v_add_f32_e32 v179, 1.0, v179
	v_rcp_f32_e32 v176, v176
	v_rcp_f32_e32 v177, v177
	v_rcp_f32_e32 v178, v178
	v_rcp_f32_e32 v179, v179
	v_mul_f32_e32 v38, v38, v176
	v_mul_f32_e32 v39, v39, v177
	v_mul_f32_e32 v40, v40, v178
	v_mul_f32_e32 v41, v41, v179
	v_mul_f32_e32 v176, 0xbfb8aa3b, v26
	v_mul_f32_e32 v177, 0xbfb8aa3b, v27
	v_mul_f32_e32 v178, 0xbfb8aa3b, v28
	v_mul_f32_e32 v179, 0xbfb8aa3b, v29
	v_exp_f32_e32 v176, v176
	v_exp_f32_e32 v177, v177
	v_exp_f32_e32 v178, v178
	v_exp_f32_e32 v179, v179
	v_add_f32_e32 v176, 1.0, v176
	v_add_f32_e32 v177, 1.0, v177
	v_add_f32_e32 v178, 1.0, v178
	v_add_f32_e32 v179, 1.0, v179
	v_rcp_f32_e32 v176, v176
	v_rcp_f32_e32 v177, v177
	v_rcp_f32_e32 v178, v178
	v_rcp_f32_e32 v179, v179
	v_mul_f32_e32 v26, v26, v176
	v_mul_f32_e32 v27, v27, v177
	v_mul_f32_e32 v28, v28, v178
	v_mul_f32_e32 v29, v29, v179
	v_cvt_pk_bf16_f32 v38, v38, v39
	v_cvt_pk_bf16_f32 v39, v40, v41
	v_cvt_pk_bf16_f32 v40, v26, v27
	v_cvt_pk_bf16_f32 v41, v28, v29
	s_nop 1
	v_permlane16_swap_b32_e32 v38, v40
	v_permlane16_swap_b32_e32 v39, v41
	global_store_dwordx4 v[132:133], v[38:41], off
	v_mul_f32_e32 v176, 0xbfb8aa3b, v22
	v_mul_f32_e32 v177, 0xbfb8aa3b, v23
	v_mul_f32_e32 v178, 0xbfb8aa3b, v24
	v_mul_f32_e32 v179, 0xbfb8aa3b, v25
	v_exp_f32_e32 v176, v176
	v_exp_f32_e32 v177, v177
	v_exp_f32_e32 v178, v178
	v_exp_f32_e32 v179, v179
	v_add_f32_e32 v176, 1.0, v176
	v_add_f32_e32 v177, 1.0, v177
	v_add_f32_e32 v178, 1.0, v178
	v_add_f32_e32 v179, 1.0, v179
	v_rcp_f32_e32 v176, v176
	v_rcp_f32_e32 v177, v177
	v_rcp_f32_e32 v178, v178
	v_rcp_f32_e32 v179, v179
	v_mul_f32_e32 v22, v22, v176
	v_mul_f32_e32 v23, v23, v177
	v_mul_f32_e32 v24, v24, v178
	v_mul_f32_e32 v25, v25, v179
	v_mul_f32_e32 v176, 0xbfb8aa3b, v18
	v_mul_f32_e32 v177, 0xbfb8aa3b, v19
	v_mul_f32_e32 v178, 0xbfb8aa3b, v20
	v_mul_f32_e32 v179, 0xbfb8aa3b, v21
	v_exp_f32_e32 v176, v176
	v_exp_f32_e32 v177, v177
	v_exp_f32_e32 v178, v178
	v_exp_f32_e32 v179, v179
	v_add_f32_e32 v176, 1.0, v176
	v_add_f32_e32 v177, 1.0, v177
	v_add_f32_e32 v178, 1.0, v178
	v_add_f32_e32 v179, 1.0, v179
	v_rcp_f32_e32 v176, v176
	v_rcp_f32_e32 v177, v177
	v_rcp_f32_e32 v178, v178
	v_rcp_f32_e32 v179, v179
	v_mul_f32_e32 v18, v18, v176
	v_mul_f32_e32 v19, v19, v177
	v_mul_f32_e32 v20, v20, v178
	v_mul_f32_e32 v21, v21, v179
	v_cvt_pk_bf16_f32 v22, v22, v23
	v_cvt_pk_bf16_f32 v23, v24, v25
	v_cvt_pk_bf16_f32 v24, v18, v19
	v_cvt_pk_bf16_f32 v25, v20, v21
	s_nop 1
	v_permlane16_swap_b32_e32 v22, v24
	v_permlane16_swap_b32_e32 v23, v25
	global_store_dwordx4 v[132:133], v[22:25], off offset:64
	v_lshl_add_u64 v[132:133], v[132:133], 0, s[4:5]
	v_mul_f32_e32 v176, 0xbfb8aa3b, v14
	v_mul_f32_e32 v177, 0xbfb8aa3b, v15
	v_mul_f32_e32 v178, 0xbfb8aa3b, v16
	v_mul_f32_e32 v179, 0xbfb8aa3b, v17
	v_exp_f32_e32 v176, v176
	v_exp_f32_e32 v177, v177
	v_exp_f32_e32 v178, v178
	v_exp_f32_e32 v179, v179
	v_add_f32_e32 v176, 1.0, v176
	v_add_f32_e32 v177, 1.0, v177
	v_add_f32_e32 v178, 1.0, v178
	v_add_f32_e32 v179, 1.0, v179
	v_rcp_f32_e32 v176, v176
	v_rcp_f32_e32 v177, v177
	v_rcp_f32_e32 v178, v178
	v_rcp_f32_e32 v179, v179
	v_mul_f32_e32 v14, v14, v176
	v_mul_f32_e32 v15, v15, v177
	v_mul_f32_e32 v16, v16, v178
	v_mul_f32_e32 v17, v17, v179
	v_mul_f32_e32 v176, 0xbfb8aa3b, v10
	v_mul_f32_e32 v177, 0xbfb8aa3b, v11
	v_mul_f32_e32 v178, 0xbfb8aa3b, v12
	v_mul_f32_e32 v179, 0xbfb8aa3b, v13
	v_exp_f32_e32 v176, v176
	v_exp_f32_e32 v177, v177
	v_exp_f32_e32 v178, v178
	v_exp_f32_e32 v179, v179
	v_add_f32_e32 v176, 1.0, v176
	v_add_f32_e32 v177, 1.0, v177
	v_add_f32_e32 v178, 1.0, v178
	v_add_f32_e32 v179, 1.0, v179
	v_rcp_f32_e32 v176, v176
	v_rcp_f32_e32 v177, v177
	v_rcp_f32_e32 v178, v178
	v_rcp_f32_e32 v179, v179
	v_mul_f32_e32 v10, v10, v176
	v_mul_f32_e32 v11, v11, v177
	v_mul_f32_e32 v12, v12, v178
	v_mul_f32_e32 v13, v13, v179
	v_cvt_pk_bf16_f32 v14, v14, v15
	v_cvt_pk_bf16_f32 v15, v16, v17
	v_cvt_pk_bf16_f32 v16, v10, v11
	v_cvt_pk_bf16_f32 v17, v12, v13
	s_nop 1
	v_permlane16_swap_b32_e32 v14, v16
	v_permlane16_swap_b32_e32 v15, v17
	global_store_dwordx4 v[132:133], v[14:17], off
	v_mul_f32_e32 v176, 0xbfb8aa3b, v6
	v_mul_f32_e32 v177, 0xbfb8aa3b, v7
	v_mul_f32_e32 v178, 0xbfb8aa3b, v8
	v_mul_f32_e32 v179, 0xbfb8aa3b, v9
	v_exp_f32_e32 v176, v176
	v_exp_f32_e32 v177, v177
	v_exp_f32_e32 v178, v178
	v_exp_f32_e32 v179, v179
	v_add_f32_e32 v176, 1.0, v176
	v_add_f32_e32 v177, 1.0, v177
	v_add_f32_e32 v178, 1.0, v178
	v_add_f32_e32 v179, 1.0, v179
	v_rcp_f32_e32 v176, v176
	v_rcp_f32_e32 v177, v177
	v_rcp_f32_e32 v178, v178
	v_rcp_f32_e32 v179, v179
	v_mul_f32_e32 v6, v6, v176
	v_mul_f32_e32 v7, v7, v177
	v_mul_f32_e32 v8, v8, v178
	v_mul_f32_e32 v9, v9, v179
	v_mul_f32_e32 v176, 0xbfb8aa3b, v2
	v_mul_f32_e32 v177, 0xbfb8aa3b, v3
	v_mul_f32_e32 v178, 0xbfb8aa3b, v4
	v_mul_f32_e32 v179, 0xbfb8aa3b, v5
	v_exp_f32_e32 v176, v176
	v_exp_f32_e32 v177, v177
	v_exp_f32_e32 v178, v178
	v_exp_f32_e32 v179, v179
	v_add_f32_e32 v176, 1.0, v176
	v_add_f32_e32 v177, 1.0, v177
	v_add_f32_e32 v178, 1.0, v178
	v_add_f32_e32 v179, 1.0, v179
	v_rcp_f32_e32 v176, v176
	v_rcp_f32_e32 v177, v177
	v_rcp_f32_e32 v178, v178
	v_rcp_f32_e32 v179, v179
	v_mul_f32_e32 v2, v2, v176
	v_mul_f32_e32 v3, v3, v177
	v_mul_f32_e32 v4, v4, v178
	v_mul_f32_e32 v5, v5, v179
	v_cvt_pk_bf16_f32 v6, v6, v7
	v_cvt_pk_bf16_f32 v7, v8, v9
	v_cvt_pk_bf16_f32 v8, v2, v3
	v_cvt_pk_bf16_f32 v9, v4, v5
	s_nop 1
	v_permlane16_swap_b32_e32 v6, v8
	v_permlane16_swap_b32_e32 v7, v9
	global_store_dwordx4 v[132:133], v[6:9], off offset:64
